# GEMM phases: removed per-phase s_setprio flips (on top of scan wait removal)
# speedup vs baseline: 1.0163x; 1.0048x over previous
; #define STG(P, GB) do { const char* _gb = (GB); \
;     _Pragma("unroll") for (int _i = 0; _i < 2; ++_i) { \
;       __builtin_amdgcn_global_load_lds((const unsigned*)(_gb + voff[_i]), \
;         (LAS unsigned*)((LAS char*)(P) + ldsw + _i * 8192), 16, 0, 0); } } while (0)
; #define LDA(dst, b, h) _Pragma("unroll") for (int m = 0; m < 4; ++m) _Pragma("unroll") for (int k = 0; k < 2; ++k) \
;     dst[m][k] = *(const LAS bf16x8*)((LAS char*)SA(b, h) + aoff + m * 2048 + k * 1024)
; #define LDB(dst, b, h) _Pragma("unroll") for (int n = 0; n < 2; ++n) _Pragma("unroll") for (int k = 0; k < 2; ++k) \
;     dst[n][k] = *(const LAS bf16x8*)((LAS char*)SB(b, h) + boff + n * 2048 + k * 1024)
; #define MMA(ai, bj, At_, Bt_) do { __builtin_amdgcn_s_setprio(1); \
;     _Pragma("unroll") for (int m = 0; m < 4; ++m) _Pragma("unroll") for (int n = 0; n < 2; ++n) _Pragma("unroll") for (int k = 0; k < 2; ++k) \
;       acc[ai][bj][m][n] = __builtin_amdgcn_mfma_f32_16x16x32_bf16(Bt_[n][k], At_[m][k], acc[ai][bj][m][n], 0, 0, 0); \
;     __builtin_amdgcn_s_setprio(0); } while (0)
; #define WAIT_V(n) asm volatile("s_waitcnt vmcnt(" #n ")" ::: "memory")
; #define WAIT_L(n) asm volatile("s_waitcnt lgkmcnt(" #n ")" ::: "memory")
; #define BAR __builtin_amdgcn_s_barrier()
; #define SCHED __builtin_amdgcn_sched_barrier(0)
; __device__ __forceinline__ void gemm_phase(const bf16_t* __restrict__ A, const bf16_t* __restrict__ Bt, bf16_t* __restrict__ C, int M, int N, int K,
;                                            int ldc, const int EPI, char* smem, const int wid_u) {
;     ...
;       LDB(B0, 0, 0); SCHED; LDA(At, 0, 0); STG(SA(1, 1), a1 + hstep);
;       WAIT_L(8); BAR; WAIT_L(0); MMA(0, 0, At, B0); BAR; SCHED;
;       LDB(B1, 0, 1); STG(SB(0, 0), b2);
;       BAR; WAIT_L(0); MMA(0, 1, At, B1); BAR;
;       LDA(At, 0, 1); STG(SA(0, 0), a2);
;       BAR; WAIT_L(0); MMA(1, 0, At, B0); BAR; SCHED;
;       STG(SB(0, 1), b2 + hstep);
;       WAIT_V(6); BAR; MMA(1, 1, At, B1); BAR;
.LBB0_145:
	ds_read_b128 v[150:153], v146
	ds_read_b128 v[154:157], v146 offset:1024
	ds_read_b128 v[158:161], v146 offset:2048
	ds_read_b128 v[162:165], v146 offset:3072
	s_add_u32 s18, s16, 0x100
	s_addc_u32 s19, s17, 0
	s_cmp_eq_u32 s49, 12
	s_cselect_b32 s23, s44, s19
	s_cselect_b32 s22, s45, s18
	s_cselect_b32 s21, s11, s48
	s_cselect_b32 s20, s46, s47
	v_lshl_add_u64 v[142:143], s[16:17], 0, v[136:137]
	s_add_i32 m0, s28, 0xc000
	ds_read_b128 v[166:169], v147
	ds_read_b128 v[170:173], v147 offset:1024
	ds_read_b128 v[174:177], v147 offset:2048
	ds_read_b128 v[178:181], v147 offset:3072
	ds_read_b128 v[182:185], v147 offset:4096
	ds_read_b128 v[186:189], v147 offset:5120
	ds_read_b128 v[190:193], v147 offset:6144
	ds_read_b128 v[194:197], v147 offset:7168
	global_load_lds_dwordx4 v[142:143], off
	v_lshl_add_u64 v[142:143], s[16:17], 0, v[134:135]
	s_add_i32 m0, s28, 0xe000
	s_nop 0
	global_load_lds_dwordx4 v[142:143], off
	s_waitcnt lgkmcnt(8)
	s_barrier
	s_waitcnt lgkmcnt(0)
	s_waitcnt lgkmcnt(0)
	v_mfma_f32_16x16x32_bf16 v[124:127], v[150:153], v[166:169], v[124:127]
	v_mfma_f32_16x16x32_bf16 v[120:123], v[158:161], v[166:169], v[120:123]
	v_mfma_f32_16x16x32_bf16 v[108:111], v[150:153], v[174:177], v[108:111]
	v_mfma_f32_16x16x32_bf16 v[104:107], v[158:161], v[174:177], v[104:107]
	v_mfma_f32_16x16x32_bf16 v[92:95], v[150:153], v[182:185], v[92:95]
	v_mfma_f32_16x16x32_bf16 v[88:91], v[158:161], v[182:185], v[88:91]
	v_mfma_f32_16x16x32_bf16 v[76:79], v[150:153], v[190:193], v[76:79]
	v_mfma_f32_16x16x32_bf16 v[72:75], v[158:161], v[190:193], v[72:75]
	v_mfma_f32_16x16x32_bf16 v[124:127], v[154:157], v[170:173], v[124:127]
	v_mfma_f32_16x16x32_bf16 v[120:123], v[162:165], v[170:173], v[120:123]
	v_mfma_f32_16x16x32_bf16 v[108:111], v[154:157], v[178:181], v[108:111]
	v_mfma_f32_16x16x32_bf16 v[104:107], v[162:165], v[178:181], v[104:107]
	v_mfma_f32_16x16x32_bf16 v[92:95], v[154:157], v[186:189], v[92:95]
	v_mfma_f32_16x16x32_bf16 v[88:91], v[162:165], v[186:189], v[88:91]
	v_mfma_f32_16x16x32_bf16 v[76:79], v[154:157], v[194:197], v[76:79]
	v_mfma_f32_16x16x32_bf16 v[72:75], v[162:165], v[194:197], v[72:75]
	s_barrier
	s_add_i32 s16, s36, s27
	v_lshl_add_u64 v[142:143], s[20:21], 0, v[130:131]
	s_mov_b32 m0, s16
	ds_read_b128 v[198:201], v148
	ds_read_b128 v[202:205], v148 offset:1024
	ds_read_b128 v[206:209], v148 offset:2048
	ds_read_b128 v[210:213], v148 offset:3072
	global_load_lds_dwordx4 v[142:143], off
	v_lshl_add_u64 v[214:215], s[20:21], 0, v[128:129]
	s_add_i32 m0, s16, 0x2000
	s_nop 0
	global_load_lds_dwordx4 v[214:215], off
	s_barrier
	s_waitcnt lgkmcnt(0)
	s_waitcnt lgkmcnt(0)
	v_mfma_f32_16x16x32_bf16 v[116:119], v[198:201], v[166:169], v[116:119]
	v_mfma_f32_16x16x32_bf16 v[112:115], v[206:209], v[166:169], v[112:115]
	v_mfma_f32_16x16x32_bf16 v[100:103], v[198:201], v[174:177], v[100:103]
	v_mfma_f32_16x16x32_bf16 v[96:99], v[206:209], v[174:177], v[96:99]
	v_mfma_f32_16x16x32_bf16 v[84:87], v[198:201], v[182:185], v[84:87]
	v_mfma_f32_16x16x32_bf16 v[80:83], v[206:209], v[182:185], v[80:83]
	v_mfma_f32_16x16x32_bf16 v[68:71], v[198:201], v[190:193], v[68:71]
	v_mfma_f32_16x16x32_bf16 v[64:67], v[206:209], v[190:193], v[64:67]
	v_mfma_f32_16x16x32_bf16 v[116:119], v[202:205], v[170:173], v[116:119]
	v_mfma_f32_16x16x32_bf16 v[112:115], v[210:213], v[170:173], v[112:115]
	v_mfma_f32_16x16x32_bf16 v[100:103], v[202:205], v[178:181], v[100:103]
	v_mfma_f32_16x16x32_bf16 v[96:99], v[210:213], v[178:181], v[96:99]
	v_mfma_f32_16x16x32_bf16 v[84:87], v[202:205], v[186:189], v[84:87]
	v_mfma_f32_16x16x32_bf16 v[80:83], v[210:213], v[186:189], v[80:83]
	v_mfma_f32_16x16x32_bf16 v[68:71], v[202:205], v[194:197], v[68:71]
	v_mfma_f32_16x16x32_bf16 v[64:67], v[210:213], v[194:197], v[64:67]
	s_mov_b32 m0, s28
	v_lshl_add_u64 v[216:217], s[22:23], 0, v[130:131]
	s_barrier
	ds_read_b128 v[166:169], v147 offset:16384
	ds_read_b128 v[170:173], v147 offset:17408
	ds_read_b128 v[174:177], v147 offset:18432
	ds_read_b128 v[178:181], v147 offset:19456
	ds_read_b128 v[182:185], v147 offset:20480
	ds_read_b128 v[186:189], v147 offset:21504
	ds_read_b128 v[190:193], v147 offset:22528
	ds_read_b128 v[194:197], v147 offset:23552
	global_load_lds_dwordx4 v[216:217], off
	v_lshl_add_u64 v[218:219], s[22:23], 0, v[128:129]
	s_mov_b32 m0, s29
	s_nop 0
	global_load_lds_dwordx4 v[218:219], off
	s_barrier
	s_waitcnt lgkmcnt(0)
	s_waitcnt lgkmcnt(0)
	v_mfma_f32_16x16x32_bf16 v[60:63], v[150:153], v[166:169], v[60:63]
	v_mfma_f32_16x16x32_bf16 v[56:59], v[158:161], v[166:169], v[56:59]
	v_mfma_f32_16x16x32_bf16 v[44:47], v[150:153], v[174:177], v[44:47]
	v_mfma_f32_16x16x32_bf16 v[40:43], v[158:161], v[174:177], v[40:43]
	v_mfma_f32_16x16x32_bf16 v[28:31], v[150:153], v[182:185], v[28:31]
	v_mfma_f32_16x16x32_bf16 v[24:27], v[158:161], v[182:185], v[24:27]
	v_mfma_f32_16x16x32_bf16 v[12:15], v[150:153], v[190:193], v[12:15]
	v_mfma_f32_16x16x32_bf16 v[8:11], v[158:161], v[190:193], v[8:11]
	v_mfma_f32_16x16x32_bf16 v[60:63], v[154:157], v[170:173], v[60:63]
	v_mfma_f32_16x16x32_bf16 v[56:59], v[162:165], v[170:173], v[56:59]
	v_mfma_f32_16x16x32_bf16 v[44:47], v[154:157], v[178:181], v[44:47]
	v_mfma_f32_16x16x32_bf16 v[40:43], v[162:165], v[178:181], v[40:43]
	v_mfma_f32_16x16x32_bf16 v[28:31], v[154:157], v[186:189], v[28:31]
	v_mfma_f32_16x16x32_bf16 v[24:27], v[162:165], v[186:189], v[24:27]
	v_mfma_f32_16x16x32_bf16 v[12:15], v[154:157], v[194:197], v[12:15]
	v_mfma_f32_16x16x32_bf16 v[8:11], v[162:165], v[194:197], v[8:11]
	s_barrier
; #define STG(P, GB) do { const char* _gb = (GB); \
;     _Pragma("unroll") for (int _i = 0; _i < 2; ++_i) { \
;       __builtin_amdgcn_global_load_lds((const unsigned*)(_gb + voff[_i]), \
;         (LAS unsigned*)((LAS char*)(P) + ldsw + _i * 8192), 16, 0, 0); } } while (0)
; #define LDA(dst, b, h) _Pragma("unroll") for (int m = 0; m < 4; ++m) _Pragma("unroll") for (int k = 0; k < 2; ++k) \
;     dst[m][k] = *(const LAS bf16x8*)((LAS char*)SA(b, h) + aoff + m * 2048 + k * 1024)
; #define LDB(dst, b, h) _Pragma("unroll") for (int n = 0; n < 2; ++n) _Pragma("unroll") for (int k = 0; k < 2; ++k) \
;     dst[n][k] = *(const LAS bf16x8*)((LAS char*)SB(b, h) + boff + n * 2048 + k * 1024)
; #define MMA(ai, bj, At_, Bt_) do { __builtin_amdgcn_s_setprio(1); \
;     _Pragma("unroll") for (int m = 0; m < 4; ++m) _Pragma("unroll") for (int n = 0; n < 2; ++n) _Pragma("unroll") for (int k = 0; k < 2; ++k) \
;       acc[ai][bj][m][n] = __builtin_amdgcn_mfma_f32_16x16x32_bf16(Bt_[n][k], At_[m][k], acc[ai][bj][m][n], 0, 0, 0); \
;     __builtin_amdgcn_s_setprio(0); } while (0)
; #define WAIT_V(n) asm volatile("s_waitcnt vmcnt(" #n ")" ::: "memory")
; #define WAIT_L(n) asm volatile("s_waitcnt lgkmcnt(" #n ")" ::: "memory")
; #define BAR __builtin_amdgcn_s_barrier()
; #define SCHED __builtin_amdgcn_sched_barrier(0)
; __device__ __forceinline__ void gemm_phase(const bf16_t* __restrict__ A, const bf16_t* __restrict__ Bt, bf16_t* __restrict__ C, int M, int N, int K,
;                                            int ldc, const int EPI, char* smem, const int wid_u) {
;     ...
;       WAIT_V(6); BAR; MMA(1, 1, At, B1); BAR;
;       LDB(B0, 1, 0); SCHED; LDA(At, 1, 0); STG(SA(0, 1), a2 + hstep);
;       WAIT_L(8); BAR; WAIT_L(0); MMA(0, 0, At, B0); BAR; SCHED;
;       LDB(B1, 1, 1); STG(SB(1, 0), b3);
;       BAR; WAIT_L(0); MMA(0, 1, At, B1); BAR;
;       LDA(At, 1, 1); STG(SA(1, 0), a3);
;       BAR; WAIT_L(0); MMA(1, 0, At, B0); BAR; SCHED;
	s_add_u32 s16, s20, 0x40000
	s_addc_u32 s17, s21, 0
	s_add_i32 s50, s37, s27
	v_lshl_add_u64 v[150:151], s[16:17], 0, v[130:131]
	s_mov_b32 m0, s50
	s_nop 0
	global_load_lds_dwordx4 v[150:151], off
	v_lshl_add_u64 v[150:151], s[16:17], 0, v[128:129]
	s_add_i32 m0, s50, 0x2000
	s_nop 0
	global_load_lds_dwordx4 v[150:151], off
	s_waitcnt vmcnt(6)
	s_barrier
	v_mfma_f32_16x16x32_bf16 v[52:55], v[198:201], v[166:169], v[52:55]
	v_mfma_f32_16x16x32_bf16 v[48:51], v[206:209], v[166:169], v[48:51]
	v_mfma_f32_16x16x32_bf16 v[36:39], v[198:201], v[174:177], v[36:39]
	v_mfma_f32_16x16x32_bf16 v[32:35], v[206:209], v[174:177], v[32:35]
	v_mfma_f32_16x16x32_bf16 v[20:23], v[198:201], v[182:185], v[20:23]
	v_mfma_f32_16x16x32_bf16 v[16:19], v[206:209], v[182:185], v[16:19]
	v_mfma_f32_16x16x32_bf16 v[4:7], v[198:201], v[190:193], v[4:7]
	v_mfma_f32_16x16x32_bf16 v[0:3], v[206:209], v[190:193], v[0:3]
	v_mfma_f32_16x16x32_bf16 v[52:55], v[202:205], v[170:173], v[52:55]
	v_mfma_f32_16x16x32_bf16 v[48:51], v[210:213], v[170:173], v[48:51]
	v_mfma_f32_16x16x32_bf16 v[36:39], v[202:205], v[178:181], v[36:39]
	v_mfma_f32_16x16x32_bf16 v[32:35], v[210:213], v[178:181], v[32:35]
	v_mfma_f32_16x16x32_bf16 v[20:23], v[202:205], v[186:189], v[20:23]
	v_mfma_f32_16x16x32_bf16 v[16:19], v[210:213], v[186:189], v[16:19]
	v_mfma_f32_16x16x32_bf16 v[4:7], v[202:205], v[194:197], v[4:7]
	v_mfma_f32_16x16x32_bf16 v[0:3], v[210:213], v[194:197], v[0:3]
	s_add_i32 s50, 0, 0x18000
	v_add_u32_e32 v149, s50, v145
	s_barrier
	ds_read_b128 v[150:153], v149
	ds_read_b128 v[154:157], v149 offset:1024
	ds_read_b128 v[158:161], v149 offset:2048
	ds_read_b128 v[162:165], v149 offset:3072
	s_add_u32 s16, s22, 0x40000
	s_addc_u32 s17, s23, 0
	s_mov_b32 m0, s30
	v_lshl_add_u64 v[198:199], s[16:17], 0, v[130:131]
	ds_read_b128 v[166:169], v147 offset:32768
	ds_read_b128 v[170:173], v147 offset:33792
	ds_read_b128 v[174:177], v147 offset:34816
	ds_read_b128 v[178:181], v147 offset:35840
	ds_read_b128 v[182:185], v147 offset:36864
	ds_read_b128 v[186:189], v147 offset:37888
	ds_read_b128 v[190:193], v147 offset:38912
	ds_read_b128 v[194:197], v147 offset:39936
	global_load_lds_dwordx4 v[198:199], off
	v_lshl_add_u64 v[198:199], s[16:17], 0, v[128:129]
	s_mov_b32 m0, s31
	s_nop 0
	global_load_lds_dwordx4 v[198:199], off
	s_waitcnt lgkmcnt(8)
	s_barrier
	s_waitcnt lgkmcnt(0)
	s_waitcnt lgkmcnt(0)
	v_mfma_f32_16x16x32_bf16 v[124:127], v[150:153], v[166:169], v[124:127]
	v_mfma_f32_16x16x32_bf16 v[120:123], v[158:161], v[166:169], v[120:123]
	v_mfma_f32_16x16x32_bf16 v[108:111], v[150:153], v[174:177], v[108:111]
	v_mfma_f32_16x16x32_bf16 v[104:107], v[158:161], v[174:177], v[104:107]
	v_mfma_f32_16x16x32_bf16 v[92:95], v[150:153], v[182:185], v[92:95]
	v_mfma_f32_16x16x32_bf16 v[88:91], v[158:161], v[182:185], v[88:91]
	v_mfma_f32_16x16x32_bf16 v[76:79], v[150:153], v[190:193], v[76:79]
	v_mfma_f32_16x16x32_bf16 v[72:75], v[158:161], v[190:193], v[72:75]
	v_mfma_f32_16x16x32_bf16 v[124:127], v[154:157], v[170:173], v[124:127]
	v_mfma_f32_16x16x32_bf16 v[120:123], v[162:165], v[170:173], v[120:123]
	v_mfma_f32_16x16x32_bf16 v[108:111], v[154:157], v[178:181], v[108:111]
	v_mfma_f32_16x16x32_bf16 v[104:107], v[162:165], v[178:181], v[104:107]
	v_mfma_f32_16x16x32_bf16 v[92:95], v[154:157], v[186:189], v[92:95]
	v_mfma_f32_16x16x32_bf16 v[88:91], v[162:165], v[186:189], v[88:91]
	v_mfma_f32_16x16x32_bf16 v[76:79], v[154:157], v[194:197], v[76:79]
	v_mfma_f32_16x16x32_bf16 v[72:75], v[162:165], v[194:197], v[72:75]
	s_barrier
	s_add_i32 s22, 0, 0x1c000
	s_add_i32 s16, s50, s27
	v_add_u32_e32 v149, s22, v145
	v_lshl_add_u64 v[142:143], v[142:143], 0, s[6:7]
	s_mov_b32 m0, s16
	ds_read_b128 v[198:201], v149
	ds_read_b128 v[202:205], v149 offset:1024
	ds_read_b128 v[206:209], v149 offset:2048
	ds_read_b128 v[210:213], v149 offset:3072
	global_load_lds_dwordx4 v[142:143], off
	v_lshl_add_u64 v[142:143], v[214:215], 0, s[6:7]
	s_add_i32 m0, s16, 0x2000
	s_nop 0
	global_load_lds_dwordx4 v[142:143], off
	s_barrier
	s_waitcnt lgkmcnt(0)
	s_waitcnt lgkmcnt(0)
	v_mfma_f32_16x16x32_bf16 v[116:119], v[198:201], v[166:169], v[116:119]
	v_mfma_f32_16x16x32_bf16 v[112:115], v[206:209], v[166:169], v[112:115]
	v_mfma_f32_16x16x32_bf16 v[100:103], v[198:201], v[174:177], v[100:103]
	v_mfma_f32_16x16x32_bf16 v[96:99], v[206:209], v[174:177], v[96:99]
	v_mfma_f32_16x16x32_bf16 v[84:87], v[198:201], v[182:185], v[84:87]
	v_mfma_f32_16x16x32_bf16 v[80:83], v[206:209], v[182:185], v[80:83]
	v_mfma_f32_16x16x32_bf16 v[68:71], v[198:201], v[190:193], v[68:71]
	v_mfma_f32_16x16x32_bf16 v[64:67], v[206:209], v[190:193], v[64:67]
	v_mfma_f32_16x16x32_bf16 v[116:119], v[202:205], v[170:173], v[116:119]
	v_mfma_f32_16x16x32_bf16 v[112:115], v[210:213], v[170:173], v[112:115]
	v_mfma_f32_16x16x32_bf16 v[100:103], v[202:205], v[178:181], v[100:103]
	v_mfma_f32_16x16x32_bf16 v[96:99], v[210:213], v[178:181], v[96:99]
	v_mfma_f32_16x16x32_bf16 v[84:87], v[202:205], v[186:189], v[84:87]
	v_mfma_f32_16x16x32_bf16 v[80:83], v[210:213], v[186:189], v[80:83]
	v_mfma_f32_16x16x32_bf16 v[68:71], v[202:205], v[194:197], v[68:71]
	v_mfma_f32_16x16x32_bf16 v[64:67], v[210:213], v[194:197], v[64:67]
	s_mov_b32 m0, s34
	v_lshl_add_u64 v[142:143], v[216:217], 0, s[6:7]
	s_barrier
	ds_read_b128 v[166:169], v147 offset:49152
	ds_read_b128 v[170:173], v147 offset:50176
	ds_read_b128 v[174:177], v147 offset:51200
	ds_read_b128 v[178:181], v147 offset:52224
	ds_read_b128 v[182:185], v147 offset:53248
	ds_read_b128 v[186:189], v147 offset:54272
	ds_read_b128 v[190:193], v147 offset:55296
	ds_read_b128 v[194:197], v147 offset:56320
	global_load_lds_dwordx4 v[142:143], off
	v_lshl_add_u64 v[142:143], v[218:219], 0, s[6:7]
	s_mov_b32 m0, s35
	s_nop 0
	global_load_lds_dwordx4 v[142:143], off
	s_barrier
; #define STG(P, GB) do { const char* _gb = (GB); \
;     _Pragma("unroll") for (int _i = 0; _i < 2; ++_i) { \
;       __builtin_amdgcn_global_load_lds((const unsigned*)(_gb + voff[_i]), \
;         (LAS unsigned*)((LAS char*)(P) + ldsw + _i * 8192), 16, 0, 0); } } while (0)
; #define MMA(ai, bj, At_, Bt_) do { __builtin_amdgcn_s_setprio(1); \
;     _Pragma("unroll") for (int m = 0; m < 4; ++m) _Pragma("unroll") for (int n = 0; n < 2; ++n) _Pragma("unroll") for (int k = 0; k < 2; ++k) \
;       acc[ai][bj][m][n] = __builtin_amdgcn_mfma_f32_16x16x32_bf16(Bt_[n][k], At_[m][k], acc[ai][bj][m][n], 0, 0, 0); \
;     __builtin_amdgcn_s_setprio(0); } while (0)
; #define WAIT_V(n) asm volatile("s_waitcnt vmcnt(" #n ")" ::: "memory")
; #define WAIT_L(n) asm volatile("s_waitcnt lgkmcnt(" #n ")" ::: "memory")
; #define BAR __builtin_amdgcn_s_barrier()
; #define SCHED __builtin_amdgcn_sched_barrier(0)
; __device__ __forceinline__ void gemm_phase(const bf16_t* __restrict__ A, const bf16_t* __restrict__ Bt, bf16_t* __restrict__ C, int M, int N, int K,
;                                            int ldc, const int EPI, char* smem, const int wid_u) {
;     ...
;       BAR; WAIT_L(0); MMA(1, 0, At, B0); BAR; SCHED;
;       STG(SB(1, 1), b3 + hstep);
;       WAIT_V(6); BAR; MMA(1, 1, At, B1); BAR;
;     ...
;           } else {
;             float o[8];
; #pragma unroll
;             for (int n = 0; n < 2; ++n) {
;               const f32x4 a = acc[ai][0][m][n], b = acc[ai][1][m][n];
; #pragma unroll
;               for (int j = 0; j < 4; ++j) o[n * 4 + j] = a[j] * __builtin_amdgcn_rcpf(1.f + __expf(-a[j])) * b[j];
;             }
;             *(uint4*)(C + row * ldc + (bcol >> 1) + wc * 32 + fq * 8) = pack8(o);
	s_waitcnt lgkmcnt(0)
	s_waitcnt lgkmcnt(0)
	v_mfma_f32_16x16x32_bf16 v[60:63], v[150:153], v[166:169], v[60:63]
	v_mfma_f32_16x16x32_bf16 v[56:59], v[158:161], v[166:169], v[56:59]
	v_mfma_f32_16x16x32_bf16 v[44:47], v[150:153], v[174:177], v[44:47]
	v_mfma_f32_16x16x32_bf16 v[40:43], v[158:161], v[174:177], v[40:43]
	v_mfma_f32_16x16x32_bf16 v[28:31], v[150:153], v[182:185], v[28:31]
	v_mfma_f32_16x16x32_bf16 v[24:27], v[158:161], v[182:185], v[24:27]
	v_mfma_f32_16x16x32_bf16 v[12:15], v[150:153], v[190:193], v[12:15]
	v_mfma_f32_16x16x32_bf16 v[8:11], v[158:161], v[190:193], v[8:11]
	v_mfma_f32_16x16x32_bf16 v[60:63], v[154:157], v[170:173], v[60:63]
	v_mfma_f32_16x16x32_bf16 v[56:59], v[162:165], v[170:173], v[56:59]
	v_mfma_f32_16x16x32_bf16 v[44:47], v[154:157], v[178:181], v[44:47]
	v_mfma_f32_16x16x32_bf16 v[40:43], v[162:165], v[178:181], v[40:43]
	v_mfma_f32_16x16x32_bf16 v[28:31], v[154:157], v[186:189], v[28:31]
	v_mfma_f32_16x16x32_bf16 v[24:27], v[162:165], v[186:189], v[24:27]
	v_mfma_f32_16x16x32_bf16 v[12:15], v[154:157], v[194:197], v[12:15]
	v_mfma_f32_16x16x32_bf16 v[8:11], v[162:165], v[194:197], v[8:11]
	s_barrier
	s_add_u32 s16, s20, 0x40080
	s_addc_u32 s17, s21, 0
	s_add_i32 s20, s22, s27
	v_lshl_add_u64 v[142:143], s[16:17], 0, v[130:131]
	s_mov_b32 m0, s20
	s_nop 0
	global_load_lds_dwordx4 v[142:143], off
	v_lshl_add_u64 v[142:143], s[16:17], 0, v[128:129]
	s_add_i32 m0, s20, 0x2000
	s_nop 0
	global_load_lds_dwordx4 v[142:143], off
	s_waitcnt vmcnt(6)
	s_barrier
	v_mfma_f32_16x16x32_bf16 v[52:55], v[198:201], v[166:169], v[52:55]
	v_mfma_f32_16x16x32_bf16 v[48:51], v[206:209], v[166:169], v[48:51]
	v_mfma_f32_16x16x32_bf16 v[36:39], v[198:201], v[174:177], v[36:39]
	v_mfma_f32_16x16x32_bf16 v[32:35], v[206:209], v[174:177], v[32:35]
	v_mfma_f32_16x16x32_bf16 v[20:23], v[198:201], v[182:185], v[20:23]
	v_mfma_f32_16x16x32_bf16 v[16:19], v[206:209], v[182:185], v[16:19]
	v_mfma_f32_16x16x32_bf16 v[4:7], v[198:201], v[190:193], v[4:7]
	v_mfma_f32_16x16x32_bf16 v[0:3], v[206:209], v[190:193], v[0:3]
	v_mfma_f32_16x16x32_bf16 v[52:55], v[202:205], v[170:173], v[52:55]
	v_mfma_f32_16x16x32_bf16 v[48:51], v[210:213], v[170:173], v[48:51]
	v_mfma_f32_16x16x32_bf16 v[36:39], v[202:205], v[178:181], v[36:39]
	v_mfma_f32_16x16x32_bf16 v[32:35], v[210:213], v[178:181], v[32:35]
	v_mfma_f32_16x16x32_bf16 v[20:23], v[202:205], v[186:189], v[20:23]
	v_mfma_f32_16x16x32_bf16 v[16:19], v[210:213], v[186:189], v[16:19]
	v_mfma_f32_16x16x32_bf16 v[4:7], v[202:205], v[194:197], v[4:7]
	v_mfma_f32_16x16x32_bf16 v[0:3], v[210:213], v[194:197], v[0:3]
	s_add_i32 s49, s49, 2
	s_add_u32 s47, s47, 0x100
	s_addc_u32 s48, s48, 0
	s_cmp_gt_u32 s49, 13
	s_mov_b64 s[16:17], s[18:19]
	s_barrier
	s_cbranch_scc0 .LBB0_145
	v_mul_f32_e32 v142, 0xbfb8aa3b, v124
	v_exp_f32_e32 v142, v142
	v_mul_f32_e32 v143, 0xbfb8aa3b, v125
	v_exp_f32_e32 v143, v143
	s_lshl_b32 s16, s40, 8
	v_add_f32_e32 v142, 1.0, v142
	v_rcp_f32_e32 v150, v142
	v_add_f32_e32 v142, 1.0, v143
	v_rcp_f32_e32 v151, v142
	s_mov_b32 s17, s9
	v_lshl_add_u32 v149, s41, 8, v144
	v_lshl_add_u64 v[142:143], v[132:133], 0, s[16:17]
	v_pk_mul_f32 v[124:125], v[124:125], v[150:151]
	v_mul_f32_e32 v150, 0xbfb8aa3b, v126
	v_mul_f32_e32 v151, 0xbfb8aa3b, v127
	v_exp_f32_e32 v150, v150
	v_exp_f32_e32 v151, v151
	v_pk_mul_f32 v[116:117], v[124:125], v[116:117]
	s_and_b64 vcc, exec, s[2:3]
	v_add_f32_e32 v124, 1.0, v150
	v_add_f32_e32 v125, 1.0, v151
	v_mul_f32_e32 v150, 0xbfb8aa3b, v120
	v_mul_f32_e32 v151, 0xbfb8aa3b, v121
	v_rcp_f32_e32 v124, v124
	v_rcp_f32_e32 v125, v125
	v_exp_f32_e32 v150, v150
	v_exp_f32_e32 v151, v151
	s_mov_b32 s41, s8
	v_pk_mul_f32 v[124:125], v[126:127], v[124:125]
	v_add_f32_e32 v126, 1.0, v150
	v_add_f32_e32 v127, 1.0, v151
	v_mul_f32_e32 v150, 0xbfb8aa3b, v122
	v_mul_f32_e32 v151, 0xbfb8aa3b, v123
	v_exp_f32_e32 v150, v150
	v_exp_f32_e32 v151, v151
	v_rcp_f32_e32 v126, v126
	v_rcp_f32_e32 v127, v127
	v_add_f32_e32 v150, 1.0, v150
	v_add_f32_e32 v151, 1.0, v151
	v_rcp_f32_e32 v150, v150
	v_rcp_f32_e32 v151, v151
	v_pk_mul_f32 v[120:121], v[120:121], v[126:127]
	v_pk_mul_f32 v[118:119], v[124:125], v[118:119]
	v_pk_mul_f32 v[120:121], v[120:121], v[112:113]
	v_pk_mul_f32 v[112:113], v[122:123], v[150:151]
	s_mov_b32 s40, s10
	v_pk_mul_f32 v[122:123], v[112:113], v[114:115]
	v_mul_f32_e32 v115, 0xbfb8aa3b, v108
	v_cvt_pk_bf16_f32 v112, v116, v117
	v_exp_f32_e32 v116, v115
	v_mul_f32_e32 v115, 0xbfb8aa3b, v109
	v_exp_f32_e32 v117, v115
	v_cvt_pk_bf16_f32 v113, v118, v119
	v_cvt_pk_bf16_f32 v114, v120, v121
	v_cvt_pk_bf16_f32 v115, v122, v123
	v_add_f32_e32 v116, 1.0, v116
	v_add_f32_e32 v117, 1.0, v117
	v_mad_i64_i32 v[118:119], s[16:17], v149, s38, v[142:143]
	v_rcp_f32_e32 v116, v116
	v_rcp_f32_e32 v117, v117
	global_store_dwordx4 v[118:119], v[112:115], off
	s_mov_b64 s[18:19], s[14:15]
	v_pk_mul_f32 v[108:109], v[108:109], v[116:117]
	v_mul_f32_e32 v112, 0xbfb8aa3b, v110
	v_mul_f32_e32 v113, 0xbfb8aa3b, v111
	v_exp_f32_e32 v112, v112
	v_exp_f32_e32 v113, v113
	v_pk_mul_f32 v[100:101], v[108:109], v[100:101]
	v_or_b32_e32 v114, 16, v149
	v_add_f32_e32 v108, 1.0, v112
	v_add_f32_e32 v109, 1.0, v113
	v_mul_f32_e32 v112, 0xbfb8aa3b, v104
	v_mul_f32_e32 v113, 0xbfb8aa3b, v105
	v_rcp_f32_e32 v108, v108
	v_rcp_f32_e32 v109, v109
	v_exp_f32_e32 v112, v112
	v_exp_f32_e32 v113, v113
	v_pk_mul_f32 v[108:109], v[110:111], v[108:109]
	v_add_f32_e32 v110, 1.0, v112
	v_add_f32_e32 v111, 1.0, v113
	v_mul_f32_e32 v112, 0xbfb8aa3b, v106
	v_mul_f32_e32 v113, 0xbfb8aa3b, v107
	v_exp_f32_e32 v112, v112
	v_exp_f32_e32 v113, v113
	v_rcp_f32_e32 v110, v110
	v_rcp_f32_e32 v111, v111
; __device__ __forceinline__ void gemm_phase(const bf16_t* __restrict__ A, const bf16_t* __restrict__ Bt, bf16_t* __restrict__ C, int M, int N, int K,
;                                            int ldc, const int EPI, char* smem, const int wid_u) {
;     ...
;           } else {
;             float o[8];
; #pragma unroll
;             for (int n = 0; n < 2; ++n) {
;               const f32x4 a = acc[ai][0][m][n], b = acc[ai][1][m][n];
; #pragma unroll
;               for (int j = 0; j < 4; ++j) o[n * 4 + j] = a[j] * __builtin_amdgcn_rcpf(1.f + __expf(-a[j])) * b[j];
;             }
;             *(uint4*)(C + row * ldc + (bcol >> 1) + wc * 32 + fq * 8) = pack8(o);
	v_add_f32_e32 v112, 1.0, v112
	v_add_f32_e32 v113, 1.0, v113
	v_rcp_f32_e32 v112, v112
	v_rcp_f32_e32 v113, v113
	v_pk_mul_f32 v[104:105], v[104:105], v[110:111]
	v_pk_mul_f32 v[102:103], v[108:109], v[102:103]
	v_pk_mul_f32 v[104:105], v[104:105], v[96:97]
	v_pk_mul_f32 v[96:97], v[106:107], v[112:113]
	s_nop 0
	v_pk_mul_f32 v[106:107], v[96:97], v[98:99]
	v_mul_f32_e32 v99, 0xbfb8aa3b, v92
	v_cvt_pk_bf16_f32 v96, v100, v101
	v_exp_f32_e32 v100, v99
	v_mul_f32_e32 v99, 0xbfb8aa3b, v93
	v_exp_f32_e32 v101, v99
	v_cvt_pk_bf16_f32 v97, v102, v103
	v_cvt_pk_bf16_f32 v98, v104, v105
	v_cvt_pk_bf16_f32 v99, v106, v107
	v_add_f32_e32 v100, 1.0, v100
	v_add_f32_e32 v101, 1.0, v101
	v_mad_i64_i32 v[102:103], s[16:17], v114, s38, v[142:143]
	v_rcp_f32_e32 v100, v100
	v_rcp_f32_e32 v101, v101
	global_store_dwordx4 v[102:103], v[96:99], off
	v_pk_mul_f32 v[92:93], v[92:93], v[100:101]
	s_nop 0
	v_mul_f32_e32 v96, 0xbfb8aa3b, v94
	v_mul_f32_e32 v97, 0xbfb8aa3b, v95
	v_exp_f32_e32 v96, v96
	v_exp_f32_e32 v97, v97
	v_pk_mul_f32 v[84:85], v[92:93], v[84:85]
	v_or_b32_e32 v98, 32, v149
	v_add_f32_e32 v92, 1.0, v96
	v_add_f32_e32 v93, 1.0, v97
	v_mul_f32_e32 v96, 0xbfb8aa3b, v88
	v_mul_f32_e32 v97, 0xbfb8aa3b, v89
	v_rcp_f32_e32 v92, v92
	v_rcp_f32_e32 v93, v93
	v_exp_f32_e32 v96, v96
	v_exp_f32_e32 v97, v97
	v_pk_mul_f32 v[92:93], v[94:95], v[92:93]
	v_add_f32_e32 v94, 1.0, v96
	v_add_f32_e32 v95, 1.0, v97
	v_mul_f32_e32 v96, 0xbfb8aa3b, v90
	v_mul_f32_e32 v97, 0xbfb8aa3b, v91
	v_exp_f32_e32 v96, v96
	v_exp_f32_e32 v97, v97
	v_rcp_f32_e32 v94, v94
	v_rcp_f32_e32 v95, v95
	v_add_f32_e32 v96, 1.0, v96
	v_add_f32_e32 v97, 1.0, v97
	v_rcp_f32_e32 v96, v96
	v_rcp_f32_e32 v97, v97
	v_pk_mul_f32 v[88:89], v[88:89], v[94:95]
	v_pk_mul_f32 v[86:87], v[92:93], v[86:87]
	v_pk_mul_f32 v[88:89], v[88:89], v[80:81]
	v_pk_mul_f32 v[80:81], v[90:91], v[96:97]
	s_nop 0
	v_pk_mul_f32 v[90:91], v[80:81], v[82:83]
	v_mul_f32_e32 v83, 0xbfb8aa3b, v76
	v_cvt_pk_bf16_f32 v80, v84, v85
	v_exp_f32_e32 v84, v83
	v_mul_f32_e32 v83, 0xbfb8aa3b, v77
	v_exp_f32_e32 v85, v83
	v_cvt_pk_bf16_f32 v81, v86, v87
	v_cvt_pk_bf16_f32 v82, v88, v89
	v_cvt_pk_bf16_f32 v83, v90, v91
	v_add_f32_e32 v84, 1.0, v84
	v_add_f32_e32 v85, 1.0, v85
	v_mad_i64_i32 v[86:87], s[16:17], v98, s38, v[142:143]
	v_rcp_f32_e32 v84, v84
	v_rcp_f32_e32 v85, v85
	global_store_dwordx4 v[86:87], v[80:83], off
	v_pk_mul_f32 v[76:77], v[76:77], v[84:85]
	s_nop 0
	v_mul_f32_e32 v80, 0xbfb8aa3b, v78
	v_mul_f32_e32 v81, 0xbfb8aa3b, v79
	v_exp_f32_e32 v80, v80
	v_exp_f32_e32 v81, v81
	v_pk_mul_f32 v[68:69], v[76:77], v[68:69]
	v_or_b32_e32 v82, 48, v149
	v_add_f32_e32 v76, 1.0, v80
	v_add_f32_e32 v77, 1.0, v81
	v_mul_f32_e32 v80, 0xbfb8aa3b, v72
	v_mul_f32_e32 v81, 0xbfb8aa3b, v73
	v_rcp_f32_e32 v76, v76
	v_rcp_f32_e32 v77, v77
	v_exp_f32_e32 v80, v80
	v_exp_f32_e32 v81, v81
	v_pk_mul_f32 v[76:77], v[78:79], v[76:77]
	v_add_f32_e32 v78, 1.0, v80
	v_add_f32_e32 v79, 1.0, v81
	v_mul_f32_e32 v80, 0xbfb8aa3b, v74
	v_mul_f32_e32 v81, 0xbfb8aa3b, v75
	v_exp_f32_e32 v80, v80
	v_exp_f32_e32 v81, v81
	v_rcp_f32_e32 v78, v78
	v_rcp_f32_e32 v79, v79
	v_add_f32_e32 v80, 1.0, v80
	v_add_f32_e32 v81, 1.0, v81
	v_rcp_f32_e32 v80, v80
	v_rcp_f32_e32 v81, v81
	v_pk_mul_f32 v[72:73], v[72:73], v[78:79]
	v_pk_mul_f32 v[70:71], v[76:77], v[70:71]
	v_pk_mul_f32 v[72:73], v[72:73], v[64:65]
	v_pk_mul_f32 v[64:65], v[74:75], v[80:81]
	s_nop 0
	v_pk_mul_f32 v[74:75], v[64:65], v[66:67]
	v_mul_f32_e32 v67, 0xbfb8aa3b, v60
	v_cvt_pk_bf16_f32 v64, v68, v69
	v_exp_f32_e32 v68, v67
	v_mul_f32_e32 v67, 0xbfb8aa3b, v61
	v_exp_f32_e32 v69, v67
	v_cvt_pk_bf16_f32 v65, v70, v71
	v_cvt_pk_bf16_f32 v66, v72, v73
	v_cvt_pk_bf16_f32 v67, v74, v75
	v_add_f32_e32 v68, 1.0, v68
	v_add_f32_e32 v69, 1.0, v69
	v_mad_i64_i32 v[70:71], s[16:17], v82, s38, v[142:143]
	v_rcp_f32_e32 v68, v68
	v_rcp_f32_e32 v69, v69
	global_store_dwordx4 v[70:71], v[64:67], off
	v_pk_mul_f32 v[60:61], v[60:61], v[68:69]
	s_nop 0
	v_mul_f32_e32 v64, 0xbfb8aa3b, v62
	v_mul_f32_e32 v65, 0xbfb8aa3b, v63
	v_exp_f32_e32 v64, v64
	v_exp_f32_e32 v65, v65
	v_pk_mul_f32 v[52:53], v[60:61], v[52:53]
	v_add_u32_e32 v66, 0x80, v149
	v_add_f32_e32 v60, 1.0, v64
	v_add_f32_e32 v61, 1.0, v65
	v_mul_f32_e32 v64, 0xbfb8aa3b, v56
	v_mul_f32_e32 v65, 0xbfb8aa3b, v57
	v_rcp_f32_e32 v60, v60
	v_rcp_f32_e32 v61, v61
	v_exp_f32_e32 v64, v64
	v_exp_f32_e32 v65, v65
	v_pk_mul_f32 v[60:61], v[62:63], v[60:61]
	v_add_f32_e32 v62, 1.0, v64
	v_add_f32_e32 v63, 1.0, v65
	v_mul_f32_e32 v64, 0xbfb8aa3b, v58
	v_mul_f32_e32 v65, 0xbfb8aa3b, v59
	v_exp_f32_e32 v64, v64
	v_exp_f32_e32 v65, v65
	v_rcp_f32_e32 v62, v62
	v_rcp_f32_e32 v63, v63
	v_add_f32_e32 v64, 1.0, v64
	v_add_f32_e32 v65, 1.0, v65
	v_rcp_f32_e32 v64, v64
	v_rcp_f32_e32 v65, v65
	v_pk_mul_f32 v[56:57], v[56:57], v[62:63]
	v_pk_mul_f32 v[54:55], v[60:61], v[54:55]
	v_pk_mul_f32 v[56:57], v[56:57], v[48:49]
	v_pk_mul_f32 v[48:49], v[58:59], v[64:65]
	s_nop 0
; #define WAIT_V(n) asm volatile("s_waitcnt vmcnt(" #n ")" ::: "memory")
; #define BAR __builtin_amdgcn_s_barrier()
; __device__ __forceinline__ void gemm_phase(const bf16_t* __restrict__ A, const bf16_t* __restrict__ Bt, bf16_t* __restrict__ C, int M, int N, int K,
;                                            int ldc, const int EPI, char* smem, const int wid_u) {
;     ...
;           } else {
;             float o[8];
; #pragma unroll
;             for (int n = 0; n < 2; ++n) {
;               const f32x4 a = acc[ai][0][m][n], b = acc[ai][1][m][n];
; #pragma unroll
;               for (int j = 0; j < 4; ++j) o[n * 4 + j] = a[j] * __builtin_amdgcn_rcpf(1.f + __expf(-a[j])) * b[j];
;             }
;             *(uint4*)(C + row * ldc + (bcol >> 1) + wc * 32 + fq * 8) = pack8(o);
;     ...
;     if (!has_next) break;
; #pragma unroll
;     for (int a = 0; a < 2; ++a)
; #pragma unroll
;       for (int b = 0; b < 2; ++b)
; #pragma unroll
;         for (int m = 0; m < 4; ++m)
; #pragma unroll
;           for (int n = 0; n < 2; ++n) acc[a][b][m][n] = (f32x4){0.f, 0.f, 0.f, 0.f};
;     pm = npm; pn = npn; cA = nA; cB = nB; ++ui;
;   }
;   WAIT_V(0);
;   if (wr == 0) BAR;
;   BAR;
	v_pk_mul_f32 v[58:59], v[48:49], v[50:51]
	v_mul_f32_e32 v51, 0xbfb8aa3b, v44
	v_cvt_pk_bf16_f32 v48, v52, v53
	v_exp_f32_e32 v52, v51
	v_mul_f32_e32 v51, 0xbfb8aa3b, v45
	v_exp_f32_e32 v53, v51
	v_cvt_pk_bf16_f32 v49, v54, v55
	v_cvt_pk_bf16_f32 v50, v56, v57
	v_cvt_pk_bf16_f32 v51, v58, v59
	v_add_f32_e32 v52, 1.0, v52
	v_add_f32_e32 v53, 1.0, v53
	v_mad_i64_i32 v[54:55], s[16:17], v66, s38, v[142:143]
	v_rcp_f32_e32 v52, v52
	v_rcp_f32_e32 v53, v53
	global_store_dwordx4 v[54:55], v[48:51], off
	v_pk_mul_f32 v[44:45], v[44:45], v[52:53]
	s_nop 0
	v_mul_f32_e32 v48, 0xbfb8aa3b, v46
	v_mul_f32_e32 v49, 0xbfb8aa3b, v47
	v_exp_f32_e32 v48, v48
	v_exp_f32_e32 v49, v49
	v_pk_mul_f32 v[36:37], v[44:45], v[36:37]
	v_add_u32_e32 v50, 0x90, v149
	v_add_f32_e32 v44, 1.0, v48
	v_add_f32_e32 v45, 1.0, v49
	v_mul_f32_e32 v48, 0xbfb8aa3b, v40
	v_mul_f32_e32 v49, 0xbfb8aa3b, v41
	v_rcp_f32_e32 v44, v44
	v_rcp_f32_e32 v45, v45
	v_exp_f32_e32 v48, v48
	v_exp_f32_e32 v49, v49
	v_pk_mul_f32 v[44:45], v[46:47], v[44:45]
	v_add_f32_e32 v46, 1.0, v48
	v_add_f32_e32 v47, 1.0, v49
	v_mul_f32_e32 v48, 0xbfb8aa3b, v42
	v_mul_f32_e32 v49, 0xbfb8aa3b, v43
	v_exp_f32_e32 v48, v48
	v_exp_f32_e32 v49, v49
	v_rcp_f32_e32 v46, v46
	v_rcp_f32_e32 v47, v47
	v_add_f32_e32 v48, 1.0, v48
	v_add_f32_e32 v49, 1.0, v49
	v_rcp_f32_e32 v48, v48
	v_rcp_f32_e32 v49, v49
	v_pk_mul_f32 v[40:41], v[40:41], v[46:47]
	v_pk_mul_f32 v[38:39], v[44:45], v[38:39]
	v_pk_mul_f32 v[40:41], v[40:41], v[32:33]
	v_pk_mul_f32 v[32:33], v[42:43], v[48:49]
	s_nop 0
	v_pk_mul_f32 v[42:43], v[32:33], v[34:35]
	v_mul_f32_e32 v35, 0xbfb8aa3b, v28
	v_cvt_pk_bf16_f32 v32, v36, v37
	v_exp_f32_e32 v36, v35
	v_mul_f32_e32 v35, 0xbfb8aa3b, v29
	v_exp_f32_e32 v37, v35
	v_cvt_pk_bf16_f32 v33, v38, v39
	v_cvt_pk_bf16_f32 v34, v40, v41
	v_cvt_pk_bf16_f32 v35, v42, v43
	v_add_f32_e32 v36, 1.0, v36
	v_add_f32_e32 v37, 1.0, v37
	v_mad_i64_i32 v[38:39], s[16:17], v50, s38, v[142:143]
	v_rcp_f32_e32 v36, v36
	v_rcp_f32_e32 v37, v37
	global_store_dwordx4 v[38:39], v[32:35], off
	v_pk_mul_f32 v[28:29], v[28:29], v[36:37]
	s_nop 0
	v_mul_f32_e32 v32, 0xbfb8aa3b, v30
	v_mul_f32_e32 v33, 0xbfb8aa3b, v31
	v_exp_f32_e32 v32, v32
	v_exp_f32_e32 v33, v33
	v_pk_mul_f32 v[20:21], v[28:29], v[20:21]
	v_add_u32_e32 v34, 0xa0, v149
	v_add_f32_e32 v28, 1.0, v32
	v_add_f32_e32 v29, 1.0, v33
	v_mul_f32_e32 v32, 0xbfb8aa3b, v24
	v_mul_f32_e32 v33, 0xbfb8aa3b, v25
	v_rcp_f32_e32 v28, v28
	v_rcp_f32_e32 v29, v29
	v_exp_f32_e32 v32, v32
	v_exp_f32_e32 v33, v33
	v_pk_mul_f32 v[28:29], v[30:31], v[28:29]
	v_add_f32_e32 v30, 1.0, v32
	v_add_f32_e32 v31, 1.0, v33
	v_mul_f32_e32 v32, 0xbfb8aa3b, v26
	v_mul_f32_e32 v33, 0xbfb8aa3b, v27
	v_exp_f32_e32 v32, v32
	v_exp_f32_e32 v33, v33
	v_rcp_f32_e32 v30, v30
	v_rcp_f32_e32 v31, v31
	v_add_f32_e32 v32, 1.0, v32
	v_add_f32_e32 v33, 1.0, v33
	v_rcp_f32_e32 v32, v32
	v_rcp_f32_e32 v33, v33
	v_pk_mul_f32 v[24:25], v[24:25], v[30:31]
	v_pk_mul_f32 v[22:23], v[28:29], v[22:23]
	v_pk_mul_f32 v[24:25], v[24:25], v[16:17]
	v_pk_mul_f32 v[16:17], v[26:27], v[32:33]
	s_nop 0
	v_pk_mul_f32 v[26:27], v[16:17], v[18:19]
	v_mul_f32_e32 v19, 0xbfb8aa3b, v12
	v_cvt_pk_bf16_f32 v16, v20, v21
	v_exp_f32_e32 v20, v19
	v_mul_f32_e32 v19, 0xbfb8aa3b, v13
	v_exp_f32_e32 v21, v19
	v_cvt_pk_bf16_f32 v17, v22, v23
	v_cvt_pk_bf16_f32 v18, v24, v25
	v_cvt_pk_bf16_f32 v19, v26, v27
	v_add_f32_e32 v20, 1.0, v20
	v_add_f32_e32 v21, 1.0, v21
	v_mad_i64_i32 v[22:23], s[16:17], v34, s38, v[142:143]
	v_rcp_f32_e32 v20, v20
	v_rcp_f32_e32 v21, v21
	global_store_dwordx4 v[22:23], v[16:19], off
	v_pk_mul_f32 v[12:13], v[12:13], v[20:21]
	s_nop 0
	v_mul_f32_e32 v16, 0xbfb8aa3b, v14
	v_mul_f32_e32 v17, 0xbfb8aa3b, v15
	v_exp_f32_e32 v16, v16
	v_exp_f32_e32 v17, v17
	v_pk_mul_f32 v[4:5], v[12:13], v[4:5]
	v_add_u32_e32 v18, 0xb0, v149
	v_add_f32_e32 v12, 1.0, v16
	v_add_f32_e32 v13, 1.0, v17
	v_mul_f32_e32 v16, 0xbfb8aa3b, v8
	v_mul_f32_e32 v17, 0xbfb8aa3b, v9
	v_rcp_f32_e32 v12, v12
	v_rcp_f32_e32 v13, v13
	v_exp_f32_e32 v16, v16
	v_exp_f32_e32 v17, v17
	v_pk_mul_f32 v[12:13], v[14:15], v[12:13]
	v_add_f32_e32 v14, 1.0, v16
	v_add_f32_e32 v15, 1.0, v17
	v_mul_f32_e32 v16, 0xbfb8aa3b, v10
	v_mul_f32_e32 v17, 0xbfb8aa3b, v11
	v_exp_f32_e32 v16, v16
	v_exp_f32_e32 v17, v17
	v_rcp_f32_e32 v14, v14
	v_rcp_f32_e32 v15, v15
	v_add_f32_e32 v16, 1.0, v16
	v_add_f32_e32 v17, 1.0, v17
	v_rcp_f32_e32 v16, v16
	v_rcp_f32_e32 v17, v17
	v_pk_mul_f32 v[8:9], v[8:9], v[14:15]
	v_pk_mul_f32 v[6:7], v[12:13], v[6:7]
	v_pk_mul_f32 v[8:9], v[8:9], v[0:1]
	v_pk_mul_f32 v[0:1], v[10:11], v[16:17]
	s_nop 0
	v_pk_mul_f32 v[10:11], v[0:1], v[2:3]
	v_cvt_pk_bf16_f32 v0, v4, v5
	v_mad_i64_i32 v[4:5], s[16:17], v18, s38, v[142:143]
	v_cvt_pk_bf16_f32 v1, v6, v7
	v_cvt_pk_bf16_f32 v2, v8, v9
	v_cvt_pk_bf16_f32 v3, v10, v11
	s_mov_b64 s[16:17], s[12:13]
	global_store_dwordx4 v[4:5], v[0:3], off
	s_cbranch_vccz .LBB0_142
	s_waitcnt vmcnt(0)
	s_cmpk_gt_u32 s24, 0xff
	s_cbranch_scc1 .LBB0_149
	s_barrier

; #define STG(P, GB) do { const char* _gb = (GB); \
;     _Pragma("unroll") for (int _i = 0; _i < 2; ++_i) { \
;       __builtin_amdgcn_global_load_lds((const unsigned*)(_gb + voff[_i]), \
;         (LAS unsigned*)((LAS char*)(P) + ldsw + _i * 8192), 16, 0, 0); } } while (0)
; #define LDA(dst, b, h) _Pragma("unroll") for (int m = 0; m < 4; ++m) _Pragma("unroll") for (int k = 0; k < 2; ++k) \
;     dst[m][k] = *(const LAS bf16x8*)((LAS char*)SA(b, h) + aoff + m * 2048 + k * 1024)
; #define LDB(dst, b, h) _Pragma("unroll") for (int n = 0; n < 2; ++n) _Pragma("unroll") for (int k = 0; k < 2; ++k) \
;     dst[n][k] = *(const LAS bf16x8*)((LAS char*)SB(b, h) + boff + n * 2048 + k * 1024)
; #define MMA(ai, bj, At_, Bt_) do { __builtin_amdgcn_s_setprio(1); \
;     _Pragma("unroll") for (int m = 0; m < 4; ++m) _Pragma("unroll") for (int n = 0; n < 2; ++n) _Pragma("unroll") for (int k = 0; k < 2; ++k) \
;       acc[ai][bj][m][n] = __builtin_amdgcn_mfma_f32_16x16x32_bf16(Bt_[n][k], At_[m][k], acc[ai][bj][m][n], 0, 0, 0); \
;     __builtin_amdgcn_s_setprio(0); } while (0)
; #define WAIT_V(n) asm volatile("s_waitcnt vmcnt(" #n ")" ::: "memory")
; #define WAIT_L(n) asm volatile("s_waitcnt lgkmcnt(" #n ")" ::: "memory")
; #define BAR __builtin_amdgcn_s_barrier()
; #define SCHED __builtin_amdgcn_sched_barrier(0)
; __device__ __forceinline__ void gemm_phase(const bf16_t* __restrict__ A, const bf16_t* __restrict__ Bt, bf16_t* __restrict__ C, int M, int N, int K,
;                                            int ldc, const int EPI, char* smem, const int wid_u) {
;     ...
;       LDB(B0, 0, 0); SCHED; LDA(At, 0, 0); STG(SA(1, 1), a1 + hstep);
;       WAIT_L(8); BAR; WAIT_L(0); MMA(0, 0, At, B0); BAR; SCHED;
;       LDB(B1, 0, 1); STG(SB(0, 0), b2);
;       BAR; WAIT_L(0); MMA(0, 1, At, B1); BAR;
;       LDA(At, 0, 1); STG(SA(0, 0), a2);
;       BAR; WAIT_L(0); MMA(1, 0, At, B0); BAR; SCHED;
;       STG(SB(0, 1), b2 + hstep);
;       WAIT_V(6); BAR; MMA(1, 1, At, B1); BAR;
.LBB0_213:
	ds_read_b128 v[148:151], v143
	ds_read_b128 v[152:155], v143 offset:1024
	ds_read_b128 v[156:159], v143 offset:2048
	ds_read_b128 v[160:163], v143 offset:3072
	s_add_u32 s16, s14, 0x100
	s_addc_u32 s17, s15, 0
	s_cmp_eq_u32 s53, 40
	s_cselect_b32 s21, s5, s17
	s_cselect_b32 s20, s4, s16
	s_cselect_b32 s19, s7, s52
	s_cselect_b32 s18, s6, s51
	s_mov_b32 m0, s36
	v_lshl_add_u64 v[196:197], s[14:15], 0, v[136:137]
	ds_read_b128 v[164:167], v144
	ds_read_b128 v[168:171], v144 offset:1024
	ds_read_b128 v[172:175], v144 offset:2048
	ds_read_b128 v[176:179], v144 offset:3072
	ds_read_b128 v[180:183], v144 offset:4096
	ds_read_b128 v[184:187], v144 offset:5120
	ds_read_b128 v[188:191], v144 offset:6144
	ds_read_b128 v[192:195], v144 offset:7168
	global_load_lds_dwordx4 v[196:197], off
	v_lshl_add_u64 v[196:197], s[14:15], 0, v[134:135]
	s_mov_b32 m0, s37
	s_nop 0
	global_load_lds_dwordx4 v[196:197], off
	s_waitcnt lgkmcnt(8)
	s_barrier
	s_waitcnt lgkmcnt(0)
	s_waitcnt lgkmcnt(0)
	v_mfma_f32_16x16x32_bf16 v[124:127], v[148:151], v[164:167], v[124:127]
	v_mfma_f32_16x16x32_bf16 v[120:123], v[156:159], v[164:167], v[120:123]
	v_mfma_f32_16x16x32_bf16 v[116:119], v[148:151], v[172:175], v[116:119]
	v_mfma_f32_16x16x32_bf16 v[112:115], v[156:159], v[172:175], v[112:115]
	v_mfma_f32_16x16x32_bf16 v[100:103], v[148:151], v[180:183], v[100:103]
	v_mfma_f32_16x16x32_bf16 v[96:99], v[156:159], v[180:183], v[96:99]
	v_mfma_f32_16x16x32_bf16 v[84:87], v[148:151], v[188:191], v[84:87]
	v_mfma_f32_16x16x32_bf16 v[80:83], v[156:159], v[188:191], v[80:83]
	v_mfma_f32_16x16x32_bf16 v[124:127], v[152:155], v[168:171], v[124:127]
	v_mfma_f32_16x16x32_bf16 v[120:123], v[160:163], v[168:171], v[120:123]
	v_mfma_f32_16x16x32_bf16 v[116:119], v[152:155], v[176:179], v[116:119]
	v_mfma_f32_16x16x32_bf16 v[112:115], v[160:163], v[176:179], v[112:115]
	v_mfma_f32_16x16x32_bf16 v[100:103], v[152:155], v[184:187], v[100:103]
	v_mfma_f32_16x16x32_bf16 v[96:99], v[160:163], v[184:187], v[96:99]
	v_mfma_f32_16x16x32_bf16 v[84:87], v[152:155], v[192:195], v[84:87]
	v_mfma_f32_16x16x32_bf16 v[80:83], v[160:163], v[192:195], v[80:83]
	s_barrier
	s_mov_b32 m0, s38
	v_lshl_add_u64 v[212:213], s[18:19], 0, v[130:131]
	ds_read_b128 v[196:199], v145
	ds_read_b128 v[200:203], v145 offset:1024
	ds_read_b128 v[204:207], v145 offset:2048
	ds_read_b128 v[208:211], v145 offset:3072
	global_load_lds_dwordx4 v[212:213], off
	v_lshl_add_u64 v[214:215], s[18:19], 0, v[128:129]
	s_mov_b32 m0, s39
	s_nop 0
	global_load_lds_dwordx4 v[214:215], off
	s_barrier
	s_waitcnt lgkmcnt(0)
	s_waitcnt lgkmcnt(0)
	v_mfma_f32_16x16x32_bf16 v[108:111], v[196:199], v[164:167], v[108:111]
	v_mfma_f32_16x16x32_bf16 v[104:107], v[204:207], v[164:167], v[104:107]
	v_mfma_f32_16x16x32_bf16 v[92:95], v[196:199], v[172:175], v[92:95]
	v_mfma_f32_16x16x32_bf16 v[88:91], v[204:207], v[172:175], v[88:91]
	v_mfma_f32_16x16x32_bf16 v[76:79], v[196:199], v[180:183], v[76:79]
	v_mfma_f32_16x16x32_bf16 v[72:75], v[204:207], v[180:183], v[72:75]
	v_mfma_f32_16x16x32_bf16 v[68:71], v[196:199], v[188:191], v[68:71]
	v_mfma_f32_16x16x32_bf16 v[64:67], v[204:207], v[188:191], v[64:67]
	v_mfma_f32_16x16x32_bf16 v[108:111], v[200:203], v[168:171], v[108:111]
	v_mfma_f32_16x16x32_bf16 v[104:107], v[208:211], v[168:171], v[104:107]
	v_mfma_f32_16x16x32_bf16 v[92:95], v[200:203], v[176:179], v[92:95]
	v_mfma_f32_16x16x32_bf16 v[88:91], v[208:211], v[176:179], v[88:91]
	v_mfma_f32_16x16x32_bf16 v[76:79], v[200:203], v[184:187], v[76:79]
	v_mfma_f32_16x16x32_bf16 v[72:75], v[208:211], v[184:187], v[72:75]
	v_mfma_f32_16x16x32_bf16 v[68:71], v[200:203], v[192:195], v[68:71]
	v_mfma_f32_16x16x32_bf16 v[64:67], v[208:211], v[192:195], v[64:67]
	s_mov_b32 m0, s28
	v_lshl_add_u64 v[216:217], s[20:21], 0, v[130:131]
	s_barrier
	ds_read_b128 v[164:167], v144 offset:16384
	ds_read_b128 v[168:171], v144 offset:17408
	ds_read_b128 v[172:175], v144 offset:18432
	ds_read_b128 v[176:179], v144 offset:19456
	ds_read_b128 v[180:183], v144 offset:20480
	ds_read_b128 v[184:187], v144 offset:21504
	ds_read_b128 v[188:191], v144 offset:22528
	ds_read_b128 v[192:195], v144 offset:23552
	global_load_lds_dwordx4 v[216:217], off
	v_lshl_add_u64 v[218:219], s[20:21], 0, v[128:129]
	s_mov_b32 m0, s29
	s_nop 0
	global_load_lds_dwordx4 v[218:219], off
	s_barrier
	s_waitcnt lgkmcnt(0)
	s_waitcnt lgkmcnt(0)
	v_mfma_f32_16x16x32_bf16 v[60:63], v[148:151], v[164:167], v[60:63]
	v_mfma_f32_16x16x32_bf16 v[56:59], v[156:159], v[164:167], v[56:59]
	v_mfma_f32_16x16x32_bf16 v[52:55], v[148:151], v[172:175], v[52:55]
	v_mfma_f32_16x16x32_bf16 v[48:51], v[156:159], v[172:175], v[48:51]
	v_mfma_f32_16x16x32_bf16 v[36:39], v[148:151], v[180:183], v[36:39]
	v_mfma_f32_16x16x32_bf16 v[32:35], v[156:159], v[180:183], v[32:35]
	v_mfma_f32_16x16x32_bf16 v[20:23], v[148:151], v[188:191], v[20:23]
	v_mfma_f32_16x16x32_bf16 v[16:19], v[156:159], v[188:191], v[16:19]
	v_mfma_f32_16x16x32_bf16 v[60:63], v[152:155], v[168:171], v[60:63]
	v_mfma_f32_16x16x32_bf16 v[56:59], v[160:163], v[168:171], v[56:59]
	v_mfma_f32_16x16x32_bf16 v[52:55], v[152:155], v[176:179], v[52:55]
	v_mfma_f32_16x16x32_bf16 v[48:51], v[160:163], v[176:179], v[48:51]
	v_mfma_f32_16x16x32_bf16 v[36:39], v[152:155], v[184:187], v[36:39]
	v_mfma_f32_16x16x32_bf16 v[32:35], v[160:163], v[184:187], v[32:35]
	v_mfma_f32_16x16x32_bf16 v[20:23], v[152:155], v[192:195], v[20:23]
	v_mfma_f32_16x16x32_bf16 v[16:19], v[160:163], v[192:195], v[16:19]
	s_barrier
; #define STG(P, GB) do { const char* _gb = (GB); \
;     _Pragma("unroll") for (int _i = 0; _i < 2; ++_i) { \
;       __builtin_amdgcn_global_load_lds((const unsigned*)(_gb + voff[_i]), \
;         (LAS unsigned*)((LAS char*)(P) + ldsw + _i * 8192), 16, 0, 0); } } while (0)
; #define LDA(dst, b, h) _Pragma("unroll") for (int m = 0; m < 4; ++m) _Pragma("unroll") for (int k = 0; k < 2; ++k) \
;     dst[m][k] = *(const LAS bf16x8*)((LAS char*)SA(b, h) + aoff + m * 2048 + k * 1024)
; #define LDB(dst, b, h) _Pragma("unroll") for (int n = 0; n < 2; ++n) _Pragma("unroll") for (int k = 0; k < 2; ++k) \
;     dst[n][k] = *(const LAS bf16x8*)((LAS char*)SB(b, h) + boff + n * 2048 + k * 1024)
; #define MMA(ai, bj, At_, Bt_) do { __builtin_amdgcn_s_setprio(1); \
;     _Pragma("unroll") for (int m = 0; m < 4; ++m) _Pragma("unroll") for (int n = 0; n < 2; ++n) _Pragma("unroll") for (int k = 0; k < 2; ++k) \
;       acc[ai][bj][m][n] = __builtin_amdgcn_mfma_f32_16x16x32_bf16(Bt_[n][k], At_[m][k], acc[ai][bj][m][n], 0, 0, 0); \
;     __builtin_amdgcn_s_setprio(0); } while (0)
; #define WAIT_V(n) asm volatile("s_waitcnt vmcnt(" #n ")" ::: "memory")
; #define WAIT_L(n) asm volatile("s_waitcnt lgkmcnt(" #n ")" ::: "memory")
; #define BAR __builtin_amdgcn_s_barrier()
; #define SCHED __builtin_amdgcn_sched_barrier(0)
; __device__ __forceinline__ void gemm_phase(const bf16_t* __restrict__ A, const bf16_t* __restrict__ Bt, bf16_t* __restrict__ C, int M, int N, int K,
;                                            int ldc, const int EPI, char* smem, const int wid_u) {
;     ...
;       WAIT_V(6); BAR; MMA(1, 1, At, B1); BAR;
;       LDB(B0, 1, 0); SCHED; LDA(At, 1, 0); STG(SA(0, 1), a2 + hstep);
;       WAIT_L(8); BAR; WAIT_L(0); MMA(0, 0, At, B0); BAR; SCHED;
;       LDB(B1, 1, 1); STG(SB(1, 0), b3);
;       BAR; WAIT_L(0); MMA(0, 1, At, B1); BAR;
;       LDA(At, 1, 1); STG(SA(1, 0), a3);
;       BAR; WAIT_L(0); MMA(1, 0, At, B0); BAR; SCHED;
	s_add_u32 s14, s18, 0xb0000
	s_addc_u32 s15, s19, 0
	s_mov_b32 m0, s40
	v_lshl_add_u64 v[148:149], s[14:15], 0, v[130:131]
	global_load_lds_dwordx4 v[148:149], off
	v_lshl_add_u64 v[148:149], s[14:15], 0, v[128:129]
	s_mov_b32 m0, s41
	s_nop 0
	global_load_lds_dwordx4 v[148:149], off
	s_waitcnt vmcnt(6)
	s_barrier
	v_mfma_f32_16x16x32_bf16 v[44:47], v[196:199], v[164:167], v[44:47]
	v_mfma_f32_16x16x32_bf16 v[40:43], v[204:207], v[164:167], v[40:43]
	v_mfma_f32_16x16x32_bf16 v[28:31], v[196:199], v[172:175], v[28:31]
	v_mfma_f32_16x16x32_bf16 v[24:27], v[204:207], v[172:175], v[24:27]
	v_mfma_f32_16x16x32_bf16 v[12:15], v[196:199], v[180:183], v[12:15]
	v_mfma_f32_16x16x32_bf16 v[8:11], v[204:207], v[180:183], v[8:11]
	v_mfma_f32_16x16x32_bf16 v[4:7], v[196:199], v[188:191], v[4:7]
	v_mfma_f32_16x16x32_bf16 v[0:3], v[204:207], v[188:191], v[0:3]
	v_mfma_f32_16x16x32_bf16 v[44:47], v[200:203], v[168:171], v[44:47]
	v_mfma_f32_16x16x32_bf16 v[40:43], v[208:211], v[168:171], v[40:43]
	v_mfma_f32_16x16x32_bf16 v[28:31], v[200:203], v[176:179], v[28:31]
	v_mfma_f32_16x16x32_bf16 v[24:27], v[208:211], v[176:179], v[24:27]
	v_mfma_f32_16x16x32_bf16 v[12:15], v[200:203], v[184:187], v[12:15]
	v_mfma_f32_16x16x32_bf16 v[8:11], v[208:211], v[184:187], v[8:11]
	v_mfma_f32_16x16x32_bf16 v[4:7], v[200:203], v[192:195], v[4:7]
	v_mfma_f32_16x16x32_bf16 v[0:3], v[208:211], v[192:195], v[0:3]
	s_barrier
	ds_read_b128 v[148:151], v146
	ds_read_b128 v[152:155], v146 offset:1024
	ds_read_b128 v[156:159], v146 offset:2048
	ds_read_b128 v[160:163], v146 offset:3072
	s_add_u32 s14, s20, 0xb0000
	s_addc_u32 s15, s21, 0
	s_mov_b32 m0, s30
	v_lshl_add_u64 v[196:197], s[14:15], 0, v[130:131]
	ds_read_b128 v[164:167], v144 offset:32768
	ds_read_b128 v[168:171], v144 offset:33792
	ds_read_b128 v[172:175], v144 offset:34816
	ds_read_b128 v[176:179], v144 offset:35840
	ds_read_b128 v[180:183], v144 offset:36864
	ds_read_b128 v[184:187], v144 offset:37888
	ds_read_b128 v[188:191], v144 offset:38912
	ds_read_b128 v[192:195], v144 offset:39936
	global_load_lds_dwordx4 v[196:197], off
	v_lshl_add_u64 v[196:197], s[14:15], 0, v[128:129]
	s_mov_b32 m0, s31
	s_nop 0
	global_load_lds_dwordx4 v[196:197], off
	s_waitcnt lgkmcnt(8)
	s_barrier
	s_waitcnt lgkmcnt(0)
	s_waitcnt lgkmcnt(0)
	v_mfma_f32_16x16x32_bf16 v[124:127], v[148:151], v[164:167], v[124:127]
	v_mfma_f32_16x16x32_bf16 v[120:123], v[156:159], v[164:167], v[120:123]
	v_mfma_f32_16x16x32_bf16 v[116:119], v[148:151], v[172:175], v[116:119]
	v_mfma_f32_16x16x32_bf16 v[112:115], v[156:159], v[172:175], v[112:115]
	v_mfma_f32_16x16x32_bf16 v[100:103], v[148:151], v[180:183], v[100:103]
	v_mfma_f32_16x16x32_bf16 v[96:99], v[156:159], v[180:183], v[96:99]
	v_mfma_f32_16x16x32_bf16 v[84:87], v[148:151], v[188:191], v[84:87]
	v_mfma_f32_16x16x32_bf16 v[80:83], v[156:159], v[188:191], v[80:83]
	v_mfma_f32_16x16x32_bf16 v[124:127], v[152:155], v[168:171], v[124:127]
	v_mfma_f32_16x16x32_bf16 v[120:123], v[160:163], v[168:171], v[120:123]
	v_mfma_f32_16x16x32_bf16 v[116:119], v[152:155], v[176:179], v[116:119]
	v_mfma_f32_16x16x32_bf16 v[112:115], v[160:163], v[176:179], v[112:115]
	v_mfma_f32_16x16x32_bf16 v[100:103], v[152:155], v[184:187], v[100:103]
	v_mfma_f32_16x16x32_bf16 v[96:99], v[160:163], v[184:187], v[96:99]
	v_mfma_f32_16x16x32_bf16 v[84:87], v[152:155], v[192:195], v[84:87]
	v_mfma_f32_16x16x32_bf16 v[80:83], v[160:163], v[192:195], v[80:83]
	s_barrier
	s_mov_b32 m0, s45
	v_lshl_add_u64 v[212:213], v[212:213], 0, s[12:13]
	ds_read_b128 v[196:199], v147
	ds_read_b128 v[200:203], v147 offset:1024
	ds_read_b128 v[204:207], v147 offset:2048
	ds_read_b128 v[208:211], v147 offset:3072
	global_load_lds_dwordx4 v[212:213], off
	v_lshl_add_u64 v[212:213], v[214:215], 0, s[12:13]
	s_mov_b32 m0, s46
	s_nop 0
	global_load_lds_dwordx4 v[212:213], off
	s_barrier
	s_waitcnt lgkmcnt(0)
	s_waitcnt lgkmcnt(0)
	v_mfma_f32_16x16x32_bf16 v[108:111], v[196:199], v[164:167], v[108:111]
	v_mfma_f32_16x16x32_bf16 v[104:107], v[204:207], v[164:167], v[104:107]
	v_mfma_f32_16x16x32_bf16 v[92:95], v[196:199], v[172:175], v[92:95]
	v_mfma_f32_16x16x32_bf16 v[88:91], v[204:207], v[172:175], v[88:91]
	v_mfma_f32_16x16x32_bf16 v[76:79], v[196:199], v[180:183], v[76:79]
	v_mfma_f32_16x16x32_bf16 v[72:75], v[204:207], v[180:183], v[72:75]
	v_mfma_f32_16x16x32_bf16 v[68:71], v[196:199], v[188:191], v[68:71]
	v_mfma_f32_16x16x32_bf16 v[64:67], v[204:207], v[188:191], v[64:67]
	v_mfma_f32_16x16x32_bf16 v[108:111], v[200:203], v[168:171], v[108:111]
	v_mfma_f32_16x16x32_bf16 v[104:107], v[208:211], v[168:171], v[104:107]
	v_mfma_f32_16x16x32_bf16 v[92:95], v[200:203], v[176:179], v[92:95]
	v_mfma_f32_16x16x32_bf16 v[88:91], v[208:211], v[176:179], v[88:91]
	v_mfma_f32_16x16x32_bf16 v[76:79], v[200:203], v[184:187], v[76:79]
	v_mfma_f32_16x16x32_bf16 v[72:75], v[208:211], v[184:187], v[72:75]
	v_mfma_f32_16x16x32_bf16 v[68:71], v[200:203], v[192:195], v[68:71]
	v_mfma_f32_16x16x32_bf16 v[64:67], v[208:211], v[192:195], v[64:67]
	s_mov_b32 m0, s34
	v_lshl_add_u64 v[212:213], v[216:217], 0, s[12:13]
	s_barrier
	ds_read_b128 v[164:167], v144 offset:49152
	ds_read_b128 v[168:171], v144 offset:50176
	ds_read_b128 v[172:175], v144 offset:51200
	ds_read_b128 v[176:179], v144 offset:52224
	ds_read_b128 v[180:183], v144 offset:53248
	ds_read_b128 v[184:187], v144 offset:54272
	ds_read_b128 v[188:191], v144 offset:55296
	ds_read_b128 v[192:195], v144 offset:56320
	global_load_lds_dwordx4 v[212:213], off
	v_lshl_add_u64 v[212:213], v[218:219], 0, s[12:13]
	s_mov_b32 m0, s35
	s_nop 0
	global_load_lds_dwordx4 v[212:213], off
	s_barrier
; #define STG(P, GB) do { const char* _gb = (GB); \
;     _Pragma("unroll") for (int _i = 0; _i < 2; ++_i) { \
;       __builtin_amdgcn_global_load_lds((const unsigned*)(_gb + voff[_i]), \
;         (LAS unsigned*)((LAS char*)(P) + ldsw + _i * 8192), 16, 0, 0); } } while (0)
; #define MMA(ai, bj, At_, Bt_) do { __builtin_amdgcn_s_setprio(1); \
;     _Pragma("unroll") for (int m = 0; m < 4; ++m) _Pragma("unroll") for (int n = 0; n < 2; ++n) _Pragma("unroll") for (int k = 0; k < 2; ++k) \
;       acc[ai][bj][m][n] = __builtin_amdgcn_mfma_f32_16x16x32_bf16(Bt_[n][k], At_[m][k], acc[ai][bj][m][n], 0, 0, 0); \
;     __builtin_amdgcn_s_setprio(0); } while (0)
; #define WAIT_V(n) asm volatile("s_waitcnt vmcnt(" #n ")" ::: "memory")
; #define WAIT_L(n) asm volatile("s_waitcnt lgkmcnt(" #n ")" ::: "memory")
; #define BAR __builtin_amdgcn_s_barrier()
; #define SCHED __builtin_amdgcn_sched_barrier(0)
; __device__ __forceinline__ void gemm_phase(const bf16_t* __restrict__ A, const bf16_t* __restrict__ Bt, bf16_t* __restrict__ C, int M, int N, int K,
;                                            int ldc, const int EPI, char* smem, const int wid_u) {
;     ...
;       BAR; WAIT_L(0); MMA(1, 0, At, B0); BAR; SCHED;
;       STG(SB(1, 1), b3 + hstep);
;       WAIT_V(6); BAR; MMA(1, 1, At, B1); BAR;
	s_waitcnt lgkmcnt(0)
	s_waitcnt lgkmcnt(0)
	v_mfma_f32_16x16x32_bf16 v[60:63], v[148:151], v[164:167], v[60:63]
	v_mfma_f32_16x16x32_bf16 v[56:59], v[156:159], v[164:167], v[56:59]
	v_mfma_f32_16x16x32_bf16 v[52:55], v[148:151], v[172:175], v[52:55]
	v_mfma_f32_16x16x32_bf16 v[48:51], v[156:159], v[172:175], v[48:51]
	v_mfma_f32_16x16x32_bf16 v[36:39], v[148:151], v[180:183], v[36:39]
	v_mfma_f32_16x16x32_bf16 v[32:35], v[156:159], v[180:183], v[32:35]
	v_mfma_f32_16x16x32_bf16 v[20:23], v[148:151], v[188:191], v[20:23]
	v_mfma_f32_16x16x32_bf16 v[16:19], v[156:159], v[188:191], v[16:19]
	v_mfma_f32_16x16x32_bf16 v[60:63], v[152:155], v[168:171], v[60:63]
	v_mfma_f32_16x16x32_bf16 v[56:59], v[160:163], v[168:171], v[56:59]
	v_mfma_f32_16x16x32_bf16 v[52:55], v[152:155], v[176:179], v[52:55]
	v_mfma_f32_16x16x32_bf16 v[48:51], v[160:163], v[176:179], v[48:51]
	v_mfma_f32_16x16x32_bf16 v[36:39], v[152:155], v[184:187], v[36:39]
	v_mfma_f32_16x16x32_bf16 v[32:35], v[160:163], v[184:187], v[32:35]
	v_mfma_f32_16x16x32_bf16 v[20:23], v[152:155], v[192:195], v[20:23]
	v_mfma_f32_16x16x32_bf16 v[16:19], v[160:163], v[192:195], v[16:19]
	s_barrier
	s_add_u32 s14, s18, 0xb0080
	s_addc_u32 s15, s19, 0
	s_add_i32 s18, s44, s27
	v_lshl_add_u64 v[148:149], s[14:15], 0, v[130:131]
	s_mov_b32 m0, s18
	s_nop 0
	global_load_lds_dwordx4 v[148:149], off
	v_lshl_add_u64 v[148:149], s[14:15], 0, v[128:129]
	s_add_i32 m0, s18, 0x2000
	s_nop 0
	global_load_lds_dwordx4 v[148:149], off
	s_waitcnt vmcnt(6)
	s_barrier
	v_mfma_f32_16x16x32_bf16 v[44:47], v[196:199], v[164:167], v[44:47]
	v_mfma_f32_16x16x32_bf16 v[40:43], v[204:207], v[164:167], v[40:43]
	v_mfma_f32_16x16x32_bf16 v[28:31], v[196:199], v[172:175], v[28:31]
	v_mfma_f32_16x16x32_bf16 v[24:27], v[204:207], v[172:175], v[24:27]
	v_mfma_f32_16x16x32_bf16 v[12:15], v[196:199], v[180:183], v[12:15]
	v_mfma_f32_16x16x32_bf16 v[8:11], v[204:207], v[180:183], v[8:11]
	v_mfma_f32_16x16x32_bf16 v[4:7], v[196:199], v[188:191], v[4:7]
	v_mfma_f32_16x16x32_bf16 v[0:3], v[204:207], v[188:191], v[0:3]
	v_mfma_f32_16x16x32_bf16 v[44:47], v[200:203], v[168:171], v[44:47]
	v_mfma_f32_16x16x32_bf16 v[40:43], v[208:211], v[168:171], v[40:43]
	v_mfma_f32_16x16x32_bf16 v[28:31], v[200:203], v[176:179], v[28:31]
	v_mfma_f32_16x16x32_bf16 v[24:27], v[208:211], v[176:179], v[24:27]
	v_mfma_f32_16x16x32_bf16 v[12:15], v[200:203], v[184:187], v[12:15]
	v_mfma_f32_16x16x32_bf16 v[8:11], v[208:211], v[184:187], v[8:11]
	v_mfma_f32_16x16x32_bf16 v[4:7], v[200:203], v[192:195], v[4:7]
	v_mfma_f32_16x16x32_bf16 v[0:3], v[208:211], v[192:195], v[0:3]
	s_add_i32 s53, s53, 2
	s_add_u32 s51, s51, 0x100
	s_addc_u32 s52, s52, 0
	s_cmp_gt_u32 s53, 41
	s_mov_b64 s[14:15], s[16:17]
	s_barrier
	s_cbranch_scc0 .LBB0_213
; #define WAIT_V(n) asm volatile("s_waitcnt vmcnt(" #n ")" ::: "memory")
; #define BAR __builtin_amdgcn_s_barrier()
; __device__ __forceinline__ void gemm_phase(const bf16_t* __restrict__ A, const bf16_t* __restrict__ Bt, bf16_t* __restrict__ C, int M, int N, int K,
;                                            int ldc, const int EPI, char* smem, const int wid_u) {
;     ...
;           if (EPI == 0) {
; #pragma unroll
;             for (int bj = 0; bj < 2; ++bj) {
;               const f32x4 v0 = acc[ai][bj][m][0], v1 = acc[ai][bj][m][1];
;               uint4 u; u.x = cvt_pk_bf16(v0[0], v0[1]); u.y = cvt_pk_bf16(v0[2], v0[3]); u.z = cvt_pk_bf16(v1[0], v1[1]); u.w = cvt_pk_bf16(v1[2], v1[3]);
;               *(uint4*)(C + row * ldc + bcol + bj * HALF + wc * 32 + fq * 8) = u;
;             }
;     ...
;     if (!has_next) break;
; #pragma unroll
;     for (int a = 0; a < 2; ++a)
; #pragma unroll
;       for (int b = 0; b < 2; ++b)
; #pragma unroll
;         for (int m = 0; m < 4; ++m)
; #pragma unroll
;           for (int n = 0; n < 2; ++n) acc[a][b][m][n] = (f32x4){0.f, 0.f, 0.f, 0.f};
;     pm = npm; pn = npn; cA = nA; cB = nB; ++ui;
;   }
;   WAIT_V(0);
;   if (wr == 0) BAR;
;   BAR;
	v_lshl_add_u32 v148, s10, 8, v142
	v_cvt_pk_bf16_f32 v68, v68, v69
	v_cvt_pk_bf16_f32 v69, v70, v71
	v_cvt_pk_bf16_f32 v70, v64, v65
	v_add_u32_e32 v64, 0x80, v148
	s_lshl_b32 s10, s50, 9
	v_ashrrev_i32_e32 v149, 31, v148
	v_cvt_pk_bf16_f32 v108, v108, v109
	v_cvt_pk_bf16_f32 v109, v110, v111
	v_cvt_pk_bf16_f32 v110, v104, v105
	v_or_b32_e32 v104, 16, v148
	v_ashrrev_i32_e32 v65, 31, v64
	v_cvt_pk_bf16_f32 v44, v44, v45
	v_cvt_pk_bf16_f32 v45, v46, v47
	v_cvt_pk_bf16_f32 v46, v40, v41
	v_add_u32_e32 v40, 0x90, v148
	v_lshl_add_u64 v[150:151], v[132:133], 0, s[10:11]
	v_lshlrev_b64 v[152:153], 11, v[148:149]
	v_ashrrev_i32_e32 v105, 31, v104
	v_cvt_pk_bf16_f32 v92, v92, v93
	v_cvt_pk_bf16_f32 v93, v94, v95
	v_cvt_pk_bf16_f32 v94, v88, v89
	v_or_b32_e32 v88, 32, v148
	v_lshlrev_b64 v[64:65], 11, v[64:65]
	v_ashrrev_i32_e32 v41, 31, v40
	v_cvt_pk_bf16_f32 v28, v28, v29
	v_cvt_pk_bf16_f32 v29, v30, v31
	v_cvt_pk_bf16_f32 v30, v24, v25
	v_add_u32_e32 v24, 0xa0, v148
	v_lshl_add_u64 v[152:153], v[150:151], 0, v[152:153]
	v_cvt_pk_bf16_f32 v111, v106, v107
	v_lshlrev_b64 v[104:105], 11, v[104:105]
	v_ashrrev_i32_e32 v89, 31, v88
	v_cvt_pk_bf16_f32 v76, v76, v77
	v_cvt_pk_bf16_f32 v77, v78, v79
	v_cvt_pk_bf16_f32 v78, v72, v73
	v_or_b32_e32 v72, 48, v148
	v_lshl_add_u64 v[64:65], v[150:151], 0, v[64:65]
	v_cvt_pk_bf16_f32 v47, v42, v43
	v_lshlrev_b64 v[40:41], 11, v[40:41]
	v_ashrrev_i32_e32 v25, 31, v24
	v_cvt_pk_bf16_f32 v12, v12, v13
	v_cvt_pk_bf16_f32 v13, v14, v15
	v_cvt_pk_bf16_f32 v14, v8, v9
	v_add_u32_e32 v8, 0xb0, v148
	global_store_dwordx4 v[152:153], v[108:111], off offset:256
	v_cvt_pk_bf16_f32 v95, v90, v91
	v_lshlrev_b64 v[88:89], 11, v[88:89]
	v_lshl_add_u64 v[108:109], v[150:151], 0, v[104:105]
	v_ashrrev_i32_e32 v73, 31, v72
	global_store_dwordx4 v[64:65], v[44:47], off offset:256
	v_cvt_pk_bf16_f32 v31, v26, v27
	v_lshlrev_b64 v[24:25], 11, v[24:25]
	v_lshl_add_u64 v[44:45], v[150:151], 0, v[40:41]
	v_ashrrev_i32_e32 v9, 31, v8
	global_store_dwordx4 v[108:109], v[92:95], off offset:256
	v_cvt_pk_bf16_f32 v79, v74, v75
	v_lshlrev_b64 v[72:73], 11, v[72:73]
	v_lshl_add_u64 v[92:93], v[150:151], 0, v[88:89]
	global_store_dwordx4 v[44:45], v[28:31], off offset:256
	v_cvt_pk_bf16_f32 v15, v10, v11
	v_lshlrev_b64 v[8:9], 11, v[8:9]
	v_lshl_add_u64 v[28:29], v[150:151], 0, v[24:25]
	v_cvt_pk_bf16_f32 v124, v124, v125
	v_cvt_pk_bf16_f32 v125, v126, v127
	v_cvt_pk_bf16_f32 v126, v120, v121
	v_cvt_pk_bf16_f32 v127, v122, v123
	v_cvt_pk_bf16_f32 v104, v116, v117
	v_cvt_pk_bf16_f32 v105, v118, v119
	v_cvt_pk_bf16_f32 v106, v112, v113
	v_cvt_pk_bf16_f32 v107, v114, v115
	v_cvt_pk_bf16_f32 v88, v100, v101
	v_cvt_pk_bf16_f32 v89, v102, v103
	v_cvt_pk_bf16_f32 v90, v96, v97
	v_cvt_pk_bf16_f32 v91, v98, v99
	global_store_dwordx4 v[92:93], v[76:79], off offset:256
	v_cvt_pk_bf16_f32 v74, v80, v81
	v_cvt_pk_bf16_f32 v75, v82, v83
	v_lshl_add_u64 v[76:77], v[150:151], 0, v[72:73]
	v_cvt_pk_bf16_f32 v72, v84, v85
	v_cvt_pk_bf16_f32 v73, v86, v87
	v_cvt_pk_bf16_f32 v71, v66, v67
	v_cvt_pk_bf16_f32 v60, v60, v61
	v_cvt_pk_bf16_f32 v61, v62, v63
	v_cvt_pk_bf16_f32 v62, v56, v57
	v_cvt_pk_bf16_f32 v63, v58, v59
	v_cvt_pk_bf16_f32 v40, v52, v53
	v_cvt_pk_bf16_f32 v41, v54, v55
	v_cvt_pk_bf16_f32 v42, v48, v49
	v_cvt_pk_bf16_f32 v43, v50, v51
	v_cvt_pk_bf16_f32 v24, v36, v37
	v_cvt_pk_bf16_f32 v25, v38, v39
	v_cvt_pk_bf16_f32 v26, v32, v33
	v_cvt_pk_bf16_f32 v27, v34, v35
	global_store_dwordx4 v[28:29], v[12:15], off offset:256
	v_cvt_pk_bf16_f32 v10, v16, v17
	v_cvt_pk_bf16_f32 v11, v18, v19
	v_lshl_add_u64 v[12:13], v[150:151], 0, v[8:9]
	v_cvt_pk_bf16_f32 v8, v20, v21
	v_cvt_pk_bf16_f32 v9, v22, v23
	v_cvt_pk_bf16_f32 v4, v4, v5
	v_cvt_pk_bf16_f32 v5, v6, v7
	v_cvt_pk_bf16_f32 v6, v0, v1
	v_cvt_pk_bf16_f32 v7, v2, v3
	s_and_b64 vcc, exec, s[2:3]
	s_mov_b32 s10, s48
	s_mov_b32 s50, s49
	s_mov_b64 s[16:17], s[6:7]
	s_mov_b64 s[14:15], s[4:5]
	global_store_dwordx4 v[152:153], v[124:127], off
	global_store_dwordx4 v[108:109], v[104:107], off
	global_store_dwordx4 v[92:93], v[88:91], off
	global_store_dwordx4 v[76:77], v[72:75], off
	global_store_dwordx4 v[76:77], v[68:71], off offset:256
	global_store_dwordx4 v[64:65], v[60:63], off
	global_store_dwordx4 v[44:45], v[40:43], off
	global_store_dwordx4 v[28:29], v[24:27], off
	global_store_dwordx4 v[12:13], v[8:11], off
	global_store_dwordx4 v[12:13], v[4:7], off offset:256
	s_cbranch_vccz .LBB0_206
	s_waitcnt vmcnt(0)
	s_cmpk_gt_u32 s22, 0xff
	s_cbranch_scc1 .LBB0_217
	s_barrier

; #define STG(P, GB) do { const char* _gb = (GB); \
;     _Pragma("unroll") for (int _i = 0; _i < 2; ++_i) { \
;       __builtin_amdgcn_global_load_lds((const unsigned*)(_gb + voff[_i]), \
;         (LAS unsigned*)((LAS char*)(P) + ldsw + _i * 8192), 16, 0, 0); } } while (0)
; #define LDA(dst, b, h) _Pragma("unroll") for (int m = 0; m < 4; ++m) _Pragma("unroll") for (int k = 0; k < 2; ++k) \
;     dst[m][k] = *(const LAS bf16x8*)((LAS char*)SA(b, h) + aoff + m * 2048 + k * 1024)
; #define LDB(dst, b, h) _Pragma("unroll") for (int n = 0; n < 2; ++n) _Pragma("unroll") for (int k = 0; k < 2; ++k) \
;     dst[n][k] = *(const LAS bf16x8*)((LAS char*)SB(b, h) + boff + n * 2048 + k * 1024)
; #define MMA(ai, bj, At_, Bt_) do { __builtin_amdgcn_s_setprio(1); \
;     _Pragma("unroll") for (int m = 0; m < 4; ++m) _Pragma("unroll") for (int n = 0; n < 2; ++n) _Pragma("unroll") for (int k = 0; k < 2; ++k) \
;       acc[ai][bj][m][n] = __builtin_amdgcn_mfma_f32_16x16x32_bf16(Bt_[n][k], At_[m][k], acc[ai][bj][m][n], 0, 0, 0); \
;     __builtin_amdgcn_s_setprio(0); } while (0)
; #define WAIT_V(n) asm volatile("s_waitcnt vmcnt(" #n ")" ::: "memory")
; #define WAIT_L(n) asm volatile("s_waitcnt lgkmcnt(" #n ")" ::: "memory")
; #define BAR __builtin_amdgcn_s_barrier()
; #define SCHED __builtin_amdgcn_sched_barrier(0)
; __device__ __forceinline__ void gemm_phase(const bf16_t* __restrict__ A, const bf16_t* __restrict__ Bt, bf16_t* __restrict__ C, int M, int N, int K,
;                                            int ldc, const int EPI, char* smem, const int wid_u) {
;     ...
;       LDB(B0, 0, 0); SCHED; LDA(At, 0, 0); STG(SA(1, 1), a1 + hstep);
;       WAIT_L(8); BAR; WAIT_L(0); MMA(0, 0, At, B0); BAR; SCHED;
;       LDB(B1, 0, 1); STG(SB(0, 0), b2);
;       BAR; WAIT_L(0); MMA(0, 1, At, B1); BAR;
;       LDA(At, 0, 1); STG(SA(0, 0), a2);
;       BAR; WAIT_L(0); MMA(1, 0, At, B0); BAR; SCHED;
;       STG(SB(0, 1), b2 + hstep);
;       WAIT_V(6); BAR; MMA(1, 1, At, B1); BAR;
.LBB0_334:
	ds_read_b128 v[148:151], v144
	ds_read_b128 v[152:155], v144 offset:1024
	ds_read_b128 v[156:159], v144 offset:2048
	ds_read_b128 v[160:163], v144 offset:3072
	s_add_u32 s18, s16, 0x100
	s_addc_u32 s19, s17, 0
	s_cmp_eq_u32 s51, 12
	s_cselect_b32 s23, s46, s19
	s_cselect_b32 s22, s47, s18
	s_cselect_b32 s21, s11, s50
	s_cselect_b32 s20, s48, s49
	v_lshl_add_u64 v[196:197], s[16:17], 0, v[136:137]
	s_add_i32 m0, s30, 0xc000
	ds_read_b128 v[164:167], v145
	ds_read_b128 v[168:171], v145 offset:1024
	ds_read_b128 v[172:175], v145 offset:2048
	ds_read_b128 v[176:179], v145 offset:3072
	ds_read_b128 v[180:183], v145 offset:4096
	ds_read_b128 v[184:187], v145 offset:5120
	ds_read_b128 v[188:191], v145 offset:6144
	ds_read_b128 v[192:195], v145 offset:7168
	global_load_lds_dwordx4 v[196:197], off
	v_lshl_add_u64 v[196:197], s[16:17], 0, v[134:135]
	s_add_i32 m0, s30, 0xe000
	s_nop 0
	global_load_lds_dwordx4 v[196:197], off
	s_waitcnt lgkmcnt(8)
	s_barrier
	s_waitcnt lgkmcnt(0)
	s_waitcnt lgkmcnt(0)
	v_mfma_f32_16x16x32_bf16 v[124:127], v[148:151], v[164:167], v[124:127]
	v_mfma_f32_16x16x32_bf16 v[120:123], v[156:159], v[164:167], v[120:123]
	v_mfma_f32_16x16x32_bf16 v[116:119], v[148:151], v[172:175], v[116:119]
	v_mfma_f32_16x16x32_bf16 v[112:115], v[156:159], v[172:175], v[112:115]
	v_mfma_f32_16x16x32_bf16 v[100:103], v[148:151], v[180:183], v[100:103]
	v_mfma_f32_16x16x32_bf16 v[96:99], v[156:159], v[180:183], v[96:99]
	v_mfma_f32_16x16x32_bf16 v[84:87], v[148:151], v[188:191], v[84:87]
	v_mfma_f32_16x16x32_bf16 v[80:83], v[156:159], v[188:191], v[80:83]
	v_mfma_f32_16x16x32_bf16 v[124:127], v[152:155], v[168:171], v[124:127]
	v_mfma_f32_16x16x32_bf16 v[120:123], v[160:163], v[168:171], v[120:123]
	v_mfma_f32_16x16x32_bf16 v[116:119], v[152:155], v[176:179], v[116:119]
	v_mfma_f32_16x16x32_bf16 v[112:115], v[160:163], v[176:179], v[112:115]
	v_mfma_f32_16x16x32_bf16 v[100:103], v[152:155], v[184:187], v[100:103]
	v_mfma_f32_16x16x32_bf16 v[96:99], v[160:163], v[184:187], v[96:99]
	v_mfma_f32_16x16x32_bf16 v[84:87], v[152:155], v[192:195], v[84:87]
	v_mfma_f32_16x16x32_bf16 v[80:83], v[160:163], v[192:195], v[80:83]
	s_barrier
	s_add_i32 s16, s38, s29
	v_lshl_add_u64 v[212:213], s[20:21], 0, v[130:131]
	s_mov_b32 m0, s16
	ds_read_b128 v[196:199], v146
	ds_read_b128 v[200:203], v146 offset:1024
	ds_read_b128 v[204:207], v146 offset:2048
	ds_read_b128 v[208:211], v146 offset:3072
	global_load_lds_dwordx4 v[212:213], off
	v_lshl_add_u64 v[214:215], s[20:21], 0, v[128:129]
	s_add_i32 m0, s16, 0x2000
	s_nop 0
	global_load_lds_dwordx4 v[214:215], off
	s_barrier
	s_waitcnt lgkmcnt(0)
	s_waitcnt lgkmcnt(0)
	v_mfma_f32_16x16x32_bf16 v[108:111], v[196:199], v[164:167], v[108:111]
	v_mfma_f32_16x16x32_bf16 v[104:107], v[204:207], v[164:167], v[104:107]
	v_mfma_f32_16x16x32_bf16 v[92:95], v[196:199], v[172:175], v[92:95]
	v_mfma_f32_16x16x32_bf16 v[88:91], v[204:207], v[172:175], v[88:91]
	v_mfma_f32_16x16x32_bf16 v[76:79], v[196:199], v[180:183], v[76:79]
	v_mfma_f32_16x16x32_bf16 v[72:75], v[204:207], v[180:183], v[72:75]
	v_mfma_f32_16x16x32_bf16 v[68:71], v[196:199], v[188:191], v[68:71]
	v_mfma_f32_16x16x32_bf16 v[64:67], v[204:207], v[188:191], v[64:67]
	v_mfma_f32_16x16x32_bf16 v[108:111], v[200:203], v[168:171], v[108:111]
	v_mfma_f32_16x16x32_bf16 v[104:107], v[208:211], v[168:171], v[104:107]
	v_mfma_f32_16x16x32_bf16 v[92:95], v[200:203], v[176:179], v[92:95]
	v_mfma_f32_16x16x32_bf16 v[88:91], v[208:211], v[176:179], v[88:91]
	v_mfma_f32_16x16x32_bf16 v[76:79], v[200:203], v[184:187], v[76:79]
	v_mfma_f32_16x16x32_bf16 v[72:75], v[208:211], v[184:187], v[72:75]
	v_mfma_f32_16x16x32_bf16 v[68:71], v[200:203], v[192:195], v[68:71]
	v_mfma_f32_16x16x32_bf16 v[64:67], v[208:211], v[192:195], v[64:67]
	s_mov_b32 m0, s30
	v_lshl_add_u64 v[216:217], s[22:23], 0, v[130:131]
	s_barrier
	ds_read_b128 v[164:167], v145 offset:16384
	ds_read_b128 v[168:171], v145 offset:17408
	ds_read_b128 v[172:175], v145 offset:18432
	ds_read_b128 v[176:179], v145 offset:19456
	ds_read_b128 v[180:183], v145 offset:20480
	ds_read_b128 v[184:187], v145 offset:21504
	ds_read_b128 v[188:191], v145 offset:22528
	ds_read_b128 v[192:195], v145 offset:23552
	global_load_lds_dwordx4 v[216:217], off
	v_lshl_add_u64 v[218:219], s[22:23], 0, v[128:129]
	s_mov_b32 m0, s31
	s_nop 0
	global_load_lds_dwordx4 v[218:219], off
	s_barrier
	s_waitcnt lgkmcnt(0)
	s_waitcnt lgkmcnt(0)
	v_mfma_f32_16x16x32_bf16 v[60:63], v[148:151], v[164:167], v[60:63]
	v_mfma_f32_16x16x32_bf16 v[56:59], v[156:159], v[164:167], v[56:59]
	v_mfma_f32_16x16x32_bf16 v[52:55], v[148:151], v[172:175], v[52:55]
	v_mfma_f32_16x16x32_bf16 v[48:51], v[156:159], v[172:175], v[48:51]
	v_mfma_f32_16x16x32_bf16 v[36:39], v[148:151], v[180:183], v[36:39]
	v_mfma_f32_16x16x32_bf16 v[32:35], v[156:159], v[180:183], v[32:35]
	v_mfma_f32_16x16x32_bf16 v[20:23], v[148:151], v[188:191], v[20:23]
	v_mfma_f32_16x16x32_bf16 v[16:19], v[156:159], v[188:191], v[16:19]
	v_mfma_f32_16x16x32_bf16 v[60:63], v[152:155], v[168:171], v[60:63]
	v_mfma_f32_16x16x32_bf16 v[56:59], v[160:163], v[168:171], v[56:59]
	v_mfma_f32_16x16x32_bf16 v[52:55], v[152:155], v[176:179], v[52:55]
	v_mfma_f32_16x16x32_bf16 v[48:51], v[160:163], v[176:179], v[48:51]
	v_mfma_f32_16x16x32_bf16 v[36:39], v[152:155], v[184:187], v[36:39]
	v_mfma_f32_16x16x32_bf16 v[32:35], v[160:163], v[184:187], v[32:35]
	v_mfma_f32_16x16x32_bf16 v[20:23], v[152:155], v[192:195], v[20:23]
	v_mfma_f32_16x16x32_bf16 v[16:19], v[160:163], v[192:195], v[16:19]
	s_barrier
; #define STG(P, GB) do { const char* _gb = (GB); \
;     _Pragma("unroll") for (int _i = 0; _i < 2; ++_i) { \
;       __builtin_amdgcn_global_load_lds((const unsigned*)(_gb + voff[_i]), \
;         (LAS unsigned*)((LAS char*)(P) + ldsw + _i * 8192), 16, 0, 0); } } while (0)
; #define LDA(dst, b, h) _Pragma("unroll") for (int m = 0; m < 4; ++m) _Pragma("unroll") for (int k = 0; k < 2; ++k) \
;     dst[m][k] = *(const LAS bf16x8*)((LAS char*)SA(b, h) + aoff + m * 2048 + k * 1024)
; #define LDB(dst, b, h) _Pragma("unroll") for (int n = 0; n < 2; ++n) _Pragma("unroll") for (int k = 0; k < 2; ++k) \
;     dst[n][k] = *(const LAS bf16x8*)((LAS char*)SB(b, h) + boff + n * 2048 + k * 1024)
; #define MMA(ai, bj, At_, Bt_) do { __builtin_amdgcn_s_setprio(1); \
;     _Pragma("unroll") for (int m = 0; m < 4; ++m) _Pragma("unroll") for (int n = 0; n < 2; ++n) _Pragma("unroll") for (int k = 0; k < 2; ++k) \
;       acc[ai][bj][m][n] = __builtin_amdgcn_mfma_f32_16x16x32_bf16(Bt_[n][k], At_[m][k], acc[ai][bj][m][n], 0, 0, 0); \
;     __builtin_amdgcn_s_setprio(0); } while (0)
; #define WAIT_V(n) asm volatile("s_waitcnt vmcnt(" #n ")" ::: "memory")
; #define WAIT_L(n) asm volatile("s_waitcnt lgkmcnt(" #n ")" ::: "memory")
; #define BAR __builtin_amdgcn_s_barrier()
; #define SCHED __builtin_amdgcn_sched_barrier(0)
; __device__ __forceinline__ void gemm_phase(const bf16_t* __restrict__ A, const bf16_t* __restrict__ Bt, bf16_t* __restrict__ C, int M, int N, int K,
;                                            int ldc, const int EPI, char* smem, const int wid_u) {
;     ...
;       WAIT_V(6); BAR; MMA(1, 1, At, B1); BAR;
;       LDB(B0, 1, 0); SCHED; LDA(At, 1, 0); STG(SA(0, 1), a2 + hstep);
;       WAIT_L(8); BAR; WAIT_L(0); MMA(0, 0, At, B0); BAR; SCHED;
;       LDB(B1, 1, 1); STG(SB(1, 0), b3);
;       BAR; WAIT_L(0); MMA(0, 1, At, B1); BAR;
;       LDA(At, 1, 1); STG(SA(1, 0), a3);
;       BAR; WAIT_L(0); MMA(1, 0, At, B0); BAR; SCHED;
	s_add_u32 s16, s20, 0x40000
	s_addc_u32 s17, s21, 0
	s_add_i32 s52, s39, s29
	v_lshl_add_u64 v[148:149], s[16:17], 0, v[130:131]
	s_mov_b32 m0, s52
	s_nop 0
	global_load_lds_dwordx4 v[148:149], off
	v_lshl_add_u64 v[148:149], s[16:17], 0, v[128:129]
	s_add_i32 m0, s52, 0x2000
	s_nop 0
	global_load_lds_dwordx4 v[148:149], off
	s_waitcnt vmcnt(6)
	s_barrier
	v_mfma_f32_16x16x32_bf16 v[44:47], v[196:199], v[164:167], v[44:47]
	v_mfma_f32_16x16x32_bf16 v[40:43], v[204:207], v[164:167], v[40:43]
	v_mfma_f32_16x16x32_bf16 v[28:31], v[196:199], v[172:175], v[28:31]
	v_mfma_f32_16x16x32_bf16 v[24:27], v[204:207], v[172:175], v[24:27]
	v_mfma_f32_16x16x32_bf16 v[12:15], v[196:199], v[180:183], v[12:15]
	v_mfma_f32_16x16x32_bf16 v[8:11], v[204:207], v[180:183], v[8:11]
	v_mfma_f32_16x16x32_bf16 v[4:7], v[196:199], v[188:191], v[4:7]
	v_mfma_f32_16x16x32_bf16 v[0:3], v[204:207], v[188:191], v[0:3]
	v_mfma_f32_16x16x32_bf16 v[44:47], v[200:203], v[168:171], v[44:47]
	v_mfma_f32_16x16x32_bf16 v[40:43], v[208:211], v[168:171], v[40:43]
	v_mfma_f32_16x16x32_bf16 v[28:31], v[200:203], v[176:179], v[28:31]
	v_mfma_f32_16x16x32_bf16 v[24:27], v[208:211], v[176:179], v[24:27]
	v_mfma_f32_16x16x32_bf16 v[12:15], v[200:203], v[184:187], v[12:15]
	v_mfma_f32_16x16x32_bf16 v[8:11], v[208:211], v[184:187], v[8:11]
	v_mfma_f32_16x16x32_bf16 v[4:7], v[200:203], v[192:195], v[4:7]
	v_mfma_f32_16x16x32_bf16 v[0:3], v[208:211], v[192:195], v[0:3]
	s_add_i32 s52, 0, 0x18000
	v_add_u32_e32 v147, s52, v143
	s_barrier
	ds_read_b128 v[148:151], v147
	ds_read_b128 v[152:155], v147 offset:1024
	ds_read_b128 v[156:159], v147 offset:2048
	ds_read_b128 v[160:163], v147 offset:3072
	s_add_u32 s16, s22, 0x40000
	s_addc_u32 s17, s23, 0
	s_mov_b32 m0, s34
	v_lshl_add_u64 v[196:197], s[16:17], 0, v[130:131]
	ds_read_b128 v[164:167], v145 offset:32768
	ds_read_b128 v[168:171], v145 offset:33792
	ds_read_b128 v[172:175], v145 offset:34816
	ds_read_b128 v[176:179], v145 offset:35840
	ds_read_b128 v[180:183], v145 offset:36864
	ds_read_b128 v[184:187], v145 offset:37888
	ds_read_b128 v[188:191], v145 offset:38912
	ds_read_b128 v[192:195], v145 offset:39936
	global_load_lds_dwordx4 v[196:197], off
	v_lshl_add_u64 v[196:197], s[16:17], 0, v[128:129]
	s_mov_b32 m0, s35
	s_nop 0
	global_load_lds_dwordx4 v[196:197], off
	s_waitcnt lgkmcnt(8)
	s_barrier
	s_waitcnt lgkmcnt(0)
	s_waitcnt lgkmcnt(0)
	v_mfma_f32_16x16x32_bf16 v[124:127], v[148:151], v[164:167], v[124:127]
	v_mfma_f32_16x16x32_bf16 v[120:123], v[156:159], v[164:167], v[120:123]
	v_mfma_f32_16x16x32_bf16 v[116:119], v[148:151], v[172:175], v[116:119]
	v_mfma_f32_16x16x32_bf16 v[112:115], v[156:159], v[172:175], v[112:115]
	v_mfma_f32_16x16x32_bf16 v[100:103], v[148:151], v[180:183], v[100:103]
	v_mfma_f32_16x16x32_bf16 v[96:99], v[156:159], v[180:183], v[96:99]
	v_mfma_f32_16x16x32_bf16 v[84:87], v[148:151], v[188:191], v[84:87]
	v_mfma_f32_16x16x32_bf16 v[80:83], v[156:159], v[188:191], v[80:83]
	v_mfma_f32_16x16x32_bf16 v[124:127], v[152:155], v[168:171], v[124:127]
	v_mfma_f32_16x16x32_bf16 v[120:123], v[160:163], v[168:171], v[120:123]
	v_mfma_f32_16x16x32_bf16 v[116:119], v[152:155], v[176:179], v[116:119]
	v_mfma_f32_16x16x32_bf16 v[112:115], v[160:163], v[176:179], v[112:115]
	v_mfma_f32_16x16x32_bf16 v[100:103], v[152:155], v[184:187], v[100:103]
	v_mfma_f32_16x16x32_bf16 v[96:99], v[160:163], v[184:187], v[96:99]
	v_mfma_f32_16x16x32_bf16 v[84:87], v[152:155], v[192:195], v[84:87]
	v_mfma_f32_16x16x32_bf16 v[80:83], v[160:163], v[192:195], v[80:83]
	s_barrier
	s_add_i32 s22, 0, 0x1c000
	s_add_i32 s16, s52, s29
	v_add_u32_e32 v147, s22, v143
	v_lshl_add_u64 v[212:213], v[212:213], 0, s[8:9]
	s_mov_b32 m0, s16
	ds_read_b128 v[196:199], v147
	ds_read_b128 v[200:203], v147 offset:1024
	ds_read_b128 v[204:207], v147 offset:2048
	ds_read_b128 v[208:211], v147 offset:3072
	global_load_lds_dwordx4 v[212:213], off
	v_lshl_add_u64 v[212:213], v[214:215], 0, s[8:9]
	s_add_i32 m0, s16, 0x2000
	s_nop 0
	global_load_lds_dwordx4 v[212:213], off
	s_barrier
	s_waitcnt lgkmcnt(0)
	s_waitcnt lgkmcnt(0)
	v_mfma_f32_16x16x32_bf16 v[108:111], v[196:199], v[164:167], v[108:111]
	v_mfma_f32_16x16x32_bf16 v[104:107], v[204:207], v[164:167], v[104:107]
	v_mfma_f32_16x16x32_bf16 v[92:95], v[196:199], v[172:175], v[92:95]
	v_mfma_f32_16x16x32_bf16 v[88:91], v[204:207], v[172:175], v[88:91]
	v_mfma_f32_16x16x32_bf16 v[76:79], v[196:199], v[180:183], v[76:79]
	v_mfma_f32_16x16x32_bf16 v[72:75], v[204:207], v[180:183], v[72:75]
	v_mfma_f32_16x16x32_bf16 v[68:71], v[196:199], v[188:191], v[68:71]
	v_mfma_f32_16x16x32_bf16 v[64:67], v[204:207], v[188:191], v[64:67]
	v_mfma_f32_16x16x32_bf16 v[108:111], v[200:203], v[168:171], v[108:111]
	v_mfma_f32_16x16x32_bf16 v[104:107], v[208:211], v[168:171], v[104:107]
	v_mfma_f32_16x16x32_bf16 v[92:95], v[200:203], v[176:179], v[92:95]
	v_mfma_f32_16x16x32_bf16 v[88:91], v[208:211], v[176:179], v[88:91]
	v_mfma_f32_16x16x32_bf16 v[76:79], v[200:203], v[184:187], v[76:79]
	v_mfma_f32_16x16x32_bf16 v[72:75], v[208:211], v[184:187], v[72:75]
	v_mfma_f32_16x16x32_bf16 v[68:71], v[200:203], v[192:195], v[68:71]
	v_mfma_f32_16x16x32_bf16 v[64:67], v[208:211], v[192:195], v[64:67]
	s_mov_b32 m0, s36
	v_lshl_add_u64 v[212:213], v[216:217], 0, s[8:9]
	s_barrier
	ds_read_b128 v[164:167], v145 offset:49152
	ds_read_b128 v[168:171], v145 offset:50176
	ds_read_b128 v[172:175], v145 offset:51200
	ds_read_b128 v[176:179], v145 offset:52224
	ds_read_b128 v[180:183], v145 offset:53248
	ds_read_b128 v[184:187], v145 offset:54272
	ds_read_b128 v[188:191], v145 offset:55296
	ds_read_b128 v[192:195], v145 offset:56320
	global_load_lds_dwordx4 v[212:213], off
	v_lshl_add_u64 v[212:213], v[218:219], 0, s[8:9]
	s_mov_b32 m0, s37
	s_nop 0
	global_load_lds_dwordx4 v[212:213], off
	s_barrier
; #define STG(P, GB) do { const char* _gb = (GB); \
;     _Pragma("unroll") for (int _i = 0; _i < 2; ++_i) { \
;       __builtin_amdgcn_global_load_lds((const unsigned*)(_gb + voff[_i]), \
;         (LAS unsigned*)((LAS char*)(P) + ldsw + _i * 8192), 16, 0, 0); } } while (0)
; #define MMA(ai, bj, At_, Bt_) do { __builtin_amdgcn_s_setprio(1); \
;     _Pragma("unroll") for (int m = 0; m < 4; ++m) _Pragma("unroll") for (int n = 0; n < 2; ++n) _Pragma("unroll") for (int k = 0; k < 2; ++k) \
;       acc[ai][bj][m][n] = __builtin_amdgcn_mfma_f32_16x16x32_bf16(Bt_[n][k], At_[m][k], acc[ai][bj][m][n], 0, 0, 0); \
;     __builtin_amdgcn_s_setprio(0); } while (0)
; #define WAIT_V(n) asm volatile("s_waitcnt vmcnt(" #n ")" ::: "memory")
; #define WAIT_L(n) asm volatile("s_waitcnt lgkmcnt(" #n ")" ::: "memory")
; #define BAR __builtin_amdgcn_s_barrier()
; #define SCHED __builtin_amdgcn_sched_barrier(0)
; __device__ __forceinline__ void gemm_phase(const bf16_t* __restrict__ A, const bf16_t* __restrict__ Bt, bf16_t* __restrict__ C, int M, int N, int K,
;                                            int ldc, const int EPI, char* smem, const int wid_u) {
;     ...
;       BAR; WAIT_L(0); MMA(1, 0, At, B0); BAR; SCHED;
;       STG(SB(1, 1), b3 + hstep);
;       WAIT_V(6); BAR; MMA(1, 1, At, B1); BAR;
;     ...
;           if (EPI == 0) {
; #pragma unroll
;             for (int bj = 0; bj < 2; ++bj) {
;               const f32x4 v0 = acc[ai][bj][m][0], v1 = acc[ai][bj][m][1];
;               uint4 u; u.x = cvt_pk_bf16(v0[0], v0[1]); u.y = cvt_pk_bf16(v0[2], v0[3]); u.z = cvt_pk_bf16(v1[0], v1[1]); u.w = cvt_pk_bf16(v1[2], v1[3]);
;               *(uint4*)(C + row * ldc + bcol + bj * HALF + wc * 32 + fq * 8) = u;
;             }
	s_waitcnt lgkmcnt(0)
	s_waitcnt lgkmcnt(0)
	v_mfma_f32_16x16x32_bf16 v[60:63], v[148:151], v[164:167], v[60:63]
	v_mfma_f32_16x16x32_bf16 v[56:59], v[156:159], v[164:167], v[56:59]
	v_mfma_f32_16x16x32_bf16 v[52:55], v[148:151], v[172:175], v[52:55]
	v_mfma_f32_16x16x32_bf16 v[48:51], v[156:159], v[172:175], v[48:51]
	v_mfma_f32_16x16x32_bf16 v[36:39], v[148:151], v[180:183], v[36:39]
	v_mfma_f32_16x16x32_bf16 v[32:35], v[156:159], v[180:183], v[32:35]
	v_mfma_f32_16x16x32_bf16 v[20:23], v[148:151], v[188:191], v[20:23]
	v_mfma_f32_16x16x32_bf16 v[16:19], v[156:159], v[188:191], v[16:19]
	v_mfma_f32_16x16x32_bf16 v[60:63], v[152:155], v[168:171], v[60:63]
	v_mfma_f32_16x16x32_bf16 v[56:59], v[160:163], v[168:171], v[56:59]
	v_mfma_f32_16x16x32_bf16 v[52:55], v[152:155], v[176:179], v[52:55]
	v_mfma_f32_16x16x32_bf16 v[48:51], v[160:163], v[176:179], v[48:51]
	v_mfma_f32_16x16x32_bf16 v[36:39], v[152:155], v[184:187], v[36:39]
	v_mfma_f32_16x16x32_bf16 v[32:35], v[160:163], v[184:187], v[32:35]
	v_mfma_f32_16x16x32_bf16 v[20:23], v[152:155], v[192:195], v[20:23]
	v_mfma_f32_16x16x32_bf16 v[16:19], v[160:163], v[192:195], v[16:19]
	s_barrier
	s_add_u32 s16, s20, 0x40080
	s_addc_u32 s17, s21, 0
	s_add_i32 s20, s22, s29
	v_lshl_add_u64 v[148:149], s[16:17], 0, v[130:131]
	s_mov_b32 m0, s20
	s_nop 0
	global_load_lds_dwordx4 v[148:149], off
	v_lshl_add_u64 v[148:149], s[16:17], 0, v[128:129]
	s_add_i32 m0, s20, 0x2000
	s_nop 0
	global_load_lds_dwordx4 v[148:149], off
	s_waitcnt vmcnt(6)
	s_barrier
	v_mfma_f32_16x16x32_bf16 v[44:47], v[196:199], v[164:167], v[44:47]
	v_mfma_f32_16x16x32_bf16 v[40:43], v[204:207], v[164:167], v[40:43]
	v_mfma_f32_16x16x32_bf16 v[28:31], v[196:199], v[172:175], v[28:31]
	v_mfma_f32_16x16x32_bf16 v[24:27], v[204:207], v[172:175], v[24:27]
	v_mfma_f32_16x16x32_bf16 v[12:15], v[196:199], v[180:183], v[12:15]
	v_mfma_f32_16x16x32_bf16 v[8:11], v[204:207], v[180:183], v[8:11]
	v_mfma_f32_16x16x32_bf16 v[4:7], v[196:199], v[188:191], v[4:7]
	v_mfma_f32_16x16x32_bf16 v[0:3], v[204:207], v[188:191], v[0:3]
	v_mfma_f32_16x16x32_bf16 v[44:47], v[200:203], v[168:171], v[44:47]
	v_mfma_f32_16x16x32_bf16 v[40:43], v[208:211], v[168:171], v[40:43]
	v_mfma_f32_16x16x32_bf16 v[28:31], v[200:203], v[176:179], v[28:31]
	v_mfma_f32_16x16x32_bf16 v[24:27], v[208:211], v[176:179], v[24:27]
	v_mfma_f32_16x16x32_bf16 v[12:15], v[200:203], v[184:187], v[12:15]
	v_mfma_f32_16x16x32_bf16 v[8:11], v[208:211], v[184:187], v[8:11]
	v_mfma_f32_16x16x32_bf16 v[4:7], v[200:203], v[192:195], v[4:7]
	v_mfma_f32_16x16x32_bf16 v[0:3], v[208:211], v[192:195], v[0:3]
	s_add_i32 s51, s51, 2
	s_add_u32 s49, s49, 0x100
	s_addc_u32 s50, s50, 0
	s_cmp_gt_u32 s51, 13
	s_mov_b64 s[16:17], s[18:19]
	s_barrier
	s_cbranch_scc0 .LBB0_334
	v_lshl_add_u32 v147, s44, 8, v142
	s_lshl_b32 s16, s45, 9
	s_mov_b32 s17, s7
	v_lshl_add_u64 v[148:149], v[132:133], 0, s[16:17]
	v_cvt_pk_bf16_f32 v68, v68, v69
	v_cvt_pk_bf16_f32 v69, v70, v71
	v_cvt_pk_bf16_f32 v70, v64, v65
	v_add_u32_e32 v64, 0x80, v147
	v_mad_i64_i32 v[150:151], s[16:17], v147, s40, v[148:149]
	v_cvt_pk_bf16_f32 v108, v108, v109
	v_cvt_pk_bf16_f32 v109, v110, v111
	v_cvt_pk_bf16_f32 v110, v104, v105
	v_cvt_pk_bf16_f32 v111, v106, v107
	v_or_b32_e32 v104, 16, v147
	v_mad_i64_i32 v[64:65], s[16:17], v64, s40, v[148:149]
	v_cvt_pk_bf16_f32 v44, v44, v45
	v_cvt_pk_bf16_f32 v45, v46, v47
	v_cvt_pk_bf16_f32 v46, v40, v41
	v_cvt_pk_bf16_f32 v47, v42, v43
	v_add_u32_e32 v40, 0x90, v147
	global_store_dwordx4 v[150:151], v[108:111], off offset:256
	v_cvt_pk_bf16_f32 v92, v92, v93
	v_cvt_pk_bf16_f32 v93, v94, v95
	v_mad_i64_i32 v[108:109], s[16:17], v104, s40, v[148:149]
	v_cvt_pk_bf16_f32 v94, v88, v89
	v_cvt_pk_bf16_f32 v95, v90, v91
	v_or_b32_e32 v88, 32, v147
	global_store_dwordx4 v[64:65], v[44:47], off offset:256
	v_cvt_pk_bf16_f32 v28, v28, v29
	v_cvt_pk_bf16_f32 v29, v30, v31
	v_mad_i64_i32 v[44:45], s[16:17], v40, s40, v[148:149]
	v_cvt_pk_bf16_f32 v30, v24, v25
	v_cvt_pk_bf16_f32 v31, v26, v27
	v_add_u32_e32 v24, 0xa0, v147
	global_store_dwordx4 v[108:109], v[92:95], off offset:256
	v_cvt_pk_bf16_f32 v76, v76, v77
	v_cvt_pk_bf16_f32 v77, v78, v79
	v_mad_i64_i32 v[92:93], s[16:17], v88, s40, v[148:149]
	v_cvt_pk_bf16_f32 v78, v72, v73
	v_cvt_pk_bf16_f32 v79, v74, v75
	v_or_b32_e32 v72, 48, v147
	global_store_dwordx4 v[44:45], v[28:31], off offset:256
	v_cvt_pk_bf16_f32 v12, v12, v13
	v_cvt_pk_bf16_f32 v13, v14, v15
	v_mad_i64_i32 v[28:29], s[16:17], v24, s40, v[148:149]
	v_cvt_pk_bf16_f32 v14, v8, v9
	v_cvt_pk_bf16_f32 v15, v10, v11
	v_add_u32_e32 v8, 0xb0, v147
	global_store_dwordx4 v[92:93], v[76:79], off offset:256
	global_store_dwordx4 v[28:29], v[12:15], off offset:256
	v_cvt_pk_bf16_f32 v124, v124, v125
	v_mad_i64_i32 v[76:77], s[16:17], v72, s40, v[148:149]
	v_mad_i64_i32 v[12:13], s[16:17], v8, s40, v[148:149]
	v_cvt_pk_bf16_f32 v125, v126, v127
	v_cvt_pk_bf16_f32 v126, v120, v121
	v_cvt_pk_bf16_f32 v127, v122, v123
	v_cvt_pk_bf16_f32 v104, v116, v117
	v_cvt_pk_bf16_f32 v105, v118, v119
	v_cvt_pk_bf16_f32 v106, v112, v113
	v_cvt_pk_bf16_f32 v107, v114, v115
	v_cvt_pk_bf16_f32 v88, v100, v101
	v_cvt_pk_bf16_f32 v89, v102, v103
	v_cvt_pk_bf16_f32 v90, v96, v97
	v_cvt_pk_bf16_f32 v91, v98, v99
	v_cvt_pk_bf16_f32 v72, v84, v85
	v_cvt_pk_bf16_f32 v73, v86, v87
	v_cvt_pk_bf16_f32 v74, v80, v81
	v_cvt_pk_bf16_f32 v75, v82, v83
	v_cvt_pk_bf16_f32 v71, v66, v67
	v_cvt_pk_bf16_f32 v60, v60, v61
	v_cvt_pk_bf16_f32 v61, v62, v63
	v_cvt_pk_bf16_f32 v62, v56, v57
	v_cvt_pk_bf16_f32 v63, v58, v59
	v_cvt_pk_bf16_f32 v40, v52, v53
	v_cvt_pk_bf16_f32 v41, v54, v55
	v_cvt_pk_bf16_f32 v42, v48, v49
	v_cvt_pk_bf16_f32 v43, v50, v51
	v_cvt_pk_bf16_f32 v24, v36, v37
	v_cvt_pk_bf16_f32 v25, v38, v39
	v_cvt_pk_bf16_f32 v26, v32, v33
	v_cvt_pk_bf16_f32 v27, v34, v35
	v_cvt_pk_bf16_f32 v8, v20, v21
	v_cvt_pk_bf16_f32 v9, v22, v23
	v_cvt_pk_bf16_f32 v10, v16, v17
	v_cvt_pk_bf16_f32 v11, v18, v19
	v_cvt_pk_bf16_f32 v4, v4, v5
	v_cvt_pk_bf16_f32 v5, v6, v7
	v_cvt_pk_bf16_f32 v6, v0, v1
	v_cvt_pk_bf16_f32 v7, v2, v3
	s_and_b64 vcc, exec, s[2:3]
	s_mov_b32 s44, s6
	s_mov_b32 s45, s10
	s_mov_b64 s[18:19], s[14:15]
	s_mov_b64 s[16:17], s[12:13]
	global_store_dwordx4 v[150:151], v[124:127], off
	global_store_dwordx4 v[108:109], v[104:107], off
	global_store_dwordx4 v[92:93], v[88:91], off
	global_store_dwordx4 v[76:77], v[72:75], off
	global_store_dwordx4 v[76:77], v[68:71], off offset:256
	global_store_dwordx4 v[64:65], v[60:63], off
	global_store_dwordx4 v[44:45], v[40:43], off
	global_store_dwordx4 v[28:29], v[24:27], off
	global_store_dwordx4 v[12:13], v[8:11], off
	global_store_dwordx4 v[12:13], v[4:7], off offset:256
	s_cbranch_vccz .LBB0_331
	s_waitcnt vmcnt(0)
	s_cmpk_gt_u32 s24, 0xff
	s_cbranch_scc1 .LBB0_338
	s_barrier

; #define STG(P, GB) do { const char* _gb = (GB); \
;     _Pragma("unroll") for (int _i = 0; _i < 2; ++_i) { \
;       __builtin_amdgcn_global_load_lds((const unsigned*)(_gb + voff[_i]), \
;         (LAS unsigned*)((LAS char*)(P) + ldsw + _i * 8192), 16, 0, 0); } } while (0)
; #define LDA(dst, b, h) _Pragma("unroll") for (int m = 0; m < 4; ++m) _Pragma("unroll") for (int k = 0; k < 2; ++k) \
;     dst[m][k] = *(const LAS bf16x8*)((LAS char*)SA(b, h) + aoff + m * 2048 + k * 1024)
; #define LDB(dst, b, h) _Pragma("unroll") for (int n = 0; n < 2; ++n) _Pragma("unroll") for (int k = 0; k < 2; ++k) \
;     dst[n][k] = *(const LAS bf16x8*)((LAS char*)SB(b, h) + boff + n * 2048 + k * 1024)
; #define MMA(ai, bj, At_, Bt_) do { __builtin_amdgcn_s_setprio(1); \
;     _Pragma("unroll") for (int m = 0; m < 4; ++m) _Pragma("unroll") for (int n = 0; n < 2; ++n) _Pragma("unroll") for (int k = 0; k < 2; ++k) \
;       acc[ai][bj][m][n] = __builtin_amdgcn_mfma_f32_16x16x32_bf16(Bt_[n][k], At_[m][k], acc[ai][bj][m][n], 0, 0, 0); \
;     __builtin_amdgcn_s_setprio(0); } while (0)
; #define WAIT_V(n) asm volatile("s_waitcnt vmcnt(" #n ")" ::: "memory")
; #define WAIT_L(n) asm volatile("s_waitcnt lgkmcnt(" #n ")" ::: "memory")
; #define BAR __builtin_amdgcn_s_barrier()
; #define SCHED __builtin_amdgcn_sched_barrier(0)
; __device__ __forceinline__ void gemm_phase(const bf16_t* __restrict__ A, const bf16_t* __restrict__ Bt, bf16_t* __restrict__ C, int M, int N, int K,
;                                            int ldc, const int EPI, char* smem, const int wid_u) {
;     ...
;       LDB(B0, 0, 0); SCHED; LDA(At, 0, 0); STG(SA(1, 1), a1 + hstep);
;       WAIT_L(8); BAR; WAIT_L(0); MMA(0, 0, At, B0); BAR; SCHED;
;       LDB(B1, 0, 1); STG(SB(0, 0), b2);
;       BAR; WAIT_L(0); MMA(0, 1, At, B1); BAR;
;       LDA(At, 0, 1); STG(SA(0, 0), a2);
;       BAR; WAIT_L(0); MMA(1, 0, At, B0); BAR; SCHED;
;       STG(SB(0, 1), b2 + hstep);
;       WAIT_V(6); BAR; MMA(1, 1, At, B1); BAR;
.LBB0_905:
	ds_read_b128 v[148:151], v144
	ds_read_b128 v[152:155], v144 offset:1024
	ds_read_b128 v[156:159], v144 offset:2048
	ds_read_b128 v[160:163], v144 offset:3072
	s_add_u32 s18, s16, 0x100
	s_addc_u32 s19, s17, 0
	s_cmp_eq_u32 s55, 12
	s_cselect_b32 s23, s49, s19
	s_cselect_b32 s22, s50, s18
	s_cselect_b32 s21, s51, s54
	s_cselect_b32 s20, s52, s53
	s_mov_b32 m0, s38
	v_lshl_add_u64 v[196:197], s[16:17], 0, v[136:137]
	ds_read_b128 v[164:167], v145
	ds_read_b128 v[168:171], v145 offset:1024
	ds_read_b128 v[172:175], v145 offset:2048
	ds_read_b128 v[176:179], v145 offset:3072
	ds_read_b128 v[180:183], v145 offset:4096
	ds_read_b128 v[184:187], v145 offset:5120
	ds_read_b128 v[188:191], v145 offset:6144
	ds_read_b128 v[192:195], v145 offset:7168
	global_load_lds_dwordx4 v[196:197], off
	v_lshl_add_u64 v[196:197], s[16:17], 0, v[134:135]
	s_mov_b32 m0, s39
	s_nop 0
	global_load_lds_dwordx4 v[196:197], off
	s_waitcnt lgkmcnt(8)
	s_barrier
	s_waitcnt lgkmcnt(0)
	s_waitcnt lgkmcnt(0)
	v_mfma_f32_16x16x32_bf16 v[124:127], v[148:151], v[164:167], v[124:127]
	v_mfma_f32_16x16x32_bf16 v[120:123], v[156:159], v[164:167], v[120:123]
	v_mfma_f32_16x16x32_bf16 v[116:119], v[148:151], v[172:175], v[116:119]
	v_mfma_f32_16x16x32_bf16 v[112:115], v[156:159], v[172:175], v[112:115]
	v_mfma_f32_16x16x32_bf16 v[100:103], v[148:151], v[180:183], v[100:103]
	v_mfma_f32_16x16x32_bf16 v[96:99], v[156:159], v[180:183], v[96:99]
	v_mfma_f32_16x16x32_bf16 v[84:87], v[148:151], v[188:191], v[84:87]
	v_mfma_f32_16x16x32_bf16 v[80:83], v[156:159], v[188:191], v[80:83]
	v_mfma_f32_16x16x32_bf16 v[124:127], v[152:155], v[168:171], v[124:127]
	v_mfma_f32_16x16x32_bf16 v[120:123], v[160:163], v[168:171], v[120:123]
	v_mfma_f32_16x16x32_bf16 v[116:119], v[152:155], v[176:179], v[116:119]
	v_mfma_f32_16x16x32_bf16 v[112:115], v[160:163], v[176:179], v[112:115]
	v_mfma_f32_16x16x32_bf16 v[100:103], v[152:155], v[184:187], v[100:103]
	v_mfma_f32_16x16x32_bf16 v[96:99], v[160:163], v[184:187], v[96:99]
	v_mfma_f32_16x16x32_bf16 v[84:87], v[152:155], v[192:195], v[84:87]
	v_mfma_f32_16x16x32_bf16 v[80:83], v[160:163], v[192:195], v[80:83]
	s_barrier
	s_mov_b32 m0, s40
	v_lshl_add_u64 v[212:213], s[20:21], 0, v[130:131]
	ds_read_b128 v[196:199], v146
	ds_read_b128 v[200:203], v146 offset:1024
	ds_read_b128 v[204:207], v146 offset:2048
	ds_read_b128 v[208:211], v146 offset:3072
	global_load_lds_dwordx4 v[212:213], off
	v_lshl_add_u64 v[214:215], s[20:21], 0, v[128:129]
	s_mov_b32 m0, s41
	s_nop 0
	global_load_lds_dwordx4 v[214:215], off
	s_barrier
	s_waitcnt lgkmcnt(0)
	s_waitcnt lgkmcnt(0)
	v_mfma_f32_16x16x32_bf16 v[108:111], v[196:199], v[164:167], v[108:111]
	v_mfma_f32_16x16x32_bf16 v[104:107], v[204:207], v[164:167], v[104:107]
	v_mfma_f32_16x16x32_bf16 v[92:95], v[196:199], v[172:175], v[92:95]
	v_mfma_f32_16x16x32_bf16 v[88:91], v[204:207], v[172:175], v[88:91]
	v_mfma_f32_16x16x32_bf16 v[76:79], v[196:199], v[180:183], v[76:79]
	v_mfma_f32_16x16x32_bf16 v[72:75], v[204:207], v[180:183], v[72:75]
	v_mfma_f32_16x16x32_bf16 v[68:71], v[196:199], v[188:191], v[68:71]
	v_mfma_f32_16x16x32_bf16 v[64:67], v[204:207], v[188:191], v[64:67]
	v_mfma_f32_16x16x32_bf16 v[108:111], v[200:203], v[168:171], v[108:111]
	v_mfma_f32_16x16x32_bf16 v[104:107], v[208:211], v[168:171], v[104:107]
	v_mfma_f32_16x16x32_bf16 v[92:95], v[200:203], v[176:179], v[92:95]
	v_mfma_f32_16x16x32_bf16 v[88:91], v[208:211], v[176:179], v[88:91]
	v_mfma_f32_16x16x32_bf16 v[76:79], v[200:203], v[184:187], v[76:79]
	v_mfma_f32_16x16x32_bf16 v[72:75], v[208:211], v[184:187], v[72:75]
	v_mfma_f32_16x16x32_bf16 v[68:71], v[200:203], v[192:195], v[68:71]
	v_mfma_f32_16x16x32_bf16 v[64:67], v[208:211], v[192:195], v[64:67]
	s_mov_b32 m0, s30
	v_lshl_add_u64 v[216:217], s[22:23], 0, v[130:131]
	s_barrier
	ds_read_b128 v[164:167], v145 offset:16384
	ds_read_b128 v[168:171], v145 offset:17408
	ds_read_b128 v[172:175], v145 offset:18432
	ds_read_b128 v[176:179], v145 offset:19456
	ds_read_b128 v[180:183], v145 offset:20480
	ds_read_b128 v[184:187], v145 offset:21504
	ds_read_b128 v[188:191], v145 offset:22528
	ds_read_b128 v[192:195], v145 offset:23552
	global_load_lds_dwordx4 v[216:217], off
	v_lshl_add_u64 v[218:219], s[22:23], 0, v[128:129]
	s_mov_b32 m0, s31
	s_nop 0
	global_load_lds_dwordx4 v[218:219], off
	s_barrier
	s_waitcnt lgkmcnt(0)
	s_waitcnt lgkmcnt(0)
	v_mfma_f32_16x16x32_bf16 v[60:63], v[148:151], v[164:167], v[60:63]
	v_mfma_f32_16x16x32_bf16 v[56:59], v[156:159], v[164:167], v[56:59]
	v_mfma_f32_16x16x32_bf16 v[52:55], v[148:151], v[172:175], v[52:55]
	v_mfma_f32_16x16x32_bf16 v[48:51], v[156:159], v[172:175], v[48:51]
	v_mfma_f32_16x16x32_bf16 v[36:39], v[148:151], v[180:183], v[36:39]
	v_mfma_f32_16x16x32_bf16 v[32:35], v[156:159], v[180:183], v[32:35]
	v_mfma_f32_16x16x32_bf16 v[20:23], v[148:151], v[188:191], v[20:23]
	v_mfma_f32_16x16x32_bf16 v[16:19], v[156:159], v[188:191], v[16:19]
	v_mfma_f32_16x16x32_bf16 v[60:63], v[152:155], v[168:171], v[60:63]
	v_mfma_f32_16x16x32_bf16 v[56:59], v[160:163], v[168:171], v[56:59]
	v_mfma_f32_16x16x32_bf16 v[52:55], v[152:155], v[176:179], v[52:55]
	v_mfma_f32_16x16x32_bf16 v[48:51], v[160:163], v[176:179], v[48:51]
	v_mfma_f32_16x16x32_bf16 v[36:39], v[152:155], v[184:187], v[36:39]
	v_mfma_f32_16x16x32_bf16 v[32:35], v[160:163], v[184:187], v[32:35]
	v_mfma_f32_16x16x32_bf16 v[20:23], v[152:155], v[192:195], v[20:23]
	v_mfma_f32_16x16x32_bf16 v[16:19], v[160:163], v[192:195], v[16:19]
	s_barrier
; #define STG(P, GB) do { const char* _gb = (GB); \
;     _Pragma("unroll") for (int _i = 0; _i < 2; ++_i) { \
;       __builtin_amdgcn_global_load_lds((const unsigned*)(_gb + voff[_i]), \
;         (LAS unsigned*)((LAS char*)(P) + ldsw + _i * 8192), 16, 0, 0); } } while (0)
; #define LDA(dst, b, h) _Pragma("unroll") for (int m = 0; m < 4; ++m) _Pragma("unroll") for (int k = 0; k < 2; ++k) \
;     dst[m][k] = *(const LAS bf16x8*)((LAS char*)SA(b, h) + aoff + m * 2048 + k * 1024)
; #define LDB(dst, b, h) _Pragma("unroll") for (int n = 0; n < 2; ++n) _Pragma("unroll") for (int k = 0; k < 2; ++k) \
;     dst[n][k] = *(const LAS bf16x8*)((LAS char*)SB(b, h) + boff + n * 2048 + k * 1024)
; #define MMA(ai, bj, At_, Bt_) do { __builtin_amdgcn_s_setprio(1); \
;     _Pragma("unroll") for (int m = 0; m < 4; ++m) _Pragma("unroll") for (int n = 0; n < 2; ++n) _Pragma("unroll") for (int k = 0; k < 2; ++k) \
;       acc[ai][bj][m][n] = __builtin_amdgcn_mfma_f32_16x16x32_bf16(Bt_[n][k], At_[m][k], acc[ai][bj][m][n], 0, 0, 0); \
;     __builtin_amdgcn_s_setprio(0); } while (0)
; #define WAIT_V(n) asm volatile("s_waitcnt vmcnt(" #n ")" ::: "memory")
; #define WAIT_L(n) asm volatile("s_waitcnt lgkmcnt(" #n ")" ::: "memory")
; #define BAR __builtin_amdgcn_s_barrier()
; #define SCHED __builtin_amdgcn_sched_barrier(0)
; __device__ __forceinline__ void gemm_phase(const bf16_t* __restrict__ A, const bf16_t* __restrict__ Bt, bf16_t* __restrict__ C, int M, int N, int K,
;                                            int ldc, const int EPI, char* smem, const int wid_u) {
;     ...
;       WAIT_V(6); BAR; MMA(1, 1, At, B1); BAR;
;       LDB(B0, 1, 0); SCHED; LDA(At, 1, 0); STG(SA(0, 1), a2 + hstep);
;       WAIT_L(8); BAR; WAIT_L(0); MMA(0, 0, At, B0); BAR; SCHED;
;       LDB(B1, 1, 1); STG(SB(1, 0), b3);
;       BAR; WAIT_L(0); MMA(0, 1, At, B1); BAR;
;       LDA(At, 1, 1); STG(SA(1, 0), a3);
;       BAR; WAIT_L(0); MMA(1, 0, At, B0); BAR; SCHED;
	s_add_u32 s16, s20, 0x40000
	s_addc_u32 s17, s21, 0
	s_mov_b32 m0, s44
	v_lshl_add_u64 v[148:149], s[16:17], 0, v[130:131]
	global_load_lds_dwordx4 v[148:149], off
	v_lshl_add_u64 v[148:149], s[16:17], 0, v[128:129]
	s_add_i32 m0, s44, 0x2000
	s_nop 0
	global_load_lds_dwordx4 v[148:149], off
	s_waitcnt vmcnt(6)
	s_barrier
	v_mfma_f32_16x16x32_bf16 v[44:47], v[196:199], v[164:167], v[44:47]
	v_mfma_f32_16x16x32_bf16 v[40:43], v[204:207], v[164:167], v[40:43]
	v_mfma_f32_16x16x32_bf16 v[28:31], v[196:199], v[172:175], v[28:31]
	v_mfma_f32_16x16x32_bf16 v[24:27], v[204:207], v[172:175], v[24:27]
	v_mfma_f32_16x16x32_bf16 v[12:15], v[196:199], v[180:183], v[12:15]
	v_mfma_f32_16x16x32_bf16 v[8:11], v[204:207], v[180:183], v[8:11]
	v_mfma_f32_16x16x32_bf16 v[4:7], v[196:199], v[188:191], v[4:7]
	v_mfma_f32_16x16x32_bf16 v[0:3], v[204:207], v[188:191], v[0:3]
	v_mfma_f32_16x16x32_bf16 v[44:47], v[200:203], v[168:171], v[44:47]
	v_mfma_f32_16x16x32_bf16 v[40:43], v[208:211], v[168:171], v[40:43]
	v_mfma_f32_16x16x32_bf16 v[28:31], v[200:203], v[176:179], v[28:31]
	v_mfma_f32_16x16x32_bf16 v[24:27], v[208:211], v[176:179], v[24:27]
	v_mfma_f32_16x16x32_bf16 v[12:15], v[200:203], v[184:187], v[12:15]
	v_mfma_f32_16x16x32_bf16 v[8:11], v[208:211], v[184:187], v[8:11]
	v_mfma_f32_16x16x32_bf16 v[4:7], v[200:203], v[192:195], v[4:7]
	v_mfma_f32_16x16x32_bf16 v[0:3], v[208:211], v[192:195], v[0:3]
	s_add_i32 s56, 0, 0x18000
	v_add_u32_e32 v147, s56, v143
	s_barrier
	ds_read_b128 v[148:151], v147
	ds_read_b128 v[152:155], v147 offset:1024
	ds_read_b128 v[156:159], v147 offset:2048
	ds_read_b128 v[160:163], v147 offset:3072
	s_add_u32 s16, s22, 0x40000
	s_addc_u32 s17, s23, 0
	s_mov_b32 m0, s34
	v_lshl_add_u64 v[196:197], s[16:17], 0, v[130:131]
	ds_read_b128 v[164:167], v145 offset:32768
	ds_read_b128 v[168:171], v145 offset:33792
	ds_read_b128 v[172:175], v145 offset:34816
	ds_read_b128 v[176:179], v145 offset:35840
	ds_read_b128 v[180:183], v145 offset:36864
	ds_read_b128 v[184:187], v145 offset:37888
	ds_read_b128 v[188:191], v145 offset:38912
	ds_read_b128 v[192:195], v145 offset:39936
	global_load_lds_dwordx4 v[196:197], off
	v_lshl_add_u64 v[196:197], s[16:17], 0, v[128:129]
	s_mov_b32 m0, s35
	s_nop 0
	global_load_lds_dwordx4 v[196:197], off
	s_waitcnt lgkmcnt(8)
	s_barrier
	s_waitcnt lgkmcnt(0)
	s_waitcnt lgkmcnt(0)
	v_mfma_f32_16x16x32_bf16 v[124:127], v[148:151], v[164:167], v[124:127]
	v_mfma_f32_16x16x32_bf16 v[120:123], v[156:159], v[164:167], v[120:123]
	v_mfma_f32_16x16x32_bf16 v[116:119], v[148:151], v[172:175], v[116:119]
	v_mfma_f32_16x16x32_bf16 v[112:115], v[156:159], v[172:175], v[112:115]
	v_mfma_f32_16x16x32_bf16 v[100:103], v[148:151], v[180:183], v[100:103]
	v_mfma_f32_16x16x32_bf16 v[96:99], v[156:159], v[180:183], v[96:99]
	v_mfma_f32_16x16x32_bf16 v[84:87], v[148:151], v[188:191], v[84:87]
	v_mfma_f32_16x16x32_bf16 v[80:83], v[156:159], v[188:191], v[80:83]
	v_mfma_f32_16x16x32_bf16 v[124:127], v[152:155], v[168:171], v[124:127]
	v_mfma_f32_16x16x32_bf16 v[120:123], v[160:163], v[168:171], v[120:123]
	v_mfma_f32_16x16x32_bf16 v[116:119], v[152:155], v[176:179], v[116:119]
	v_mfma_f32_16x16x32_bf16 v[112:115], v[160:163], v[176:179], v[112:115]
	v_mfma_f32_16x16x32_bf16 v[100:103], v[152:155], v[184:187], v[100:103]
	v_mfma_f32_16x16x32_bf16 v[96:99], v[160:163], v[184:187], v[96:99]
	v_mfma_f32_16x16x32_bf16 v[84:87], v[152:155], v[192:195], v[84:87]
	v_mfma_f32_16x16x32_bf16 v[80:83], v[160:163], v[192:195], v[80:83]
	s_barrier
	s_add_i32 s22, 0, 0x1c000
	s_add_i32 s16, s56, s29
	v_add_u32_e32 v147, s22, v143
	v_lshl_add_u64 v[212:213], v[212:213], 0, s[10:11]
	s_mov_b32 m0, s16
	ds_read_b128 v[196:199], v147
	ds_read_b128 v[200:203], v147 offset:1024
	ds_read_b128 v[204:207], v147 offset:2048
	ds_read_b128 v[208:211], v147 offset:3072
	global_load_lds_dwordx4 v[212:213], off
	v_lshl_add_u64 v[212:213], v[214:215], 0, s[10:11]
	s_add_i32 m0, s16, 0x2000
	s_nop 0
	global_load_lds_dwordx4 v[212:213], off
	s_barrier
	s_waitcnt lgkmcnt(0)
	s_waitcnt lgkmcnt(0)
	v_mfma_f32_16x16x32_bf16 v[108:111], v[196:199], v[164:167], v[108:111]
	v_mfma_f32_16x16x32_bf16 v[104:107], v[204:207], v[164:167], v[104:107]
	v_mfma_f32_16x16x32_bf16 v[92:95], v[196:199], v[172:175], v[92:95]
	v_mfma_f32_16x16x32_bf16 v[88:91], v[204:207], v[172:175], v[88:91]
	v_mfma_f32_16x16x32_bf16 v[76:79], v[196:199], v[180:183], v[76:79]
	v_mfma_f32_16x16x32_bf16 v[72:75], v[204:207], v[180:183], v[72:75]
	v_mfma_f32_16x16x32_bf16 v[68:71], v[196:199], v[188:191], v[68:71]
	v_mfma_f32_16x16x32_bf16 v[64:67], v[204:207], v[188:191], v[64:67]
	v_mfma_f32_16x16x32_bf16 v[108:111], v[200:203], v[168:171], v[108:111]
	v_mfma_f32_16x16x32_bf16 v[104:107], v[208:211], v[168:171], v[104:107]
	v_mfma_f32_16x16x32_bf16 v[92:95], v[200:203], v[176:179], v[92:95]
	v_mfma_f32_16x16x32_bf16 v[88:91], v[208:211], v[176:179], v[88:91]
	v_mfma_f32_16x16x32_bf16 v[76:79], v[200:203], v[184:187], v[76:79]
	v_mfma_f32_16x16x32_bf16 v[72:75], v[208:211], v[184:187], v[72:75]
	v_mfma_f32_16x16x32_bf16 v[68:71], v[200:203], v[192:195], v[68:71]
	v_mfma_f32_16x16x32_bf16 v[64:67], v[208:211], v[192:195], v[64:67]
	s_mov_b32 m0, s36
	v_lshl_add_u64 v[212:213], v[216:217], 0, s[10:11]
	s_barrier
	ds_read_b128 v[164:167], v145 offset:49152
	ds_read_b128 v[168:171], v145 offset:50176
	ds_read_b128 v[172:175], v145 offset:51200
	ds_read_b128 v[176:179], v145 offset:52224
	ds_read_b128 v[180:183], v145 offset:53248
	ds_read_b128 v[184:187], v145 offset:54272
	ds_read_b128 v[188:191], v145 offset:55296
	ds_read_b128 v[192:195], v145 offset:56320
	global_load_lds_dwordx4 v[212:213], off
	v_lshl_add_u64 v[212:213], v[218:219], 0, s[10:11]
	s_mov_b32 m0, s37
	s_nop 0
	global_load_lds_dwordx4 v[212:213], off
	s_barrier
; #define STG(P, GB) do { const char* _gb = (GB); \
;     _Pragma("unroll") for (int _i = 0; _i < 2; ++_i) { \
;       __builtin_amdgcn_global_load_lds((const unsigned*)(_gb + voff[_i]), \
;         (LAS unsigned*)((LAS char*)(P) + ldsw + _i * 8192), 16, 0, 0); } } while (0)
; #define MMA(ai, bj, At_, Bt_) do { __builtin_amdgcn_s_setprio(1); \
;     _Pragma("unroll") for (int m = 0; m < 4; ++m) _Pragma("unroll") for (int n = 0; n < 2; ++n) _Pragma("unroll") for (int k = 0; k < 2; ++k) \
;       acc[ai][bj][m][n] = __builtin_amdgcn_mfma_f32_16x16x32_bf16(Bt_[n][k], At_[m][k], acc[ai][bj][m][n], 0, 0, 0); \
;     __builtin_amdgcn_s_setprio(0); } while (0)
; #define WAIT_V(n) asm volatile("s_waitcnt vmcnt(" #n ")" ::: "memory")
; #define WAIT_L(n) asm volatile("s_waitcnt lgkmcnt(" #n ")" ::: "memory")
; #define BAR __builtin_amdgcn_s_barrier()
; #define SCHED __builtin_amdgcn_sched_barrier(0)
; __device__ __forceinline__ void gemm_phase(const bf16_t* __restrict__ A, const bf16_t* __restrict__ Bt, bf16_t* __restrict__ C, int M, int N, int K,
;                                            int ldc, const int EPI, char* smem, const int wid_u) {
;     ...
;       BAR; WAIT_L(0); MMA(1, 0, At, B0); BAR; SCHED;
;       STG(SB(1, 1), b3 + hstep);
;       WAIT_V(6); BAR; MMA(1, 1, At, B1); BAR;
	s_waitcnt lgkmcnt(0)
	s_waitcnt lgkmcnt(0)
	v_mfma_f32_16x16x32_bf16 v[60:63], v[148:151], v[164:167], v[60:63]
	v_mfma_f32_16x16x32_bf16 v[56:59], v[156:159], v[164:167], v[56:59]
	v_mfma_f32_16x16x32_bf16 v[52:55], v[148:151], v[172:175], v[52:55]
	v_mfma_f32_16x16x32_bf16 v[48:51], v[156:159], v[172:175], v[48:51]
	v_mfma_f32_16x16x32_bf16 v[36:39], v[148:151], v[180:183], v[36:39]
	v_mfma_f32_16x16x32_bf16 v[32:35], v[156:159], v[180:183], v[32:35]
	v_mfma_f32_16x16x32_bf16 v[20:23], v[148:151], v[188:191], v[20:23]
	v_mfma_f32_16x16x32_bf16 v[16:19], v[156:159], v[188:191], v[16:19]
	v_mfma_f32_16x16x32_bf16 v[60:63], v[152:155], v[168:171], v[60:63]
	v_mfma_f32_16x16x32_bf16 v[56:59], v[160:163], v[168:171], v[56:59]
	v_mfma_f32_16x16x32_bf16 v[52:55], v[152:155], v[176:179], v[52:55]
	v_mfma_f32_16x16x32_bf16 v[48:51], v[160:163], v[176:179], v[48:51]
	v_mfma_f32_16x16x32_bf16 v[36:39], v[152:155], v[184:187], v[36:39]
	v_mfma_f32_16x16x32_bf16 v[32:35], v[160:163], v[184:187], v[32:35]
	v_mfma_f32_16x16x32_bf16 v[20:23], v[152:155], v[192:195], v[20:23]
	v_mfma_f32_16x16x32_bf16 v[16:19], v[160:163], v[192:195], v[16:19]
	s_barrier
	s_add_u32 s16, s20, 0x40080
	s_addc_u32 s17, s21, 0
	s_add_i32 s20, s22, s29
	v_lshl_add_u64 v[148:149], s[16:17], 0, v[130:131]
	s_mov_b32 m0, s20
	s_nop 0
	global_load_lds_dwordx4 v[148:149], off
	v_lshl_add_u64 v[148:149], s[16:17], 0, v[128:129]
	s_add_i32 m0, s20, 0x2000
	s_nop 0
	global_load_lds_dwordx4 v[148:149], off
	s_waitcnt vmcnt(6)
	s_barrier
	v_mfma_f32_16x16x32_bf16 v[44:47], v[196:199], v[164:167], v[44:47]
	v_mfma_f32_16x16x32_bf16 v[40:43], v[204:207], v[164:167], v[40:43]
	v_mfma_f32_16x16x32_bf16 v[28:31], v[196:199], v[172:175], v[28:31]
	v_mfma_f32_16x16x32_bf16 v[24:27], v[204:207], v[172:175], v[24:27]
	v_mfma_f32_16x16x32_bf16 v[12:15], v[196:199], v[180:183], v[12:15]
	v_mfma_f32_16x16x32_bf16 v[8:11], v[204:207], v[180:183], v[8:11]
	v_mfma_f32_16x16x32_bf16 v[4:7], v[196:199], v[188:191], v[4:7]
	v_mfma_f32_16x16x32_bf16 v[0:3], v[204:207], v[188:191], v[0:3]
	v_mfma_f32_16x16x32_bf16 v[44:47], v[200:203], v[168:171], v[44:47]
	v_mfma_f32_16x16x32_bf16 v[40:43], v[208:211], v[168:171], v[40:43]
	v_mfma_f32_16x16x32_bf16 v[28:31], v[200:203], v[176:179], v[28:31]
	v_mfma_f32_16x16x32_bf16 v[24:27], v[208:211], v[176:179], v[24:27]
	v_mfma_f32_16x16x32_bf16 v[12:15], v[200:203], v[184:187], v[12:15]
	v_mfma_f32_16x16x32_bf16 v[8:11], v[208:211], v[184:187], v[8:11]
	v_mfma_f32_16x16x32_bf16 v[4:7], v[200:203], v[192:195], v[4:7]
	v_mfma_f32_16x16x32_bf16 v[0:3], v[208:211], v[192:195], v[0:3]
	s_add_i32 s55, s55, 2
	s_add_u32 s53, s53, 0x100
	s_addc_u32 s54, s54, 0
	s_cmp_gt_u32 s55, 13
	s_mov_b64 s[16:17], s[18:19]
	s_barrier
	s_cbranch_scc0 .LBB0_905
; #define WAIT_V(n) asm volatile("s_waitcnt vmcnt(" #n ")" ::: "memory")
; #define BAR __builtin_amdgcn_s_barrier()
; __device__ __forceinline__ void gemm_phase(const bf16_t* __restrict__ A, const bf16_t* __restrict__ Bt, bf16_t* __restrict__ C, int M, int N, int K,
;                                            int ldc, const int EPI, char* smem, const int wid_u) {
;     ...
;           if (EPI == 0) {
; #pragma unroll
;             for (int bj = 0; bj < 2; ++bj) {
;               const f32x4 v0 = acc[ai][bj][m][0], v1 = acc[ai][bj][m][1];
;               uint4 u; u.x = cvt_pk_bf16(v0[0], v0[1]); u.y = cvt_pk_bf16(v0[2], v0[3]); u.z = cvt_pk_bf16(v1[0], v1[1]); u.w = cvt_pk_bf16(v1[2], v1[3]);
;               *(uint4*)(C + row * ldc + bcol + bj * HALF + wc * 32 + fq * 8) = u;
;             }
;     ...
;     if (!has_next) break;
; #pragma unroll
;     for (int a = 0; a < 2; ++a)
; #pragma unroll
;       for (int b = 0; b < 2; ++b)
; #pragma unroll
;         for (int m = 0; m < 4; ++m)
; #pragma unroll
;           for (int n = 0; n < 2; ++n) acc[a][b][m][n] = (f32x4){0.f, 0.f, 0.f, 0.f};
;     pm = npm; pn = npn; cA = nA; cB = nB; ++ui;
;   }
;   WAIT_V(0);
;   if (wr == 0) BAR;
;   BAR;
	v_lshl_add_u32 v148, s47, 8, v142
	v_cvt_pk_bf16_f32 v68, v68, v69
	v_cvt_pk_bf16_f32 v69, v70, v71
	v_cvt_pk_bf16_f32 v70, v64, v65
	v_add_u32_e32 v64, 0x80, v148
	s_lshl_b32 s16, s48, 9
	s_mov_b32 s17, s9
	v_ashrrev_i32_e32 v149, 31, v148
	v_cvt_pk_bf16_f32 v108, v108, v109
	v_cvt_pk_bf16_f32 v109, v110, v111
	v_cvt_pk_bf16_f32 v110, v104, v105
	v_or_b32_e32 v104, 16, v148
	v_ashrrev_i32_e32 v65, 31, v64
	v_cvt_pk_bf16_f32 v44, v44, v45
	v_cvt_pk_bf16_f32 v45, v46, v47
	v_cvt_pk_bf16_f32 v46, v40, v41
	v_add_u32_e32 v40, 0x90, v148
	v_lshl_add_u64 v[150:151], v[132:133], 0, s[16:17]
	v_lshlrev_b64 v[152:153], 11, v[148:149]
	v_ashrrev_i32_e32 v105, 31, v104
	v_cvt_pk_bf16_f32 v92, v92, v93
	v_cvt_pk_bf16_f32 v93, v94, v95
	v_cvt_pk_bf16_f32 v94, v88, v89
	v_or_b32_e32 v88, 32, v148
	v_lshlrev_b64 v[64:65], 11, v[64:65]
	v_ashrrev_i32_e32 v41, 31, v40
	v_cvt_pk_bf16_f32 v28, v28, v29
	v_cvt_pk_bf16_f32 v29, v30, v31
	v_cvt_pk_bf16_f32 v30, v24, v25
	v_add_u32_e32 v24, 0xa0, v148
	v_lshl_add_u64 v[152:153], v[150:151], 0, v[152:153]
	v_cvt_pk_bf16_f32 v111, v106, v107
	v_lshlrev_b64 v[104:105], 11, v[104:105]
	v_ashrrev_i32_e32 v89, 31, v88
	v_cvt_pk_bf16_f32 v76, v76, v77
	v_cvt_pk_bf16_f32 v77, v78, v79
	v_cvt_pk_bf16_f32 v78, v72, v73
	v_or_b32_e32 v72, 48, v148
	v_lshl_add_u64 v[64:65], v[150:151], 0, v[64:65]
	v_cvt_pk_bf16_f32 v47, v42, v43
	v_lshlrev_b64 v[40:41], 11, v[40:41]
	v_ashrrev_i32_e32 v25, 31, v24
	v_cvt_pk_bf16_f32 v12, v12, v13
	v_cvt_pk_bf16_f32 v13, v14, v15
	v_cvt_pk_bf16_f32 v14, v8, v9
	v_add_u32_e32 v8, 0xb0, v148
	global_store_dwordx4 v[152:153], v[108:111], off offset:256
	v_cvt_pk_bf16_f32 v95, v90, v91
	v_lshlrev_b64 v[88:89], 11, v[88:89]
	v_lshl_add_u64 v[108:109], v[150:151], 0, v[104:105]
	v_ashrrev_i32_e32 v73, 31, v72
	global_store_dwordx4 v[64:65], v[44:47], off offset:256
	v_cvt_pk_bf16_f32 v31, v26, v27
	v_lshlrev_b64 v[24:25], 11, v[24:25]
	v_lshl_add_u64 v[44:45], v[150:151], 0, v[40:41]
	v_ashrrev_i32_e32 v9, 31, v8
	global_store_dwordx4 v[108:109], v[92:95], off offset:256
	v_cvt_pk_bf16_f32 v79, v74, v75
	v_lshlrev_b64 v[72:73], 11, v[72:73]
	v_lshl_add_u64 v[92:93], v[150:151], 0, v[88:89]
	global_store_dwordx4 v[44:45], v[28:31], off offset:256
	v_cvt_pk_bf16_f32 v15, v10, v11
	v_lshlrev_b64 v[8:9], 11, v[8:9]
	v_lshl_add_u64 v[28:29], v[150:151], 0, v[24:25]
	v_cvt_pk_bf16_f32 v124, v124, v125
	v_cvt_pk_bf16_f32 v125, v126, v127
	v_cvt_pk_bf16_f32 v126, v120, v121
	v_cvt_pk_bf16_f32 v127, v122, v123
	v_cvt_pk_bf16_f32 v104, v116, v117
	v_cvt_pk_bf16_f32 v105, v118, v119
	v_cvt_pk_bf16_f32 v106, v112, v113
	v_cvt_pk_bf16_f32 v107, v114, v115
	v_cvt_pk_bf16_f32 v88, v100, v101
	v_cvt_pk_bf16_f32 v89, v102, v103
	v_cvt_pk_bf16_f32 v90, v96, v97
	v_cvt_pk_bf16_f32 v91, v98, v99
	global_store_dwordx4 v[92:93], v[76:79], off offset:256
	v_cvt_pk_bf16_f32 v74, v80, v81
	v_cvt_pk_bf16_f32 v75, v82, v83
	v_lshl_add_u64 v[76:77], v[150:151], 0, v[72:73]
	v_cvt_pk_bf16_f32 v72, v84, v85
	v_cvt_pk_bf16_f32 v73, v86, v87
	v_cvt_pk_bf16_f32 v71, v66, v67
	v_cvt_pk_bf16_f32 v60, v60, v61
	v_cvt_pk_bf16_f32 v61, v62, v63
	v_cvt_pk_bf16_f32 v62, v56, v57
	v_cvt_pk_bf16_f32 v63, v58, v59
	v_cvt_pk_bf16_f32 v40, v52, v53
	v_cvt_pk_bf16_f32 v41, v54, v55
	v_cvt_pk_bf16_f32 v42, v48, v49
	v_cvt_pk_bf16_f32 v43, v50, v51
	v_cvt_pk_bf16_f32 v24, v36, v37
	v_cvt_pk_bf16_f32 v25, v38, v39
	v_cvt_pk_bf16_f32 v26, v32, v33
	v_cvt_pk_bf16_f32 v27, v34, v35
	global_store_dwordx4 v[28:29], v[12:15], off offset:256
	v_cvt_pk_bf16_f32 v10, v16, v17
	v_cvt_pk_bf16_f32 v11, v18, v19
	v_lshl_add_u64 v[12:13], v[150:151], 0, v[8:9]
	v_cvt_pk_bf16_f32 v8, v20, v21
	v_cvt_pk_bf16_f32 v9, v22, v23
	v_cvt_pk_bf16_f32 v4, v4, v5
	v_cvt_pk_bf16_f32 v5, v6, v7
	v_cvt_pk_bf16_f32 v6, v0, v1
	v_cvt_pk_bf16_f32 v7, v2, v3
	s_and_b64 vcc, exec, s[4:5]
	s_mov_b32 s47, s8
	s_mov_b32 s48, s46
	s_mov_b64 s[18:19], s[14:15]
	s_mov_b64 s[16:17], s[12:13]
	global_store_dwordx4 v[152:153], v[124:127], off
	global_store_dwordx4 v[108:109], v[104:107], off
	global_store_dwordx4 v[92:93], v[88:91], off
	global_store_dwordx4 v[76:77], v[72:75], off
	global_store_dwordx4 v[76:77], v[68:71], off offset:256
	global_store_dwordx4 v[64:65], v[60:63], off
	global_store_dwordx4 v[44:45], v[40:43], off
	global_store_dwordx4 v[28:29], v[24:27], off
	global_store_dwordx4 v[12:13], v[8:11], off
	global_store_dwordx4 v[12:13], v[4:7], off offset:256
	s_cbranch_vccz .LBB0_902
	s_waitcnt vmcnt(0)
	s_cmpk_gt_u32 s24, 0xff
	s_cbranch_scc1 .LBB0_909
	s_barrier

; #define STG(P, GB) do { const char* _gb = (GB); \
;     _Pragma("unroll") for (int _i = 0; _i < 2; ++_i) { \
;       __builtin_amdgcn_global_load_lds((const unsigned*)(_gb + voff[_i]), \
;         (LAS unsigned*)((LAS char*)(P) + ldsw + _i * 8192), 16, 0, 0); } } while (0)
; #define LDA(dst, b, h) _Pragma("unroll") for (int m = 0; m < 4; ++m) _Pragma("unroll") for (int k = 0; k < 2; ++k) \
;     dst[m][k] = *(const LAS bf16x8*)((LAS char*)SA(b, h) + aoff + m * 2048 + k * 1024)
; #define LDB(dst, b, h) _Pragma("unroll") for (int n = 0; n < 2; ++n) _Pragma("unroll") for (int k = 0; k < 2; ++k) \
;     dst[n][k] = *(const LAS bf16x8*)((LAS char*)SB(b, h) + boff + n * 2048 + k * 1024)
; #define MMA(ai, bj, At_, Bt_) do { __builtin_amdgcn_s_setprio(1); \
;     _Pragma("unroll") for (int m = 0; m < 4; ++m) _Pragma("unroll") for (int n = 0; n < 2; ++n) _Pragma("unroll") for (int k = 0; k < 2; ++k) \
;       acc[ai][bj][m][n] = __builtin_amdgcn_mfma_f32_16x16x32_bf16(Bt_[n][k], At_[m][k], acc[ai][bj][m][n], 0, 0, 0); \
;     __builtin_amdgcn_s_setprio(0); } while (0)
; #define WAIT_V(n) asm volatile("s_waitcnt vmcnt(" #n ")" ::: "memory")
; #define WAIT_L(n) asm volatile("s_waitcnt lgkmcnt(" #n ")" ::: "memory")
; #define BAR __builtin_amdgcn_s_barrier()
; #define SCHED __builtin_amdgcn_sched_barrier(0)
; __device__ __forceinline__ void gemm_phase(const bf16_t* __restrict__ A, const bf16_t* __restrict__ Bt, bf16_t* __restrict__ C, int M, int N, int K,
;                                            int ldc, const int EPI, char* smem, const int wid_u) {
;     ...
;       LDB(B0, 0, 0); SCHED; LDA(At, 0, 0); STG(SA(1, 1), a1 + hstep);
;       WAIT_L(8); BAR; WAIT_L(0); MMA(0, 0, At, B0); BAR; SCHED;
;       LDB(B1, 0, 1); STG(SB(0, 0), b2);
;       BAR; WAIT_L(0); MMA(0, 1, At, B1); BAR;
;       LDA(At, 0, 1); STG(SA(0, 0), a2);
;       BAR; WAIT_L(0); MMA(1, 0, At, B0); BAR; SCHED;
;       STG(SB(0, 1), b2 + hstep);
;       WAIT_V(6); BAR; MMA(1, 1, At, B1); BAR;
.LBB0_1026:
	ds_read_b128 v[150:153], v146
	ds_read_b128 v[154:157], v146 offset:1024
	ds_read_b128 v[158:161], v146 offset:2048
	ds_read_b128 v[162:165], v146 offset:3072
	s_add_u32 s20, s18, 0x100
	s_addc_u32 s21, s19, 0
	s_cmp_eq_u32 s53, 12
	s_cselect_b32 s25, s48, s21
	s_cselect_b32 s24, s49, s20
	s_cselect_b32 s23, s13, s52
	s_cselect_b32 s22, s50, s51
	v_lshl_add_u64 v[142:143], s[18:19], 0, v[136:137]
	s_add_i32 m0, s34, 0xc000
	ds_read_b128 v[166:169], v147
	ds_read_b128 v[170:173], v147 offset:1024
	ds_read_b128 v[174:177], v147 offset:2048
	ds_read_b128 v[178:181], v147 offset:3072
	ds_read_b128 v[182:185], v147 offset:4096
	ds_read_b128 v[186:189], v147 offset:5120
	ds_read_b128 v[190:193], v147 offset:6144
	ds_read_b128 v[194:197], v147 offset:7168
	global_load_lds_dwordx4 v[142:143], off
	v_lshl_add_u64 v[142:143], s[18:19], 0, v[134:135]
	s_add_i32 m0, s34, 0xe000
	s_nop 0
	global_load_lds_dwordx4 v[142:143], off
	s_waitcnt lgkmcnt(8)
	s_barrier
	s_waitcnt lgkmcnt(0)
	s_waitcnt lgkmcnt(0)
	v_mfma_f32_16x16x32_bf16 v[124:127], v[150:153], v[166:169], v[124:127]
	v_mfma_f32_16x16x32_bf16 v[120:123], v[158:161], v[166:169], v[120:123]
	v_mfma_f32_16x16x32_bf16 v[108:111], v[150:153], v[174:177], v[108:111]
	v_mfma_f32_16x16x32_bf16 v[104:107], v[158:161], v[174:177], v[104:107]
	v_mfma_f32_16x16x32_bf16 v[92:95], v[150:153], v[182:185], v[92:95]
	v_mfma_f32_16x16x32_bf16 v[88:91], v[158:161], v[182:185], v[88:91]
	v_mfma_f32_16x16x32_bf16 v[76:79], v[150:153], v[190:193], v[76:79]
	v_mfma_f32_16x16x32_bf16 v[72:75], v[158:161], v[190:193], v[72:75]
	v_mfma_f32_16x16x32_bf16 v[124:127], v[154:157], v[170:173], v[124:127]
	v_mfma_f32_16x16x32_bf16 v[120:123], v[162:165], v[170:173], v[120:123]
	v_mfma_f32_16x16x32_bf16 v[108:111], v[154:157], v[178:181], v[108:111]
	v_mfma_f32_16x16x32_bf16 v[104:107], v[162:165], v[178:181], v[104:107]
	v_mfma_f32_16x16x32_bf16 v[92:95], v[154:157], v[186:189], v[92:95]
	v_mfma_f32_16x16x32_bf16 v[88:91], v[162:165], v[186:189], v[88:91]
	v_mfma_f32_16x16x32_bf16 v[76:79], v[154:157], v[194:197], v[76:79]
	v_mfma_f32_16x16x32_bf16 v[72:75], v[162:165], v[194:197], v[72:75]
	s_barrier
	s_add_i32 s18, s40, s31
	v_lshl_add_u64 v[142:143], s[22:23], 0, v[130:131]
	s_mov_b32 m0, s18
	ds_read_b128 v[198:201], v148
	ds_read_b128 v[202:205], v148 offset:1024
	ds_read_b128 v[206:209], v148 offset:2048
	ds_read_b128 v[210:213], v148 offset:3072
	global_load_lds_dwordx4 v[142:143], off
	v_lshl_add_u64 v[214:215], s[22:23], 0, v[128:129]
	s_add_i32 m0, s18, 0x2000
	s_nop 0
	global_load_lds_dwordx4 v[214:215], off
	s_barrier
	s_waitcnt lgkmcnt(0)
	s_waitcnt lgkmcnt(0)
	v_mfma_f32_16x16x32_bf16 v[116:119], v[198:201], v[166:169], v[116:119]
	v_mfma_f32_16x16x32_bf16 v[112:115], v[206:209], v[166:169], v[112:115]
	v_mfma_f32_16x16x32_bf16 v[100:103], v[198:201], v[174:177], v[100:103]
	v_mfma_f32_16x16x32_bf16 v[96:99], v[206:209], v[174:177], v[96:99]
	v_mfma_f32_16x16x32_bf16 v[84:87], v[198:201], v[182:185], v[84:87]
	v_mfma_f32_16x16x32_bf16 v[80:83], v[206:209], v[182:185], v[80:83]
	v_mfma_f32_16x16x32_bf16 v[68:71], v[198:201], v[190:193], v[68:71]
	v_mfma_f32_16x16x32_bf16 v[64:67], v[206:209], v[190:193], v[64:67]
	v_mfma_f32_16x16x32_bf16 v[116:119], v[202:205], v[170:173], v[116:119]
	v_mfma_f32_16x16x32_bf16 v[112:115], v[210:213], v[170:173], v[112:115]
	v_mfma_f32_16x16x32_bf16 v[100:103], v[202:205], v[178:181], v[100:103]
	v_mfma_f32_16x16x32_bf16 v[96:99], v[210:213], v[178:181], v[96:99]
	v_mfma_f32_16x16x32_bf16 v[84:87], v[202:205], v[186:189], v[84:87]
	v_mfma_f32_16x16x32_bf16 v[80:83], v[210:213], v[186:189], v[80:83]
	v_mfma_f32_16x16x32_bf16 v[68:71], v[202:205], v[194:197], v[68:71]
	v_mfma_f32_16x16x32_bf16 v[64:67], v[210:213], v[194:197], v[64:67]
	s_mov_b32 m0, s34
	v_lshl_add_u64 v[216:217], s[24:25], 0, v[130:131]
	s_barrier
	ds_read_b128 v[166:169], v147 offset:16384
	ds_read_b128 v[170:173], v147 offset:17408
	ds_read_b128 v[174:177], v147 offset:18432
	ds_read_b128 v[178:181], v147 offset:19456
	ds_read_b128 v[182:185], v147 offset:20480
	ds_read_b128 v[186:189], v147 offset:21504
	ds_read_b128 v[190:193], v147 offset:22528
	ds_read_b128 v[194:197], v147 offset:23552
	global_load_lds_dwordx4 v[216:217], off
	v_lshl_add_u64 v[218:219], s[24:25], 0, v[128:129]
	s_mov_b32 m0, s35
	s_nop 0
	global_load_lds_dwordx4 v[218:219], off
	s_barrier
	s_waitcnt lgkmcnt(0)
	s_waitcnt lgkmcnt(0)
	v_mfma_f32_16x16x32_bf16 v[60:63], v[150:153], v[166:169], v[60:63]
	v_mfma_f32_16x16x32_bf16 v[56:59], v[158:161], v[166:169], v[56:59]
	v_mfma_f32_16x16x32_bf16 v[44:47], v[150:153], v[174:177], v[44:47]
	v_mfma_f32_16x16x32_bf16 v[40:43], v[158:161], v[174:177], v[40:43]
	v_mfma_f32_16x16x32_bf16 v[28:31], v[150:153], v[182:185], v[28:31]
	v_mfma_f32_16x16x32_bf16 v[24:27], v[158:161], v[182:185], v[24:27]
	v_mfma_f32_16x16x32_bf16 v[12:15], v[150:153], v[190:193], v[12:15]
	v_mfma_f32_16x16x32_bf16 v[8:11], v[158:161], v[190:193], v[8:11]
	v_mfma_f32_16x16x32_bf16 v[60:63], v[154:157], v[170:173], v[60:63]
	v_mfma_f32_16x16x32_bf16 v[56:59], v[162:165], v[170:173], v[56:59]
	v_mfma_f32_16x16x32_bf16 v[44:47], v[154:157], v[178:181], v[44:47]
	v_mfma_f32_16x16x32_bf16 v[40:43], v[162:165], v[178:181], v[40:43]
	v_mfma_f32_16x16x32_bf16 v[28:31], v[154:157], v[186:189], v[28:31]
	v_mfma_f32_16x16x32_bf16 v[24:27], v[162:165], v[186:189], v[24:27]
	v_mfma_f32_16x16x32_bf16 v[12:15], v[154:157], v[194:197], v[12:15]
	v_mfma_f32_16x16x32_bf16 v[8:11], v[162:165], v[194:197], v[8:11]
	s_barrier
; #define STG(P, GB) do { const char* _gb = (GB); \
;     _Pragma("unroll") for (int _i = 0; _i < 2; ++_i) { \
;       __builtin_amdgcn_global_load_lds((const unsigned*)(_gb + voff[_i]), \
;         (LAS unsigned*)((LAS char*)(P) + ldsw + _i * 8192), 16, 0, 0); } } while (0)
; #define LDA(dst, b, h) _Pragma("unroll") for (int m = 0; m < 4; ++m) _Pragma("unroll") for (int k = 0; k < 2; ++k) \
;     dst[m][k] = *(const LAS bf16x8*)((LAS char*)SA(b, h) + aoff + m * 2048 + k * 1024)
; #define LDB(dst, b, h) _Pragma("unroll") for (int n = 0; n < 2; ++n) _Pragma("unroll") for (int k = 0; k < 2; ++k) \
;     dst[n][k] = *(const LAS bf16x8*)((LAS char*)SB(b, h) + boff + n * 2048 + k * 1024)
; #define MMA(ai, bj, At_, Bt_) do { __builtin_amdgcn_s_setprio(1); \
;     _Pragma("unroll") for (int m = 0; m < 4; ++m) _Pragma("unroll") for (int n = 0; n < 2; ++n) _Pragma("unroll") for (int k = 0; k < 2; ++k) \
;       acc[ai][bj][m][n] = __builtin_amdgcn_mfma_f32_16x16x32_bf16(Bt_[n][k], At_[m][k], acc[ai][bj][m][n], 0, 0, 0); \
;     __builtin_amdgcn_s_setprio(0); } while (0)
; #define WAIT_V(n) asm volatile("s_waitcnt vmcnt(" #n ")" ::: "memory")
; #define WAIT_L(n) asm volatile("s_waitcnt lgkmcnt(" #n ")" ::: "memory")
; #define BAR __builtin_amdgcn_s_barrier()
; #define SCHED __builtin_amdgcn_sched_barrier(0)
; __device__ __forceinline__ void gemm_phase(const bf16_t* __restrict__ A, const bf16_t* __restrict__ Bt, bf16_t* __restrict__ C, int M, int N, int K,
;                                            int ldc, const int EPI, char* smem, const int wid_u) {
;     ...
;       WAIT_V(6); BAR; MMA(1, 1, At, B1); BAR;
;       LDB(B0, 1, 0); SCHED; LDA(At, 1, 0); STG(SA(0, 1), a2 + hstep);
;       WAIT_L(8); BAR; WAIT_L(0); MMA(0, 0, At, B0); BAR; SCHED;
;       LDB(B1, 1, 1); STG(SB(1, 0), b3);
;       BAR; WAIT_L(0); MMA(0, 1, At, B1); BAR;
;       LDA(At, 1, 1); STG(SA(1, 0), a3);
;       BAR; WAIT_L(0); MMA(1, 0, At, B0); BAR; SCHED;
	s_add_u32 s18, s22, 0x40000
	s_addc_u32 s19, s23, 0
	s_add_i32 s54, s41, s31
	v_lshl_add_u64 v[150:151], s[18:19], 0, v[130:131]
	s_mov_b32 m0, s54
	s_nop 0
	global_load_lds_dwordx4 v[150:151], off
	v_lshl_add_u64 v[150:151], s[18:19], 0, v[128:129]
	s_add_i32 m0, s54, 0x2000
	s_nop 0
	global_load_lds_dwordx4 v[150:151], off
	s_waitcnt vmcnt(6)
	s_barrier
	v_mfma_f32_16x16x32_bf16 v[52:55], v[198:201], v[166:169], v[52:55]
	v_mfma_f32_16x16x32_bf16 v[48:51], v[206:209], v[166:169], v[48:51]
	v_mfma_f32_16x16x32_bf16 v[36:39], v[198:201], v[174:177], v[36:39]
	v_mfma_f32_16x16x32_bf16 v[32:35], v[206:209], v[174:177], v[32:35]
	v_mfma_f32_16x16x32_bf16 v[20:23], v[198:201], v[182:185], v[20:23]
	v_mfma_f32_16x16x32_bf16 v[16:19], v[206:209], v[182:185], v[16:19]
	v_mfma_f32_16x16x32_bf16 v[4:7], v[198:201], v[190:193], v[4:7]
	v_mfma_f32_16x16x32_bf16 v[0:3], v[206:209], v[190:193], v[0:3]
	v_mfma_f32_16x16x32_bf16 v[52:55], v[202:205], v[170:173], v[52:55]
	v_mfma_f32_16x16x32_bf16 v[48:51], v[210:213], v[170:173], v[48:51]
	v_mfma_f32_16x16x32_bf16 v[36:39], v[202:205], v[178:181], v[36:39]
	v_mfma_f32_16x16x32_bf16 v[32:35], v[210:213], v[178:181], v[32:35]
	v_mfma_f32_16x16x32_bf16 v[20:23], v[202:205], v[186:189], v[20:23]
	v_mfma_f32_16x16x32_bf16 v[16:19], v[210:213], v[186:189], v[16:19]
	v_mfma_f32_16x16x32_bf16 v[4:7], v[202:205], v[194:197], v[4:7]
	v_mfma_f32_16x16x32_bf16 v[0:3], v[210:213], v[194:197], v[0:3]
	s_add_i32 s54, 0, 0x18000
	v_add_u32_e32 v149, s54, v145
	s_barrier
	ds_read_b128 v[150:153], v149
	ds_read_b128 v[154:157], v149 offset:1024
	ds_read_b128 v[158:161], v149 offset:2048
	ds_read_b128 v[162:165], v149 offset:3072
	s_add_u32 s18, s24, 0x40000
	s_addc_u32 s19, s25, 0
	s_mov_b32 m0, s36
	v_lshl_add_u64 v[198:199], s[18:19], 0, v[130:131]
	ds_read_b128 v[166:169], v147 offset:32768
	ds_read_b128 v[170:173], v147 offset:33792
	ds_read_b128 v[174:177], v147 offset:34816
	ds_read_b128 v[178:181], v147 offset:35840
	ds_read_b128 v[182:185], v147 offset:36864
	ds_read_b128 v[186:189], v147 offset:37888
	ds_read_b128 v[190:193], v147 offset:38912
	ds_read_b128 v[194:197], v147 offset:39936
	global_load_lds_dwordx4 v[198:199], off
	v_lshl_add_u64 v[198:199], s[18:19], 0, v[128:129]
	s_mov_b32 m0, s37
	s_nop 0
	global_load_lds_dwordx4 v[198:199], off
	s_waitcnt lgkmcnt(8)
	s_barrier
	s_waitcnt lgkmcnt(0)
	s_waitcnt lgkmcnt(0)
	v_mfma_f32_16x16x32_bf16 v[124:127], v[150:153], v[166:169], v[124:127]
	v_mfma_f32_16x16x32_bf16 v[120:123], v[158:161], v[166:169], v[120:123]
	v_mfma_f32_16x16x32_bf16 v[108:111], v[150:153], v[174:177], v[108:111]
	v_mfma_f32_16x16x32_bf16 v[104:107], v[158:161], v[174:177], v[104:107]
	v_mfma_f32_16x16x32_bf16 v[92:95], v[150:153], v[182:185], v[92:95]
	v_mfma_f32_16x16x32_bf16 v[88:91], v[158:161], v[182:185], v[88:91]
	v_mfma_f32_16x16x32_bf16 v[76:79], v[150:153], v[190:193], v[76:79]
	v_mfma_f32_16x16x32_bf16 v[72:75], v[158:161], v[190:193], v[72:75]
	v_mfma_f32_16x16x32_bf16 v[124:127], v[154:157], v[170:173], v[124:127]
	v_mfma_f32_16x16x32_bf16 v[120:123], v[162:165], v[170:173], v[120:123]
	v_mfma_f32_16x16x32_bf16 v[108:111], v[154:157], v[178:181], v[108:111]
	v_mfma_f32_16x16x32_bf16 v[104:107], v[162:165], v[178:181], v[104:107]
	v_mfma_f32_16x16x32_bf16 v[92:95], v[154:157], v[186:189], v[92:95]
	v_mfma_f32_16x16x32_bf16 v[88:91], v[162:165], v[186:189], v[88:91]
	v_mfma_f32_16x16x32_bf16 v[76:79], v[154:157], v[194:197], v[76:79]
	v_mfma_f32_16x16x32_bf16 v[72:75], v[162:165], v[194:197], v[72:75]
	s_barrier
	s_add_i32 s24, 0, 0x1c000
	s_add_i32 s18, s54, s31
	v_add_u32_e32 v149, s24, v145
	v_lshl_add_u64 v[142:143], v[142:143], 0, s[10:11]
	s_mov_b32 m0, s18
	ds_read_b128 v[198:201], v149
	ds_read_b128 v[202:205], v149 offset:1024
	ds_read_b128 v[206:209], v149 offset:2048
	ds_read_b128 v[210:213], v149 offset:3072
	global_load_lds_dwordx4 v[142:143], off
	v_lshl_add_u64 v[142:143], v[214:215], 0, s[10:11]
	s_add_i32 m0, s18, 0x2000
	s_nop 0
	global_load_lds_dwordx4 v[142:143], off
	s_barrier
	s_waitcnt lgkmcnt(0)
	s_waitcnt lgkmcnt(0)
	v_mfma_f32_16x16x32_bf16 v[116:119], v[198:201], v[166:169], v[116:119]
	v_mfma_f32_16x16x32_bf16 v[112:115], v[206:209], v[166:169], v[112:115]
	v_mfma_f32_16x16x32_bf16 v[100:103], v[198:201], v[174:177], v[100:103]
	v_mfma_f32_16x16x32_bf16 v[96:99], v[206:209], v[174:177], v[96:99]
	v_mfma_f32_16x16x32_bf16 v[84:87], v[198:201], v[182:185], v[84:87]
	v_mfma_f32_16x16x32_bf16 v[80:83], v[206:209], v[182:185], v[80:83]
	v_mfma_f32_16x16x32_bf16 v[68:71], v[198:201], v[190:193], v[68:71]
	v_mfma_f32_16x16x32_bf16 v[64:67], v[206:209], v[190:193], v[64:67]
	v_mfma_f32_16x16x32_bf16 v[116:119], v[202:205], v[170:173], v[116:119]
	v_mfma_f32_16x16x32_bf16 v[112:115], v[210:213], v[170:173], v[112:115]
	v_mfma_f32_16x16x32_bf16 v[100:103], v[202:205], v[178:181], v[100:103]
	v_mfma_f32_16x16x32_bf16 v[96:99], v[210:213], v[178:181], v[96:99]
	v_mfma_f32_16x16x32_bf16 v[84:87], v[202:205], v[186:189], v[84:87]
	v_mfma_f32_16x16x32_bf16 v[80:83], v[210:213], v[186:189], v[80:83]
	v_mfma_f32_16x16x32_bf16 v[68:71], v[202:205], v[194:197], v[68:71]
	v_mfma_f32_16x16x32_bf16 v[64:67], v[210:213], v[194:197], v[64:67]
	s_mov_b32 m0, s38
	v_lshl_add_u64 v[142:143], v[216:217], 0, s[10:11]
	s_barrier
	ds_read_b128 v[166:169], v147 offset:49152
	ds_read_b128 v[170:173], v147 offset:50176
	ds_read_b128 v[174:177], v147 offset:51200
	ds_read_b128 v[178:181], v147 offset:52224
	ds_read_b128 v[182:185], v147 offset:53248
	ds_read_b128 v[186:189], v147 offset:54272
	ds_read_b128 v[190:193], v147 offset:55296
	ds_read_b128 v[194:197], v147 offset:56320
	global_load_lds_dwordx4 v[142:143], off
	v_lshl_add_u64 v[142:143], v[218:219], 0, s[10:11]
	s_mov_b32 m0, s39
	s_nop 0
	global_load_lds_dwordx4 v[142:143], off
	s_barrier
; #define STG(P, GB) do { const char* _gb = (GB); \
;     _Pragma("unroll") for (int _i = 0; _i < 2; ++_i) { \
;       __builtin_amdgcn_global_load_lds((const unsigned*)(_gb + voff[_i]), \
;         (LAS unsigned*)((LAS char*)(P) + ldsw + _i * 8192), 16, 0, 0); } } while (0)
; #define MMA(ai, bj, At_, Bt_) do { __builtin_amdgcn_s_setprio(1); \
;     _Pragma("unroll") for (int m = 0; m < 4; ++m) _Pragma("unroll") for (int n = 0; n < 2; ++n) _Pragma("unroll") for (int k = 0; k < 2; ++k) \
;       acc[ai][bj][m][n] = __builtin_amdgcn_mfma_f32_16x16x32_bf16(Bt_[n][k], At_[m][k], acc[ai][bj][m][n], 0, 0, 0); \
;     __builtin_amdgcn_s_setprio(0); } while (0)
; #define WAIT_V(n) asm volatile("s_waitcnt vmcnt(" #n ")" ::: "memory")
; #define WAIT_L(n) asm volatile("s_waitcnt lgkmcnt(" #n ")" ::: "memory")
; #define BAR __builtin_amdgcn_s_barrier()
; #define SCHED __builtin_amdgcn_sched_barrier(0)
; __device__ __forceinline__ void gemm_phase(const bf16_t* __restrict__ A, const bf16_t* __restrict__ Bt, bf16_t* __restrict__ C, int M, int N, int K,
;                                            int ldc, const int EPI, char* smem, const int wid_u) {
;     ...
;       BAR; WAIT_L(0); MMA(1, 0, At, B0); BAR; SCHED;
;       STG(SB(1, 1), b3 + hstep);
;       WAIT_V(6); BAR; MMA(1, 1, At, B1); BAR;
;     ...
;           } else {
;             float o[8];
; #pragma unroll
;             for (int n = 0; n < 2; ++n) {
;               const f32x4 a = acc[ai][0][m][n], b = acc[ai][1][m][n];
; #pragma unroll
;               for (int j = 0; j < 4; ++j) o[n * 4 + j] = a[j] * __builtin_amdgcn_rcpf(1.f + __expf(-a[j])) * b[j];
;             }
;             *(uint4*)(C + row * ldc + (bcol >> 1) + wc * 32 + fq * 8) = pack8(o);
	s_waitcnt lgkmcnt(0)
	s_waitcnt lgkmcnt(0)
	v_mfma_f32_16x16x32_bf16 v[60:63], v[150:153], v[166:169], v[60:63]
	v_mfma_f32_16x16x32_bf16 v[56:59], v[158:161], v[166:169], v[56:59]
	v_mfma_f32_16x16x32_bf16 v[44:47], v[150:153], v[174:177], v[44:47]
	v_mfma_f32_16x16x32_bf16 v[40:43], v[158:161], v[174:177], v[40:43]
	v_mfma_f32_16x16x32_bf16 v[28:31], v[150:153], v[182:185], v[28:31]
	v_mfma_f32_16x16x32_bf16 v[24:27], v[158:161], v[182:185], v[24:27]
	v_mfma_f32_16x16x32_bf16 v[12:15], v[150:153], v[190:193], v[12:15]
	v_mfma_f32_16x16x32_bf16 v[8:11], v[158:161], v[190:193], v[8:11]
	v_mfma_f32_16x16x32_bf16 v[60:63], v[154:157], v[170:173], v[60:63]
	v_mfma_f32_16x16x32_bf16 v[56:59], v[162:165], v[170:173], v[56:59]
	v_mfma_f32_16x16x32_bf16 v[44:47], v[154:157], v[178:181], v[44:47]
	v_mfma_f32_16x16x32_bf16 v[40:43], v[162:165], v[178:181], v[40:43]
	v_mfma_f32_16x16x32_bf16 v[28:31], v[154:157], v[186:189], v[28:31]
	v_mfma_f32_16x16x32_bf16 v[24:27], v[162:165], v[186:189], v[24:27]
	v_mfma_f32_16x16x32_bf16 v[12:15], v[154:157], v[194:197], v[12:15]
	v_mfma_f32_16x16x32_bf16 v[8:11], v[162:165], v[194:197], v[8:11]
	s_barrier
	s_add_u32 s18, s22, 0x40080
	s_addc_u32 s19, s23, 0
	s_add_i32 s22, s24, s31
	v_lshl_add_u64 v[142:143], s[18:19], 0, v[130:131]
	s_mov_b32 m0, s22
	s_nop 0
	global_load_lds_dwordx4 v[142:143], off
	v_lshl_add_u64 v[142:143], s[18:19], 0, v[128:129]
	s_add_i32 m0, s22, 0x2000
	s_nop 0
	global_load_lds_dwordx4 v[142:143], off
	s_waitcnt vmcnt(6)
	s_barrier
	v_mfma_f32_16x16x32_bf16 v[52:55], v[198:201], v[166:169], v[52:55]
	v_mfma_f32_16x16x32_bf16 v[48:51], v[206:209], v[166:169], v[48:51]
	v_mfma_f32_16x16x32_bf16 v[36:39], v[198:201], v[174:177], v[36:39]
	v_mfma_f32_16x16x32_bf16 v[32:35], v[206:209], v[174:177], v[32:35]
	v_mfma_f32_16x16x32_bf16 v[20:23], v[198:201], v[182:185], v[20:23]
	v_mfma_f32_16x16x32_bf16 v[16:19], v[206:209], v[182:185], v[16:19]
	v_mfma_f32_16x16x32_bf16 v[4:7], v[198:201], v[190:193], v[4:7]
	v_mfma_f32_16x16x32_bf16 v[0:3], v[206:209], v[190:193], v[0:3]
	v_mfma_f32_16x16x32_bf16 v[52:55], v[202:205], v[170:173], v[52:55]
	v_mfma_f32_16x16x32_bf16 v[48:51], v[210:213], v[170:173], v[48:51]
	v_mfma_f32_16x16x32_bf16 v[36:39], v[202:205], v[178:181], v[36:39]
	v_mfma_f32_16x16x32_bf16 v[32:35], v[210:213], v[178:181], v[32:35]
	v_mfma_f32_16x16x32_bf16 v[20:23], v[202:205], v[186:189], v[20:23]
	v_mfma_f32_16x16x32_bf16 v[16:19], v[210:213], v[186:189], v[16:19]
	v_mfma_f32_16x16x32_bf16 v[4:7], v[202:205], v[194:197], v[4:7]
	v_mfma_f32_16x16x32_bf16 v[0:3], v[210:213], v[194:197], v[0:3]
	s_add_i32 s53, s53, 2
	s_add_u32 s51, s51, 0x100
	s_addc_u32 s52, s52, 0
	s_cmp_gt_u32 s53, 13
	s_mov_b64 s[18:19], s[20:21]
	s_barrier
	s_cbranch_scc0 .LBB0_1026
	v_mul_f32_e32 v142, 0xbfb8aa3b, v124
	v_exp_f32_e32 v142, v142
	v_mul_f32_e32 v143, 0xbfb8aa3b, v125
	v_exp_f32_e32 v143, v143
	s_lshl_b32 s18, s46, 8
	v_add_f32_e32 v142, 1.0, v142
	v_rcp_f32_e32 v150, v142
	v_add_f32_e32 v142, 1.0, v143
	v_rcp_f32_e32 v151, v142
	s_mov_b32 s19, s9
	v_lshl_add_u32 v149, s47, 8, v144
	v_lshl_add_u64 v[142:143], v[132:133], 0, s[18:19]
	v_pk_mul_f32 v[124:125], v[124:125], v[150:151]
	v_mul_f32_e32 v150, 0xbfb8aa3b, v126
	v_mul_f32_e32 v151, 0xbfb8aa3b, v127
	v_exp_f32_e32 v150, v150
	v_exp_f32_e32 v151, v151
	v_pk_mul_f32 v[116:117], v[124:125], v[116:117]
	s_and_b64 vcc, exec, s[4:5]
	v_add_f32_e32 v124, 1.0, v150
	v_add_f32_e32 v125, 1.0, v151
	v_mul_f32_e32 v150, 0xbfb8aa3b, v120
	v_mul_f32_e32 v151, 0xbfb8aa3b, v121
	v_rcp_f32_e32 v124, v124
	v_rcp_f32_e32 v125, v125
	v_exp_f32_e32 v150, v150
	v_exp_f32_e32 v151, v151
	s_mov_b32 s47, s8
	v_pk_mul_f32 v[124:125], v[126:127], v[124:125]
	v_add_f32_e32 v126, 1.0, v150
	v_add_f32_e32 v127, 1.0, v151
	v_mul_f32_e32 v150, 0xbfb8aa3b, v122
	v_mul_f32_e32 v151, 0xbfb8aa3b, v123
	v_exp_f32_e32 v150, v150
	v_exp_f32_e32 v151, v151
	v_rcp_f32_e32 v126, v126
	v_rcp_f32_e32 v127, v127
	v_add_f32_e32 v150, 1.0, v150
	v_add_f32_e32 v151, 1.0, v151
	v_rcp_f32_e32 v150, v150
	v_rcp_f32_e32 v151, v151
	v_pk_mul_f32 v[120:121], v[120:121], v[126:127]
	v_pk_mul_f32 v[118:119], v[124:125], v[118:119]
	v_pk_mul_f32 v[120:121], v[120:121], v[112:113]
	v_pk_mul_f32 v[112:113], v[122:123], v[150:151]
	s_mov_b32 s46, s12
	v_pk_mul_f32 v[122:123], v[112:113], v[114:115]
	v_mul_f32_e32 v115, 0xbfb8aa3b, v108
	v_cvt_pk_bf16_f32 v112, v116, v117
	v_exp_f32_e32 v116, v115
	v_mul_f32_e32 v115, 0xbfb8aa3b, v109
	v_exp_f32_e32 v117, v115
	v_cvt_pk_bf16_f32 v113, v118, v119
	v_cvt_pk_bf16_f32 v114, v120, v121
	v_cvt_pk_bf16_f32 v115, v122, v123
	v_add_f32_e32 v116, 1.0, v116
	v_add_f32_e32 v117, 1.0, v117
	v_mad_i64_i32 v[118:119], s[18:19], v149, s44, v[142:143]
	v_rcp_f32_e32 v116, v116
	v_rcp_f32_e32 v117, v117
	global_store_dwordx4 v[118:119], v[112:115], off
	s_mov_b64 s[20:21], s[16:17]
	v_pk_mul_f32 v[108:109], v[108:109], v[116:117]
	v_mul_f32_e32 v112, 0xbfb8aa3b, v110
	v_mul_f32_e32 v113, 0xbfb8aa3b, v111
	v_exp_f32_e32 v112, v112
	v_exp_f32_e32 v113, v113
	v_pk_mul_f32 v[100:101], v[108:109], v[100:101]
	v_or_b32_e32 v114, 16, v149
	v_add_f32_e32 v108, 1.0, v112
	v_add_f32_e32 v109, 1.0, v113
	v_mul_f32_e32 v112, 0xbfb8aa3b, v104
	v_mul_f32_e32 v113, 0xbfb8aa3b, v105
	v_rcp_f32_e32 v108, v108
	v_rcp_f32_e32 v109, v109
	v_exp_f32_e32 v112, v112
	v_exp_f32_e32 v113, v113
	v_pk_mul_f32 v[108:109], v[110:111], v[108:109]
	v_add_f32_e32 v110, 1.0, v112
	v_add_f32_e32 v111, 1.0, v113
	v_mul_f32_e32 v112, 0xbfb8aa3b, v106
	v_mul_f32_e32 v113, 0xbfb8aa3b, v107
	v_exp_f32_e32 v112, v112
	v_exp_f32_e32 v113, v113
	v_rcp_f32_e32 v110, v110
	v_rcp_f32_e32 v111, v111
; __device__ __forceinline__ void gemm_phase(const bf16_t* __restrict__ A, const bf16_t* __restrict__ Bt, bf16_t* __restrict__ C, int M, int N, int K,
;                                            int ldc, const int EPI, char* smem, const int wid_u) {
;     ...
;           } else {
;             float o[8];
; #pragma unroll
;             for (int n = 0; n < 2; ++n) {
;               const f32x4 a = acc[ai][0][m][n], b = acc[ai][1][m][n];
; #pragma unroll
;               for (int j = 0; j < 4; ++j) o[n * 4 + j] = a[j] * __builtin_amdgcn_rcpf(1.f + __expf(-a[j])) * b[j];
;             }
;             *(uint4*)(C + row * ldc + (bcol >> 1) + wc * 32 + fq * 8) = pack8(o);
	v_add_f32_e32 v112, 1.0, v112
	v_add_f32_e32 v113, 1.0, v113
	v_rcp_f32_e32 v112, v112
	v_rcp_f32_e32 v113, v113
	v_pk_mul_f32 v[104:105], v[104:105], v[110:111]
	v_pk_mul_f32 v[102:103], v[108:109], v[102:103]
	v_pk_mul_f32 v[104:105], v[104:105], v[96:97]
	v_pk_mul_f32 v[96:97], v[106:107], v[112:113]
	s_nop 0
	v_pk_mul_f32 v[106:107], v[96:97], v[98:99]
	v_mul_f32_e32 v99, 0xbfb8aa3b, v92
	v_cvt_pk_bf16_f32 v96, v100, v101
	v_exp_f32_e32 v100, v99
	v_mul_f32_e32 v99, 0xbfb8aa3b, v93
	v_exp_f32_e32 v101, v99
	v_cvt_pk_bf16_f32 v97, v102, v103
	v_cvt_pk_bf16_f32 v98, v104, v105
	v_cvt_pk_bf16_f32 v99, v106, v107
	v_add_f32_e32 v100, 1.0, v100
	v_add_f32_e32 v101, 1.0, v101
	v_mad_i64_i32 v[102:103], s[18:19], v114, s44, v[142:143]
	v_rcp_f32_e32 v100, v100
	v_rcp_f32_e32 v101, v101
	global_store_dwordx4 v[102:103], v[96:99], off
	v_pk_mul_f32 v[92:93], v[92:93], v[100:101]
	s_nop 0
	v_mul_f32_e32 v96, 0xbfb8aa3b, v94
	v_mul_f32_e32 v97, 0xbfb8aa3b, v95
	v_exp_f32_e32 v96, v96
	v_exp_f32_e32 v97, v97
	v_pk_mul_f32 v[84:85], v[92:93], v[84:85]
	v_or_b32_e32 v98, 32, v149
	v_add_f32_e32 v92, 1.0, v96
	v_add_f32_e32 v93, 1.0, v97
	v_mul_f32_e32 v96, 0xbfb8aa3b, v88
	v_mul_f32_e32 v97, 0xbfb8aa3b, v89
	v_rcp_f32_e32 v92, v92
	v_rcp_f32_e32 v93, v93
	v_exp_f32_e32 v96, v96
	v_exp_f32_e32 v97, v97
	v_pk_mul_f32 v[92:93], v[94:95], v[92:93]
	v_add_f32_e32 v94, 1.0, v96
	v_add_f32_e32 v95, 1.0, v97
	v_mul_f32_e32 v96, 0xbfb8aa3b, v90
	v_mul_f32_e32 v97, 0xbfb8aa3b, v91
	v_exp_f32_e32 v96, v96
	v_exp_f32_e32 v97, v97
	v_rcp_f32_e32 v94, v94
	v_rcp_f32_e32 v95, v95
	v_add_f32_e32 v96, 1.0, v96
	v_add_f32_e32 v97, 1.0, v97
	v_rcp_f32_e32 v96, v96
	v_rcp_f32_e32 v97, v97
	v_pk_mul_f32 v[88:89], v[88:89], v[94:95]
	v_pk_mul_f32 v[86:87], v[92:93], v[86:87]
	v_pk_mul_f32 v[88:89], v[88:89], v[80:81]
	v_pk_mul_f32 v[80:81], v[90:91], v[96:97]
	s_nop 0
	v_pk_mul_f32 v[90:91], v[80:81], v[82:83]
	v_mul_f32_e32 v83, 0xbfb8aa3b, v76
	v_cvt_pk_bf16_f32 v80, v84, v85
	v_exp_f32_e32 v84, v83
	v_mul_f32_e32 v83, 0xbfb8aa3b, v77
	v_exp_f32_e32 v85, v83
	v_cvt_pk_bf16_f32 v81, v86, v87
	v_cvt_pk_bf16_f32 v82, v88, v89
	v_cvt_pk_bf16_f32 v83, v90, v91
	v_add_f32_e32 v84, 1.0, v84
	v_add_f32_e32 v85, 1.0, v85
	v_mad_i64_i32 v[86:87], s[18:19], v98, s44, v[142:143]
	v_rcp_f32_e32 v84, v84
	v_rcp_f32_e32 v85, v85
	global_store_dwordx4 v[86:87], v[80:83], off
	v_pk_mul_f32 v[76:77], v[76:77], v[84:85]
	s_nop 0
	v_mul_f32_e32 v80, 0xbfb8aa3b, v78
	v_mul_f32_e32 v81, 0xbfb8aa3b, v79
	v_exp_f32_e32 v80, v80
	v_exp_f32_e32 v81, v81
	v_pk_mul_f32 v[68:69], v[76:77], v[68:69]
	v_or_b32_e32 v82, 48, v149
	v_add_f32_e32 v76, 1.0, v80
	v_add_f32_e32 v77, 1.0, v81
	v_mul_f32_e32 v80, 0xbfb8aa3b, v72
	v_mul_f32_e32 v81, 0xbfb8aa3b, v73
	v_rcp_f32_e32 v76, v76
	v_rcp_f32_e32 v77, v77
	v_exp_f32_e32 v80, v80
	v_exp_f32_e32 v81, v81
	v_pk_mul_f32 v[76:77], v[78:79], v[76:77]
	v_add_f32_e32 v78, 1.0, v80
	v_add_f32_e32 v79, 1.0, v81
	v_mul_f32_e32 v80, 0xbfb8aa3b, v74
	v_mul_f32_e32 v81, 0xbfb8aa3b, v75
	v_exp_f32_e32 v80, v80
	v_exp_f32_e32 v81, v81
	v_rcp_f32_e32 v78, v78
	v_rcp_f32_e32 v79, v79
	v_add_f32_e32 v80, 1.0, v80
	v_add_f32_e32 v81, 1.0, v81
	v_rcp_f32_e32 v80, v80
	v_rcp_f32_e32 v81, v81
	v_pk_mul_f32 v[72:73], v[72:73], v[78:79]
	v_pk_mul_f32 v[70:71], v[76:77], v[70:71]
	v_pk_mul_f32 v[72:73], v[72:73], v[64:65]
	v_pk_mul_f32 v[64:65], v[74:75], v[80:81]
	s_nop 0
	v_pk_mul_f32 v[74:75], v[64:65], v[66:67]
	v_mul_f32_e32 v67, 0xbfb8aa3b, v60
	v_cvt_pk_bf16_f32 v64, v68, v69
	v_exp_f32_e32 v68, v67
	v_mul_f32_e32 v67, 0xbfb8aa3b, v61
	v_exp_f32_e32 v69, v67
	v_cvt_pk_bf16_f32 v65, v70, v71
	v_cvt_pk_bf16_f32 v66, v72, v73
	v_cvt_pk_bf16_f32 v67, v74, v75
	v_add_f32_e32 v68, 1.0, v68
	v_add_f32_e32 v69, 1.0, v69
	v_mad_i64_i32 v[70:71], s[18:19], v82, s44, v[142:143]
	v_rcp_f32_e32 v68, v68
	v_rcp_f32_e32 v69, v69
	global_store_dwordx4 v[70:71], v[64:67], off
	v_pk_mul_f32 v[60:61], v[60:61], v[68:69]
	s_nop 0
	v_mul_f32_e32 v64, 0xbfb8aa3b, v62
	v_mul_f32_e32 v65, 0xbfb8aa3b, v63
	v_exp_f32_e32 v64, v64
	v_exp_f32_e32 v65, v65
	v_pk_mul_f32 v[52:53], v[60:61], v[52:53]
	v_add_u32_e32 v66, 0x80, v149
	v_add_f32_e32 v60, 1.0, v64
	v_add_f32_e32 v61, 1.0, v65
	v_mul_f32_e32 v64, 0xbfb8aa3b, v56
	v_mul_f32_e32 v65, 0xbfb8aa3b, v57
	v_rcp_f32_e32 v60, v60
	v_rcp_f32_e32 v61, v61
	v_exp_f32_e32 v64, v64
	v_exp_f32_e32 v65, v65
	v_pk_mul_f32 v[60:61], v[62:63], v[60:61]
	v_add_f32_e32 v62, 1.0, v64
	v_add_f32_e32 v63, 1.0, v65
	v_mul_f32_e32 v64, 0xbfb8aa3b, v58
	v_mul_f32_e32 v65, 0xbfb8aa3b, v59
	v_exp_f32_e32 v64, v64
	v_exp_f32_e32 v65, v65
	v_rcp_f32_e32 v62, v62
	v_rcp_f32_e32 v63, v63
	v_add_f32_e32 v64, 1.0, v64
	v_add_f32_e32 v65, 1.0, v65
	v_rcp_f32_e32 v64, v64
	v_rcp_f32_e32 v65, v65
	v_pk_mul_f32 v[56:57], v[56:57], v[62:63]
	v_pk_mul_f32 v[54:55], v[60:61], v[54:55]
	v_pk_mul_f32 v[56:57], v[56:57], v[48:49]
	v_pk_mul_f32 v[48:49], v[58:59], v[64:65]
	s_nop 0
; #define WAIT_V(n) asm volatile("s_waitcnt vmcnt(" #n ")" ::: "memory")
; #define BAR __builtin_amdgcn_s_barrier()
; __device__ __forceinline__ void gemm_phase(const bf16_t* __restrict__ A, const bf16_t* __restrict__ Bt, bf16_t* __restrict__ C, int M, int N, int K,
;                                            int ldc, const int EPI, char* smem, const int wid_u) {
;     ...
;           } else {
;             float o[8];
; #pragma unroll
;             for (int n = 0; n < 2; ++n) {
;               const f32x4 a = acc[ai][0][m][n], b = acc[ai][1][m][n];
; #pragma unroll
;               for (int j = 0; j < 4; ++j) o[n * 4 + j] = a[j] * __builtin_amdgcn_rcpf(1.f + __expf(-a[j])) * b[j];
;             }
;             *(uint4*)(C + row * ldc + (bcol >> 1) + wc * 32 + fq * 8) = pack8(o);
;     ...
;     if (!has_next) break;
; #pragma unroll
;     for (int a = 0; a < 2; ++a)
; #pragma unroll
;       for (int b = 0; b < 2; ++b)
; #pragma unroll
;         for (int m = 0; m < 4; ++m)
; #pragma unroll
;           for (int n = 0; n < 2; ++n) acc[a][b][m][n] = (f32x4){0.f, 0.f, 0.f, 0.f};
;     pm = npm; pn = npn; cA = nA; cB = nB; ++ui;
;   }
;   WAIT_V(0);
;   if (wr == 0) BAR;
;   BAR;
	v_pk_mul_f32 v[58:59], v[48:49], v[50:51]
	v_mul_f32_e32 v51, 0xbfb8aa3b, v44
	v_cvt_pk_bf16_f32 v48, v52, v53
	v_exp_f32_e32 v52, v51
	v_mul_f32_e32 v51, 0xbfb8aa3b, v45
	v_exp_f32_e32 v53, v51
	v_cvt_pk_bf16_f32 v49, v54, v55
	v_cvt_pk_bf16_f32 v50, v56, v57
	v_cvt_pk_bf16_f32 v51, v58, v59
	v_add_f32_e32 v52, 1.0, v52
	v_add_f32_e32 v53, 1.0, v53
	v_mad_i64_i32 v[54:55], s[18:19], v66, s44, v[142:143]
	v_rcp_f32_e32 v52, v52
	v_rcp_f32_e32 v53, v53
	global_store_dwordx4 v[54:55], v[48:51], off
	v_pk_mul_f32 v[44:45], v[44:45], v[52:53]
	s_nop 0
	v_mul_f32_e32 v48, 0xbfb8aa3b, v46
	v_mul_f32_e32 v49, 0xbfb8aa3b, v47
	v_exp_f32_e32 v48, v48
	v_exp_f32_e32 v49, v49
	v_pk_mul_f32 v[36:37], v[44:45], v[36:37]
	v_add_u32_e32 v50, 0x90, v149
	v_add_f32_e32 v44, 1.0, v48
	v_add_f32_e32 v45, 1.0, v49
	v_mul_f32_e32 v48, 0xbfb8aa3b, v40
	v_mul_f32_e32 v49, 0xbfb8aa3b, v41
	v_rcp_f32_e32 v44, v44
	v_rcp_f32_e32 v45, v45
	v_exp_f32_e32 v48, v48
	v_exp_f32_e32 v49, v49
	v_pk_mul_f32 v[44:45], v[46:47], v[44:45]
	v_add_f32_e32 v46, 1.0, v48
	v_add_f32_e32 v47, 1.0, v49
	v_mul_f32_e32 v48, 0xbfb8aa3b, v42
	v_mul_f32_e32 v49, 0xbfb8aa3b, v43
	v_exp_f32_e32 v48, v48
	v_exp_f32_e32 v49, v49
	v_rcp_f32_e32 v46, v46
	v_rcp_f32_e32 v47, v47
	v_add_f32_e32 v48, 1.0, v48
	v_add_f32_e32 v49, 1.0, v49
	v_rcp_f32_e32 v48, v48
	v_rcp_f32_e32 v49, v49
	v_pk_mul_f32 v[40:41], v[40:41], v[46:47]
	v_pk_mul_f32 v[38:39], v[44:45], v[38:39]
	v_pk_mul_f32 v[40:41], v[40:41], v[32:33]
	v_pk_mul_f32 v[32:33], v[42:43], v[48:49]
	s_nop 0
	v_pk_mul_f32 v[42:43], v[32:33], v[34:35]
	v_mul_f32_e32 v35, 0xbfb8aa3b, v28
	v_cvt_pk_bf16_f32 v32, v36, v37
	v_exp_f32_e32 v36, v35
	v_mul_f32_e32 v35, 0xbfb8aa3b, v29
	v_exp_f32_e32 v37, v35
	v_cvt_pk_bf16_f32 v33, v38, v39
	v_cvt_pk_bf16_f32 v34, v40, v41
	v_cvt_pk_bf16_f32 v35, v42, v43
	v_add_f32_e32 v36, 1.0, v36
	v_add_f32_e32 v37, 1.0, v37
	v_mad_i64_i32 v[38:39], s[18:19], v50, s44, v[142:143]
	v_rcp_f32_e32 v36, v36
	v_rcp_f32_e32 v37, v37
	global_store_dwordx4 v[38:39], v[32:35], off
	v_pk_mul_f32 v[28:29], v[28:29], v[36:37]
	s_nop 0
	v_mul_f32_e32 v32, 0xbfb8aa3b, v30
	v_mul_f32_e32 v33, 0xbfb8aa3b, v31
	v_exp_f32_e32 v32, v32
	v_exp_f32_e32 v33, v33
	v_pk_mul_f32 v[20:21], v[28:29], v[20:21]
	v_add_u32_e32 v34, 0xa0, v149
	v_add_f32_e32 v28, 1.0, v32
	v_add_f32_e32 v29, 1.0, v33
	v_mul_f32_e32 v32, 0xbfb8aa3b, v24
	v_mul_f32_e32 v33, 0xbfb8aa3b, v25
	v_rcp_f32_e32 v28, v28
	v_rcp_f32_e32 v29, v29
	v_exp_f32_e32 v32, v32
	v_exp_f32_e32 v33, v33
	v_pk_mul_f32 v[28:29], v[30:31], v[28:29]
	v_add_f32_e32 v30, 1.0, v32
	v_add_f32_e32 v31, 1.0, v33
	v_mul_f32_e32 v32, 0xbfb8aa3b, v26
	v_mul_f32_e32 v33, 0xbfb8aa3b, v27
	v_exp_f32_e32 v32, v32
	v_exp_f32_e32 v33, v33
	v_rcp_f32_e32 v30, v30
	v_rcp_f32_e32 v31, v31
	v_add_f32_e32 v32, 1.0, v32
	v_add_f32_e32 v33, 1.0, v33
	v_rcp_f32_e32 v32, v32
	v_rcp_f32_e32 v33, v33
	v_pk_mul_f32 v[24:25], v[24:25], v[30:31]
	v_pk_mul_f32 v[22:23], v[28:29], v[22:23]
	v_pk_mul_f32 v[24:25], v[24:25], v[16:17]
	v_pk_mul_f32 v[16:17], v[26:27], v[32:33]
	s_nop 0
	v_pk_mul_f32 v[26:27], v[16:17], v[18:19]
	v_mul_f32_e32 v19, 0xbfb8aa3b, v12
	v_cvt_pk_bf16_f32 v16, v20, v21
	v_exp_f32_e32 v20, v19
	v_mul_f32_e32 v19, 0xbfb8aa3b, v13
	v_exp_f32_e32 v21, v19
	v_cvt_pk_bf16_f32 v17, v22, v23
	v_cvt_pk_bf16_f32 v18, v24, v25
	v_cvt_pk_bf16_f32 v19, v26, v27
	v_add_f32_e32 v20, 1.0, v20
	v_add_f32_e32 v21, 1.0, v21
	v_mad_i64_i32 v[22:23], s[18:19], v34, s44, v[142:143]
	v_rcp_f32_e32 v20, v20
	v_rcp_f32_e32 v21, v21
	global_store_dwordx4 v[22:23], v[16:19], off
	v_pk_mul_f32 v[12:13], v[12:13], v[20:21]
	s_nop 0
	v_mul_f32_e32 v16, 0xbfb8aa3b, v14
	v_mul_f32_e32 v17, 0xbfb8aa3b, v15
	v_exp_f32_e32 v16, v16
	v_exp_f32_e32 v17, v17
	v_pk_mul_f32 v[4:5], v[12:13], v[4:5]
	v_add_u32_e32 v18, 0xb0, v149
	v_add_f32_e32 v12, 1.0, v16
	v_add_f32_e32 v13, 1.0, v17
	v_mul_f32_e32 v16, 0xbfb8aa3b, v8
	v_mul_f32_e32 v17, 0xbfb8aa3b, v9
	v_rcp_f32_e32 v12, v12
	v_rcp_f32_e32 v13, v13
	v_exp_f32_e32 v16, v16
	v_exp_f32_e32 v17, v17
	v_pk_mul_f32 v[12:13], v[14:15], v[12:13]
	v_add_f32_e32 v14, 1.0, v16
	v_add_f32_e32 v15, 1.0, v17
	v_mul_f32_e32 v16, 0xbfb8aa3b, v10
	v_mul_f32_e32 v17, 0xbfb8aa3b, v11
	v_exp_f32_e32 v16, v16
	v_exp_f32_e32 v17, v17
	v_rcp_f32_e32 v14, v14
	v_rcp_f32_e32 v15, v15
	v_add_f32_e32 v16, 1.0, v16
	v_add_f32_e32 v17, 1.0, v17
	v_rcp_f32_e32 v16, v16
	v_rcp_f32_e32 v17, v17
	v_pk_mul_f32 v[8:9], v[8:9], v[14:15]
	v_pk_mul_f32 v[6:7], v[12:13], v[6:7]
	v_pk_mul_f32 v[8:9], v[8:9], v[0:1]
	v_pk_mul_f32 v[0:1], v[10:11], v[16:17]
	s_nop 0
	v_pk_mul_f32 v[10:11], v[0:1], v[2:3]
	v_cvt_pk_bf16_f32 v0, v4, v5
	v_mad_i64_i32 v[4:5], s[18:19], v18, s44, v[142:143]
	v_cvt_pk_bf16_f32 v1, v6, v7
	v_cvt_pk_bf16_f32 v2, v8, v9
	v_cvt_pk_bf16_f32 v3, v10, v11
	s_mov_b64 s[18:19], s[14:15]
	global_store_dwordx4 v[4:5], v[0:3], off
	s_cbranch_vccz .LBB0_1023
	s_waitcnt vmcnt(0)
	s_cmpk_gt_u32 s26, 0xff
	s_cbranch_scc1 .LBB0_1030
	s_barrier
